# v132 plus nt on all mixer stage-1 (phase 2) output stores, so the streamed intermediates do not evict the re-read parameters from L2
# baseline (speedup 1.0000x reference)
.LBB0_630:
	s_ashr_i32 s19, s18, 31
	v_readfirstlane_b32 s88, v235
	s_lshl_b64 s[18:19], s[18:19], 2
	s_ashr_i32 s5, s88, 6
	s_or_b64 s[18:19], s[18:19], s[26:27]
	s_and_b32 s0, s5, 3
	s_or_b32 s68, s18, 4
	s_mov_b32 s69, s19
	s_lshl_b64 s[18:19], s[18:19], 15
	s_add_u32 s70, s3, s18
	s_addc_u32 s71, s2, s19
	s_lshl_b64 s[36:37], s[68:69], 14
	s_lshl_b64 s[68:69], s[68:69], 15
	s_add_u32 s89, s3, s68
	s_addc_u32 s90, s2, s69
	s_lshl_b32 s80, s5, 2
	s_ashr_i32 s81, s80, 31
	v_lshl_add_u64 v[6:7], v[74:75], 0, s[18:19]
	s_lshl_b64 s[82:83], s[80:81], 10
	v_lshl_add_u64 v[8:9], v[6:7], 0, s[82:83]
	s_lshl_b32 s4, s5, 11
	s_waitcnt vmcnt(0)
	s_barrier
	global_load_dwordx4 v[126:129], v[8:9], off
	v_or_b32_e32 v8, s4, v72
	s_or_b32 s18, s80, 1
	v_ashrrev_i32_e32 v9, 31, v8
	s_ashr_i32 s19, s18, 31
	v_lshl_add_u64 v[8:9], v[8:9], 1, s[70:71]
	s_lshl_b64 s[84:85], s[18:19], 10
	global_load_dwordx4 v[130:133], v[8:9], off
	v_lshl_add_u64 v[8:9], v[6:7], 0, s[84:85]
	global_load_dwordx4 v[134:137], v[8:9], off
	v_lshl_or_b32 v8, s18, 9, v72
	s_or_b32 s18, s80, 2
	v_ashrrev_i32_e32 v9, 31, v8
	s_ashr_i32 s19, s18, 31
	v_lshl_add_u64 v[8:9], v[8:9], 1, s[70:71]
	s_lshl_b64 s[86:87], s[18:19], 10
	global_load_dwordx4 v[138:141], v[8:9], off
	v_lshl_add_u64 v[8:9], v[6:7], 0, s[86:87]
	global_load_dwordx4 v[142:145], v[8:9], off
	v_lshl_or_b32 v8, s18, 9, v72
	s_or_b32 s18, s80, 3
	s_ashr_i32 s19, s18, 31
	s_lshl_b64 s[80:81], s[18:19], 10
	v_ashrrev_i32_e32 v9, 31, v8
	s_add_u32 s68, s78, s68
	v_lshl_add_u64 v[8:9], v[8:9], 1, s[70:71]
	v_lshl_add_u64 v[6:7], v[6:7], 0, s[80:81]
	s_addc_u32 s69, s79, s69
	global_load_dwordx4 v[146:149], v[8:9], off
	global_load_dwordx4 v[150:153], v[6:7], off
	v_lshl_or_b32 v6, s18, 9, v72
	s_add_u32 s18, s14, s36
	s_addc_u32 s19, s15, s37
	v_lshlrev_b32_e32 v190, 1, v72
	v_ashrrev_i32_e32 v7, 31, v6
	s_lshl_b32 s26, s0, 12
	v_lshl_add_u64 v[8:9], s[18:19], 0, v[190:191]
	v_lshl_add_u64 v[6:7], v[6:7], 1, s[70:71]
	v_lshl_add_u64 v[8:9], v[8:9], 0, s[26:27]
	global_load_dwordx4 v[158:161], v[6:7], off
	global_load_dwordx4 v[18:21], v[8:9], off
	v_lshl_add_u64 v[6:7], s[68:69], 0, v[190:191]
	v_lshl_add_u64 v[10:11], v[6:7], 0, s[82:83]
	global_load_dwordx4 v[42:45], v[10:11], off
	v_lshl_add_u64 v[10:11], v[6:7], 0, s[84:85]
	global_load_dwordx4 v[38:41], v[10:11], off
	global_load_dwordx4 v[14:17], v[8:9], off offset:1024
	v_lshl_add_u64 v[10:11], v[6:7], 0, s[86:87]
	global_load_dwordx4 v[34:37], v[10:11], off
	s_nop 0
	global_load_dwordx4 v[10:13], v[8:9], off offset:2048
	v_lshl_add_u64 v[6:7], v[6:7], 0, s[80:81]
	global_load_dwordx4 v[26:29], v[6:7], off
	s_nop 0
	global_load_dwordx4 v[6:9], v[8:9], off offset:3072
	s_lshl_b32 s26, s88, 2
	s_and_b32 s26, s26, 0xfffffe00
	v_or_b32_e32 v22, s26, v72
	s_lshl_b32 s26, s5, 3
	s_ashr_i32 s1, s88, 8
	s_and_b32 s26, s26, 8
	s_add_u32 s70, s89, s26
	v_add_u32_e32 v24, 0x800, v22
	s_addc_u32 s71, s90, 0
	v_ashrrev_i32_e32 v25, 31, v24
	v_lshl_add_u64 v[92:93], v[24:25], 1, s[70:71]
	v_add_u32_e32 v24, 0x1000, v22
	v_ashrrev_i32_e32 v25, 31, v24
	v_lshl_add_u64 v[86:87], v[24:25], 1, s[70:71]
	v_add_u32_e32 v24, 0x1800, v22
	v_ashrrev_i32_e32 v25, 31, v24
	v_lshl_add_u64 v[84:85], v[24:25], 1, s[70:71]
	v_add_u32_e32 v24, 0x2000, v22
	v_ashrrev_i32_e32 v25, 31, v24
	v_lshl_add_u64 v[80:81], v[24:25], 1, s[70:71]
	v_add_u32_e32 v24, 0x2800, v22
	v_ashrrev_i32_e32 v23, 31, v22
	v_ashrrev_i32_e32 v25, 31, v24
	v_lshl_add_u64 v[94:95], v[22:23], 1, s[70:71]
	v_lshl_add_u64 v[54:55], v[24:25], 1, s[70:71]
	v_add_u32_e32 v24, 0x3000, v22
	v_add_u32_e32 v22, 0x3800, v22
	v_ashrrev_i32_e32 v23, 31, v22
	v_lshl_add_u64 v[46:47], v[22:23], 1, s[70:71]
	v_lshl_or_b32 v22, s1, 10, v72
	v_lshl_or_b32 v100, s5, 4, v111
	s_add_u32 s36, s23, s36
	v_lshl_add_u32 v22, s0, 11, v22
	v_mul_lo_u32 v100, v100, s7
	v_ashrrev_i32_e32 v25, 31, v24
	s_addc_u32 s37, s21, s37
	v_ashrrev_i32_e32 v23, 31, v22
	v_add_u32_e32 v101, v236, v100
	v_add_u32_e32 v100, v114, v100
	v_lshl_add_u64 v[48:49], v[24:25], 1, s[70:71]
	v_lshl_add_u64 v[22:23], v[22:23], 1, s[36:37]
	v_add_u32_e32 v100, 0x8800, v100
	global_load_dwordx2 v[98:99], v[94:95], off
	global_load_dwordx2 v[96:97], v[92:93], off
	global_load_dwordx2 v[90:91], v[86:87], off
	global_load_dwordx2 v[88:89], v[84:85], off
	global_load_dwordx2 v[82:83], v[80:81], off
	global_load_dwordx2 v[78:79], v[54:55], off
	global_load_dwordx2 v[52:53], v[48:49], off
	global_load_dwordx2 v[50:51], v[46:47], off
	global_load_dwordx4 v[30:33], v[22:23], off
	s_nop 0
	global_load_dwordx4 v[22:25], v[22:23], off offset:1024
	s_waitcnt vmcnt(25)
	ds_write_b128 v101, v[126:129]
	s_waitcnt vmcnt(24)
	ds_write2_b64 v100, v[130:131], v[132:133] offset1:4
	s_waitcnt vmcnt(23)
	ds_write_b128 v101, v[134:137] offset:64
	s_waitcnt vmcnt(22)
	ds_write2_b64 v100, v[138:139], v[140:141] offset0:8 offset1:12
	s_waitcnt vmcnt(21)
	ds_write_b128 v101, v[142:145] offset:128
	s_waitcnt vmcnt(20)
	ds_write2_b64 v100, v[146:147], v[148:149] offset0:16 offset1:20
	s_waitcnt vmcnt(19)
	ds_write_b128 v101, v[150:153] offset:192
	s_waitcnt vmcnt(18)
	ds_write2_b64 v100, v[158:159], v[160:161] offset0:24 offset1:28
	s_waitcnt lgkmcnt(0)
	s_barrier
	ds_read_b64_tr_b16 v[128:129], v112 offset:1088
	ds_read_b64_tr_b16 v[126:127], v112
	ds_read_b64_tr_b16 v[130:131], v112 offset:32
	ds_read_b64_tr_b16 v[132:133], v112 offset:8704
	ds_read_b64_tr_b16 v[134:135], v112 offset:9792
	s_waitcnt vmcnt(16) lgkmcnt(3)
	v_mfma_f32_16x16x32_bf16 v[126:129], v[126:129], v[42:45], 0
	s_lshl_b32 s26, s1, 1
	s_lshl_b32 s5, s0, 2
	s_lshl_b32 s0, s0, 8
	s_waitcnt vmcnt(15) lgkmcnt(0)
	v_mfma_f32_16x16x32_bf16 v[126:129], v[132:135], v[38:41], v[126:129]
	ds_read_b64_tr_b16 v[132:133], v112 offset:17408
	ds_read_b64_tr_b16 v[134:135], v112 offset:18496
	s_add_i32 s5, s5, s26
	s_add_i32 s29, s29, s22
	s_waitcnt vmcnt(13) lgkmcnt(0)
	v_mfma_f32_16x16x32_bf16 v[126:129], v[132:135], v[34:37], v[126:129]
	ds_read_b64_tr_b16 v[132:133], v112 offset:26112
	ds_read_b64_tr_b16 v[134:135], v112 offset:27200
	s_waitcnt vmcnt(11) lgkmcnt(0)
	v_mfma_f32_16x16x32_bf16 v[126:129], v[132:135], v[26:29], v[126:129]
	ds_read_b64_tr_b16 v[132:133], v112 offset:1120
	s_nop 6
	v_cvt_pk_bf16_f32 v134, v126, v127
	v_cvt_pk_bf16_f32 v135, v128, v129
	s_waitcnt lgkmcnt(0)
	v_mfma_f32_16x16x32_bf16 v[126:129], v[130:133], v[42:45], 0
	ds_read_b64_tr_b16 v[130:131], v112 offset:8736
	ds_read_b64_tr_b16 v[132:133], v112 offset:9824
	s_waitcnt lgkmcnt(0)
	v_mfma_f32_16x16x32_bf16 v[126:129], v[130:133], v[38:41], v[126:129]
	ds_read_b64_tr_b16 v[130:131], v112 offset:17440
	ds_read_b64_tr_b16 v[132:133], v112 offset:18528
	s_waitcnt lgkmcnt(0)
	v_mfma_f32_16x16x32_bf16 v[126:129], v[130:133], v[34:37], v[126:129]
	ds_read_b64_tr_b16 v[130:131], v112 offset:26144
	ds_read_b64_tr_b16 v[132:133], v112 offset:27232
	s_waitcnt lgkmcnt(0)
	v_mfma_f32_16x16x32_bf16 v[126:129], v[130:133], v[26:29], v[126:129]
	s_nop 7
	v_cvt_pk_bf16_f32 v136, v126, v127
	v_lshlrev_b32_e32 v126, 3, v113
	v_or_b32_e32 v100, s4, v126
	v_cvt_pk_bf16_f32 v137, v128, v129
	v_ashrrev_i32_e32 v101, 31, v100
	v_permlane16_swap_b32_e32 v134, v136
	v_permlane16_swap_b32_e32 v135, v137
	v_lshl_add_u64 v[100:101], v[100:101], 1, s[68:69]
	global_store_dwordx4 v[100:101], v[134:137], off nt
	ds_read_b64_tr_b16 v[130:131], v112 offset:1152
	ds_read_b64_tr_b16 v[128:129], v112 offset:64
	ds_read_b64_tr_b16 v[132:133], v112 offset:96
	ds_read_b64_tr_b16 v[134:135], v112 offset:8768
	ds_read_b64_tr_b16 v[136:137], v112 offset:9856
	s_waitcnt lgkmcnt(3)
	v_mfma_f32_16x16x32_bf16 v[128:131], v[128:131], v[42:45], 0
	s_lshl_b32 s4, s1, 6
	s_lshl_b32 s1, s1, 7
	s_add_i32 s0, s0, s1
	s_waitcnt lgkmcnt(0)
	v_mfma_f32_16x16x32_bf16 v[128:131], v[134:137], v[38:41], v[128:131]
	ds_read_b64_tr_b16 v[134:135], v112 offset:17472
	ds_read_b64_tr_b16 v[136:137], v112 offset:18560
	s_waitcnt lgkmcnt(0)
	v_mfma_f32_16x16x32_bf16 v[128:131], v[134:137], v[34:37], v[128:131]
	ds_read_b64_tr_b16 v[134:135], v112 offset:26176
	ds_read_b64_tr_b16 v[136:137], v112 offset:27264
	s_waitcnt lgkmcnt(0)
	v_mfma_f32_16x16x32_bf16 v[128:131], v[134:137], v[26:29], v[128:131]
	ds_read_b64_tr_b16 v[134:135], v112 offset:1184
	s_nop 6
	v_cvt_pk_bf16_f32 v128, v128, v129
	v_cvt_pk_bf16_f32 v129, v130, v131
	s_waitcnt lgkmcnt(0)
	v_mfma_f32_16x16x32_bf16 v[130:133], v[132:135], v[42:45], 0
	ds_read_b64_tr_b16 v[134:135], v112 offset:8800
	ds_read_b64_tr_b16 v[136:137], v112 offset:9888
	s_waitcnt lgkmcnt(0)
	v_mfma_f32_16x16x32_bf16 v[130:133], v[134:137], v[38:41], v[130:133]
	ds_read_b64_tr_b16 v[134:135], v112 offset:17504
	ds_read_b64_tr_b16 v[136:137], v112 offset:18592
	s_waitcnt lgkmcnt(0)
	v_mfma_f32_16x16x32_bf16 v[130:133], v[134:137], v[34:37], v[130:133]
	ds_read_b64_tr_b16 v[134:135], v112 offset:26208
	ds_read_b64_tr_b16 v[136:137], v112 offset:27296
	s_waitcnt lgkmcnt(0)
	v_mfma_f32_16x16x32_bf16 v[130:133], v[134:137], v[26:29], v[130:133]
	s_nop 7
	v_cvt_pk_bf16_f32 v130, v130, v131
	v_cvt_pk_bf16_f32 v131, v132, v133
	s_nop 0
	v_permlane16_swap_b32_e32 v128, v130
	v_permlane16_swap_b32_e32 v129, v131
	global_store_dwordx4 v[100:101], v[128:131], off offset:1024 nt
	ds_read_b64_tr_b16 v[130:131], v112 offset:1216
	ds_read_b64_tr_b16 v[128:129], v112 offset:128
	ds_read_b64_tr_b16 v[132:133], v112 offset:160
	ds_read_b64_tr_b16 v[134:135], v112 offset:8832
	ds_read_b64_tr_b16 v[136:137], v112 offset:9920
	s_waitcnt lgkmcnt(3)
	v_mfma_f32_16x16x32_bf16 v[128:131], v[128:131], v[42:45], 0
	s_waitcnt lgkmcnt(0)
	v_mfma_f32_16x16x32_bf16 v[128:131], v[134:137], v[38:41], v[128:131]
	ds_read_b64_tr_b16 v[134:135], v112 offset:17536
	ds_read_b64_tr_b16 v[136:137], v112 offset:18624
	s_waitcnt lgkmcnt(0)
	v_mfma_f32_16x16x32_bf16 v[128:131], v[134:137], v[34:37], v[128:131]
	ds_read_b64_tr_b16 v[134:135], v112 offset:26240
	ds_read_b64_tr_b16 v[136:137], v112 offset:27328
	s_waitcnt lgkmcnt(0)
	v_mfma_f32_16x16x32_bf16 v[128:131], v[134:137], v[26:29], v[128:131]
	ds_read_b64_tr_b16 v[134:135], v112 offset:1248
	s_nop 6
	v_cvt_pk_bf16_f32 v128, v128, v129
	v_cvt_pk_bf16_f32 v129, v130, v131
	s_waitcnt lgkmcnt(0)
	v_mfma_f32_16x16x32_bf16 v[130:133], v[132:135], v[42:45], 0
	ds_read_b64_tr_b16 v[134:135], v112 offset:8864
	ds_read_b64_tr_b16 v[136:137], v112 offset:9952
	s_waitcnt lgkmcnt(0)
	v_mfma_f32_16x16x32_bf16 v[130:133], v[134:137], v[38:41], v[130:133]
	ds_read_b64_tr_b16 v[134:135], v112 offset:17568
	ds_read_b64_tr_b16 v[136:137], v112 offset:18656
	s_waitcnt lgkmcnt(0)
	v_mfma_f32_16x16x32_bf16 v[130:133], v[134:137], v[34:37], v[130:133]
	ds_read_b64_tr_b16 v[134:135], v112 offset:26272
	ds_read_b64_tr_b16 v[136:137], v112 offset:27360
	s_waitcnt lgkmcnt(0)
	v_mfma_f32_16x16x32_bf16 v[130:133], v[134:137], v[26:29], v[130:133]
	s_nop 7
	v_cvt_pk_bf16_f32 v130, v130, v131
	v_cvt_pk_bf16_f32 v131, v132, v133
	s_nop 0
	v_permlane16_swap_b32_e32 v128, v130
	v_permlane16_swap_b32_e32 v129, v131
	global_store_dwordx4 v[100:101], v[128:131], off offset:2048 nt
	ds_read_b64_tr_b16 v[130:131], v112 offset:1280
	ds_read_b64_tr_b16 v[128:129], v112 offset:192
	ds_read_b64_tr_b16 v[132:133], v112 offset:224
	ds_read_b64_tr_b16 v[134:135], v112 offset:8896
	ds_read_b64_tr_b16 v[136:137], v112 offset:9984
	s_waitcnt lgkmcnt(3)
	v_mfma_f32_16x16x32_bf16 v[128:131], v[128:131], v[42:45], 0
	s_waitcnt lgkmcnt(0)
	v_mfma_f32_16x16x32_bf16 v[128:131], v[134:137], v[38:41], v[128:131]
	ds_read_b64_tr_b16 v[134:135], v112 offset:17600
	ds_read_b64_tr_b16 v[136:137], v112 offset:18688
	s_waitcnt lgkmcnt(0)
	v_mfma_f32_16x16x32_bf16 v[128:131], v[134:137], v[34:37], v[128:131]
	ds_read_b64_tr_b16 v[134:135], v112 offset:26304
	ds_read_b64_tr_b16 v[136:137], v112 offset:27392
	s_waitcnt lgkmcnt(0)
	v_mfma_f32_16x16x32_bf16 v[128:131], v[134:137], v[26:29], v[128:131]
	ds_read_b64_tr_b16 v[134:135], v112 offset:1312
	s_nop 6
	v_cvt_pk_bf16_f32 v128, v128, v129
	v_cvt_pk_bf16_f32 v129, v130, v131
	s_waitcnt lgkmcnt(0)
	v_mfma_f32_16x16x32_bf16 v[130:133], v[132:135], v[42:45], 0
	ds_read_b64_tr_b16 v[134:135], v112 offset:8928
	ds_read_b64_tr_b16 v[136:137], v112 offset:10016
	s_waitcnt lgkmcnt(0)
	v_mfma_f32_16x16x32_bf16 v[130:133], v[134:137], v[38:41], v[130:133]
	ds_read_b64_tr_b16 v[134:135], v112 offset:17632
	ds_read_b64_tr_b16 v[136:137], v112 offset:18720
	s_waitcnt lgkmcnt(0)
	v_mfma_f32_16x16x32_bf16 v[130:133], v[134:137], v[34:37], v[130:133]
	ds_read_b64_tr_b16 v[134:135], v112 offset:26336
	ds_read_b64_tr_b16 v[136:137], v112 offset:27424
	s_waitcnt lgkmcnt(0)
	v_mfma_f32_16x16x32_bf16 v[130:133], v[134:137], v[26:29], v[130:133]
	s_nop 7
	v_cvt_pk_bf16_f32 v130, v130, v131
	v_cvt_pk_bf16_f32 v131, v132, v133
	s_nop 0
	v_permlane16_swap_b32_e32 v128, v130
	v_permlane16_swap_b32_e32 v129, v131
	global_store_dwordx4 v[100:101], v[128:131], off offset:3072 nt
	s_waitcnt vmcnt(13)
	s_nop 0
	v_lshlrev_b32_e32 v128, 16, v98
	v_and_b32_e32 v129, 0xffff0000, v98
	v_lshlrev_b32_e32 v130, 16, v99
	v_and_b32_e32 v131, 0xffff0000, v99
	ds_read_b128 v[98:101], v125 offset:34816
	s_waitcnt lgkmcnt(0)
	v_mfma_f32_16x16x32_bf16 v[98:101], v[42:45], v[98:101], v[128:131]
	s_nop 2
	ds_read_b128 v[128:131], v125 offset:34880
	s_waitcnt lgkmcnt(0)
	v_mfma_f32_16x16x32_bf16 v[98:101], v[38:41], v[128:131], v[98:101]
	ds_read_b128 v[128:131], v125 offset:34944
	s_waitcnt lgkmcnt(0)
	v_mfma_f32_16x16x32_bf16 v[98:101], v[34:37], v[128:131], v[98:101]
	ds_read_b128 v[128:131], v125 offset:35008
	s_waitcnt lgkmcnt(0)
	v_mfma_f32_16x16x32_bf16 v[98:101], v[26:29], v[128:131], v[98:101]
	s_nop 7
	v_cvt_pk_bf16_f32 v98, v98, v99
	v_cvt_pk_bf16_f32 v99, v100, v101
	global_store_dwordx2 v[94:95], v[98:99], off nt
	ds_read_b128 v[98:101], v125 offset:39168
	s_waitcnt vmcnt(13)
	v_lshlrev_b32_e32 v94, 16, v96
	v_and_b32_e32 v95, 0xffff0000, v96
	v_lshlrev_b32_e32 v96, 16, v97
	v_and_b32_e32 v97, 0xffff0000, v97
	s_waitcnt lgkmcnt(0)
	s_nop 0
	v_mfma_f32_16x16x32_bf16 v[94:97], v[42:45], v[98:101], v[94:97]
	ds_read_b128 v[98:101], v125 offset:39232
	s_waitcnt lgkmcnt(0)
	v_mfma_f32_16x16x32_bf16 v[94:97], v[38:41], v[98:101], v[94:97]
	ds_read_b128 v[98:101], v125 offset:39296
	s_waitcnt lgkmcnt(0)
	v_mfma_f32_16x16x32_bf16 v[94:97], v[34:37], v[98:101], v[94:97]
	ds_read_b128 v[98:101], v125 offset:39360
	s_waitcnt lgkmcnt(0)
	v_mfma_f32_16x16x32_bf16 v[94:97], v[26:29], v[98:101], v[94:97]
	s_nop 7
	v_cvt_pk_bf16_f32 v94, v94, v95
	v_cvt_pk_bf16_f32 v95, v96, v97
	ds_read_b128 v[96:99], v125 offset:43520
	global_store_dwordx2 v[92:93], v[94:95], off nt
	s_waitcnt vmcnt(13)
	v_lshlrev_b32_e32 v92, 16, v90
	v_and_b32_e32 v93, 0xffff0000, v90
	v_lshlrev_b32_e32 v94, 16, v91
	v_and_b32_e32 v95, 0xffff0000, v91
	s_waitcnt lgkmcnt(0)
	s_nop 0
	v_mfma_f32_16x16x32_bf16 v[90:93], v[42:45], v[96:99], v[92:95]
	s_nop 2
	ds_read_b128 v[94:97], v125 offset:43584
	s_waitcnt lgkmcnt(0)
	v_mfma_f32_16x16x32_bf16 v[90:93], v[38:41], v[94:97], v[90:93]
	ds_read_b128 v[94:97], v125 offset:43648
	s_waitcnt lgkmcnt(0)
	v_mfma_f32_16x16x32_bf16 v[90:93], v[34:37], v[94:97], v[90:93]
	ds_read_b128 v[94:97], v125 offset:43712
	s_waitcnt lgkmcnt(0)
	v_mfma_f32_16x16x32_bf16 v[90:93], v[26:29], v[94:97], v[90:93]
	s_nop 7
	v_cvt_pk_bf16_f32 v90, v90, v91
	v_cvt_pk_bf16_f32 v91, v92, v93
	global_store_dwordx2 v[86:87], v[90:91], off nt
	ds_read_b128 v[90:93], v125 offset:47872
	s_waitcnt vmcnt(13)
	v_lshlrev_b32_e32 v86, 16, v88
	v_and_b32_e32 v87, 0xffff0000, v88
	v_lshlrev_b32_e32 v88, 16, v89
	v_and_b32_e32 v89, 0xffff0000, v89
	s_waitcnt lgkmcnt(0)
	s_nop 0
	v_mfma_f32_16x16x32_bf16 v[86:89], v[42:45], v[90:93], v[86:89]
	ds_read_b128 v[90:93], v125 offset:47936
	s_waitcnt lgkmcnt(0)
	v_mfma_f32_16x16x32_bf16 v[86:89], v[38:41], v[90:93], v[86:89]
	ds_read_b128 v[90:93], v125 offset:48000
	s_waitcnt lgkmcnt(0)
	v_mfma_f32_16x16x32_bf16 v[86:89], v[34:37], v[90:93], v[86:89]
	ds_read_b128 v[90:93], v125 offset:48064
	s_waitcnt lgkmcnt(0)
	v_mfma_f32_16x16x32_bf16 v[86:89], v[26:29], v[90:93], v[86:89]
	s_nop 7
	v_cvt_pk_bf16_f32 v86, v86, v87
	v_cvt_pk_bf16_f32 v87, v88, v89
	ds_read_b128 v[88:91], v125 offset:52224
	global_store_dwordx2 v[84:85], v[86:87], off nt
	s_waitcnt vmcnt(13)
	v_lshlrev_b32_e32 v84, 16, v82
	v_and_b32_e32 v85, 0xffff0000, v82
	v_lshlrev_b32_e32 v86, 16, v83
	v_and_b32_e32 v87, 0xffff0000, v83
	s_waitcnt lgkmcnt(0)
	s_nop 0
	v_mfma_f32_16x16x32_bf16 v[82:85], v[42:45], v[88:91], v[84:87]
	s_nop 2
	ds_read_b128 v[86:89], v125 offset:52288
	s_waitcnt lgkmcnt(0)
	v_mfma_f32_16x16x32_bf16 v[82:85], v[38:41], v[86:89], v[82:85]
	ds_read_b128 v[86:89], v125 offset:52352
	s_waitcnt lgkmcnt(0)
	v_mfma_f32_16x16x32_bf16 v[82:85], v[34:37], v[86:89], v[82:85]
	ds_read_b128 v[86:89], v125 offset:52416
	s_waitcnt lgkmcnt(0)
	v_mfma_f32_16x16x32_bf16 v[82:85], v[26:29], v[86:89], v[82:85]
	s_nop 7
	v_cvt_pk_bf16_f32 v82, v82, v83
	v_cvt_pk_bf16_f32 v83, v84, v85
	ds_read_b128 v[84:87], v125 offset:56576
	global_store_dwordx2 v[80:81], v[82:83], off nt
	s_waitcnt vmcnt(13)
	v_lshlrev_b32_e32 v80, 16, v78
	v_and_b32_e32 v81, 0xffff0000, v78
	v_lshlrev_b32_e32 v82, 16, v79
	v_and_b32_e32 v83, 0xffff0000, v79
	s_waitcnt lgkmcnt(0)
	s_nop 0
	v_mfma_f32_16x16x32_bf16 v[78:81], v[42:45], v[84:87], v[80:83]
	s_nop 2
	ds_read_b128 v[82:85], v125 offset:56640
	s_waitcnt lgkmcnt(0)
	v_mfma_f32_16x16x32_bf16 v[78:81], v[38:41], v[82:85], v[78:81]
	ds_read_b128 v[82:85], v125 offset:56704
	s_waitcnt lgkmcnt(0)
	v_mfma_f32_16x16x32_bf16 v[78:81], v[34:37], v[82:85], v[78:81]
	ds_read_b128 v[82:85], v125 offset:56768
	s_waitcnt lgkmcnt(0)
	v_mfma_f32_16x16x32_bf16 v[78:81], v[26:29], v[82:85], v[78:81]
	s_nop 7
	v_cvt_pk_bf16_f32 v78, v78, v79
	v_cvt_pk_bf16_f32 v79, v80, v81
	global_store_dwordx2 v[54:55], v[78:79], off nt
	s_waitcnt vmcnt(13)
	v_lshlrev_b32_e32 v78, 16, v52
	v_and_b32_e32 v79, 0xffff0000, v52
	v_lshlrev_b32_e32 v80, 16, v53
	v_and_b32_e32 v81, 0xffff0000, v53
	ds_read_b128 v[52:55], v125 offset:60928
	s_waitcnt lgkmcnt(0)
	v_mfma_f32_16x16x32_bf16 v[52:55], v[42:45], v[52:55], v[78:81]
	s_nop 2
	ds_read_b128 v[78:81], v125 offset:60992
	s_waitcnt lgkmcnt(0)
	v_mfma_f32_16x16x32_bf16 v[52:55], v[38:41], v[78:81], v[52:55]
	ds_read_b128 v[78:81], v125 offset:61056
	s_waitcnt lgkmcnt(0)
	v_mfma_f32_16x16x32_bf16 v[52:55], v[34:37], v[78:81], v[52:55]
	ds_read_b128 v[78:81], v125 offset:61120
	s_waitcnt lgkmcnt(0)
	v_mfma_f32_16x16x32_bf16 v[52:55], v[26:29], v[78:81], v[52:55]
	s_nop 7
	v_cvt_pk_bf16_f32 v52, v52, v53
	v_cvt_pk_bf16_f32 v53, v54, v55
	global_store_dwordx2 v[48:49], v[52:53], off nt
	ds_read_b128 v[52:55], v125 offset:65280
	s_waitcnt vmcnt(13)
	v_lshlrev_b32_e32 v48, 16, v50
	v_and_b32_e32 v49, 0xffff0000, v50
	v_lshlrev_b32_e32 v50, 16, v51
	v_and_b32_e32 v51, 0xffff0000, v51
	s_waitcnt lgkmcnt(0)
	s_nop 0
	v_mfma_f32_16x16x32_bf16 v[42:45], v[42:45], v[52:55], v[48:51]
	s_nop 2
	ds_read_b128 v[48:51], v125 offset:65344
	s_waitcnt lgkmcnt(0)
	v_mfma_f32_16x16x32_bf16 v[38:41], v[38:41], v[48:51], v[42:45]
	s_nop 2
	ds_read_b128 v[42:45], v125 offset:65408
	s_waitcnt lgkmcnt(0)
	v_mfma_f32_16x16x32_bf16 v[34:37], v[34:37], v[42:45], v[38:41]
	s_nop 2
	ds_read_b128 v[38:41], v125 offset:65472
	s_waitcnt lgkmcnt(0)
	v_mfma_f32_16x16x32_bf16 v[26:29], v[26:29], v[38:41], v[34:37]
	s_nop 2
	v_add_u32_e32 v36, s1, v112
	s_nop 3
	v_cvt_pk_bf16_f32 v26, v26, v27
	v_cvt_pk_bf16_f32 v27, v28, v29
	global_store_dwordx2 v[46:47], v[26:27], off nt
	s_waitcnt vmcnt(13)
	v_lshlrev_b32_e32 v26, 16, v30
	v_and_b32_e32 v27, 0xffff0000, v30
	v_or_b32_e32 v30, s4, v111
	v_mad_u64_u32 v[34:35], s[68:69], v30, s7, v[76:77]
	v_lshlrev_b32_e32 v28, 16, v31
	v_and_b32_e32 v29, 0xffff0000, v31
	ds_read_b64_tr_b16 v[40:41], v36 offset:1088
	ds_read_b64_tr_b16 v[38:39], v36
	ds_read_b64_tr_b16 v[30:31], v36 offset:32
	ds_read_b128 v[42:45], v34 offset:34816
	s_waitcnt lgkmcnt(0)
	v_mfma_f32_16x16x32_bf16 v[26:29], v[42:45], v[18:21], v[26:29]
	ds_read_b64_tr_b16 v[42:43], v36 offset:8704
	ds_read_b64_tr_b16 v[44:45], v36 offset:9792
	v_mfma_f32_16x16x32_bf16 v[38:41], v[38:41], v[18:21], 0
	s_waitcnt lgkmcnt(0)
	v_mfma_f32_16x16x32_bf16 v[38:41], v[42:45], v[14:17], v[38:41]
	ds_read_b128 v[42:45], v34 offset:34880
	s_waitcnt lgkmcnt(0)
	v_mfma_f32_16x16x32_bf16 v[26:29], v[42:45], v[14:17], v[26:29]
	ds_read_b64_tr_b16 v[42:43], v36 offset:17408
	ds_read_b64_tr_b16 v[44:45], v36 offset:18496
	s_waitcnt lgkmcnt(0)
	v_mfma_f32_16x16x32_bf16 v[38:41], v[42:45], v[10:13], v[38:41]
	ds_read_b128 v[42:45], v34 offset:34944
	s_waitcnt lgkmcnt(0)
	v_mfma_f32_16x16x32_bf16 v[26:29], v[42:45], v[10:13], v[26:29]
	ds_read_b64_tr_b16 v[42:43], v36 offset:26112
	ds_read_b64_tr_b16 v[44:45], v36 offset:27200
	s_waitcnt lgkmcnt(0)
	v_mfma_f32_16x16x32_bf16 v[38:41], v[42:45], v[6:9], v[38:41]
	ds_read_b128 v[42:45], v34 offset:35008
	s_waitcnt lgkmcnt(0)
	v_mfma_f32_16x16x32_bf16 v[26:29], v[42:45], v[6:9], v[26:29]
	s_nop 4
	v_cvt_pk_bf16_f32 v38, v38, v39
	v_cvt_pk_bf16_f32 v39, v40, v41
	v_lshlrev_b32_e32 v40, 16, v32
	v_and_b32_e32 v41, 0xffff0000, v32
	v_lshlrev_b32_e32 v42, 16, v33
	v_and_b32_e32 v43, 0xffff0000, v33
	ds_read_b64_tr_b16 v[32:33], v36 offset:1120
	v_cvt_pk_bf16_f32 v26, v26, v27
	v_cvt_pk_bf16_f32 v27, v28, v29
	v_or_b32_e32 v28, s4, v115
	v_mad_u64_u32 v[44:45], s[68:69], v28, s7, v[76:77]
	s_waitcnt lgkmcnt(0)
	v_mfma_f32_16x16x32_bf16 v[28:31], v[30:33], v[18:21], 0
	ds_read_b128 v[32:35], v44 offset:34816
	s_waitcnt lgkmcnt(0)
	v_mfma_f32_16x16x32_bf16 v[32:35], v[32:35], v[18:21], v[40:43]
	s_nop 2
	ds_read_b64_tr_b16 v[40:41], v36 offset:8736
	ds_read_b64_tr_b16 v[42:43], v36 offset:9824
	s_waitcnt lgkmcnt(0)
	v_mfma_f32_16x16x32_bf16 v[28:31], v[40:43], v[14:17], v[28:31]
	ds_read_b128 v[40:43], v44 offset:34880
	s_waitcnt lgkmcnt(0)
	v_mfma_f32_16x16x32_bf16 v[32:35], v[40:43], v[14:17], v[32:35]
	ds_read_b64_tr_b16 v[40:41], v36 offset:17440
	ds_read_b64_tr_b16 v[42:43], v36 offset:18528
	s_waitcnt lgkmcnt(0)
	v_mfma_f32_16x16x32_bf16 v[28:31], v[40:43], v[10:13], v[28:31]
	ds_read_b128 v[40:43], v44 offset:34944
	s_waitcnt lgkmcnt(0)
	v_mfma_f32_16x16x32_bf16 v[32:35], v[40:43], v[10:13], v[32:35]
	ds_read_b64_tr_b16 v[40:41], v36 offset:26144
	ds_read_b64_tr_b16 v[42:43], v36 offset:27232
	s_waitcnt lgkmcnt(0)
	v_mfma_f32_16x16x32_bf16 v[28:31], v[40:43], v[6:9], v[28:31]
	ds_read_b128 v[40:43], v44 offset:35008
	s_waitcnt lgkmcnt(0)
	v_mfma_f32_16x16x32_bf16 v[32:35], v[40:43], v[6:9], v[32:35]
	s_nop 4
	v_cvt_pk_bf16_f32 v41, v30, v31
	v_or_b32_e32 v30, s0, v113
	v_lshlrev_b32_e32 v30, 3, v30
	v_cvt_pk_bf16_f32 v40, v28, v29
	v_ashrrev_i32_e32 v31, 31, v30
	s_nop 0
	v_permlane16_swap_b32_e32 v38, v40
	v_permlane16_swap_b32_e32 v39, v41
	v_lshl_add_u64 v[30:31], v[30:31], 1, s[18:19]
	s_lshl_b32 s0, s5, 9
	global_store_dwordx4 v[30:31], v[38:41], off nt
	v_or_b32_e32 v30, s0, v72
	v_ashrrev_i32_e32 v31, 31, v30
	v_cvt_pk_bf16_f32 v28, v32, v33
	v_cvt_pk_bf16_f32 v29, v34, v35
	v_lshl_add_u64 v[34:35], v[30:31], 1, s[36:37]
	global_store_dwordx4 v[34:35], v[26:29], off nt
	ds_read_b64_tr_b16 v[32:33], v36 offset:1152
	ds_read_b64_tr_b16 v[30:31], v36 offset:64
	ds_read_b64_tr_b16 v[38:39], v36 offset:96
	s_waitcnt vmcnt(14)
	v_lshlrev_b32_e32 v26, 16, v22
	v_and_b32_e32 v27, 0xffff0000, v22
	v_or_b32_e32 v22, s4, v116
	v_lshlrev_b32_e32 v28, 16, v23
	v_and_b32_e32 v29, 0xffff0000, v23
	v_mad_u64_u32 v[22:23], s[36:37], v22, s7, v[76:77]
	ds_read_b128 v[40:43], v22 offset:34816
	s_waitcnt lgkmcnt(0)
	v_mfma_f32_16x16x32_bf16 v[26:29], v[40:43], v[18:21], v[26:29]
	ds_read_b64_tr_b16 v[40:41], v36 offset:8768
	ds_read_b64_tr_b16 v[42:43], v36 offset:9856
	s_cmpk_lt_i32 s29, 0x100
	v_mfma_f32_16x16x32_bf16 v[30:33], v[30:33], v[18:21], 0
	s_waitcnt lgkmcnt(0)
	v_mfma_f32_16x16x32_bf16 v[30:33], v[40:43], v[14:17], v[30:33]
	ds_read_b128 v[40:43], v22 offset:34880
	s_waitcnt lgkmcnt(0)
	v_mfma_f32_16x16x32_bf16 v[26:29], v[40:43], v[14:17], v[26:29]
	ds_read_b64_tr_b16 v[40:41], v36 offset:17472
	ds_read_b64_tr_b16 v[42:43], v36 offset:18560
	s_waitcnt lgkmcnt(0)
	v_mfma_f32_16x16x32_bf16 v[30:33], v[40:43], v[10:13], v[30:33]
	ds_read_b128 v[40:43], v22 offset:34944
	s_waitcnt lgkmcnt(0)
	v_mfma_f32_16x16x32_bf16 v[26:29], v[40:43], v[10:13], v[26:29]
	ds_read_b64_tr_b16 v[40:41], v36 offset:26176
	ds_read_b64_tr_b16 v[42:43], v36 offset:27264
	s_waitcnt lgkmcnt(0)
	v_mfma_f32_16x16x32_bf16 v[30:33], v[40:43], v[6:9], v[30:33]
	ds_read_b128 v[40:43], v22 offset:35008
	s_waitcnt lgkmcnt(0)
	v_mfma_f32_16x16x32_bf16 v[26:29], v[40:43], v[6:9], v[26:29]
	s_nop 4
	v_cvt_pk_bf16_f32 v22, v30, v31
	v_lshlrev_b32_e32 v30, 16, v25
	v_and_b32_e32 v31, 0xffff0000, v25
	v_cvt_pk_bf16_f32 v26, v26, v27
	v_cvt_pk_bf16_f32 v27, v28, v29
	v_lshlrev_b32_e32 v28, 16, v24
	v_and_b32_e32 v29, 0xffff0000, v24
	v_or_b32_e32 v24, s4, v117
	v_mad_u64_u32 v[24:25], s[4:5], v24, s7, v[76:77]
	ds_read_b64_tr_b16 v[40:41], v36 offset:1184
	ds_read_b128 v[42:45], v24 offset:34816
	s_waitcnt lgkmcnt(1)
	v_mfma_f32_16x16x32_bf16 v[38:41], v[38:41], v[18:21], 0
	v_cvt_pk_bf16_f32 v23, v32, v33
	s_waitcnt lgkmcnt(0)
	v_mfma_f32_16x16x32_bf16 v[18:21], v[42:45], v[18:21], v[28:31]
	s_nop 2
	ds_read_b64_tr_b16 v[28:29], v36 offset:8800
	ds_read_b64_tr_b16 v[30:31], v36 offset:9888
	s_waitcnt lgkmcnt(0)
	v_mfma_f32_16x16x32_bf16 v[28:31], v[28:31], v[14:17], v[38:41]
	s_nop 2
	ds_read_b128 v[38:41], v24 offset:34880
	s_waitcnt lgkmcnt(0)
	v_mfma_f32_16x16x32_bf16 v[14:17], v[38:41], v[14:17], v[18:21]
	s_nop 2
	ds_read_b64_tr_b16 v[18:19], v36 offset:17504
	ds_read_b64_tr_b16 v[20:21], v36 offset:18592
	s_waitcnt lgkmcnt(0)
	v_mfma_f32_16x16x32_bf16 v[18:21], v[18:21], v[10:13], v[28:31]
	s_nop 2
	ds_read_b128 v[28:31], v24 offset:34944
	s_waitcnt lgkmcnt(0)
	v_mfma_f32_16x16x32_bf16 v[10:13], v[28:31], v[10:13], v[14:17]
	s_nop 2
	ds_read_b64_tr_b16 v[14:15], v36 offset:26208
	ds_read_b64_tr_b16 v[16:17], v36 offset:27296
	s_waitcnt lgkmcnt(0)
	v_mfma_f32_16x16x32_bf16 v[14:17], v[14:17], v[6:9], v[18:21]
	s_nop 2
	ds_read_b128 v[18:21], v24 offset:35008
	s_waitcnt lgkmcnt(0)
	v_mfma_f32_16x16x32_bf16 v[6:9], v[18:21], v[6:9], v[10:13]
	s_nop 1
	v_cvt_pk_bf16_f32 v24, v14, v15
	v_cvt_pk_bf16_f32 v25, v16, v17
	s_nop 0
	v_permlane16_swap_b32_e32 v22, v24
	s_nop 1
	v_cvt_pk_bf16_f32 v28, v6, v7
	v_or_b32_e32 v6, s0, v126
	v_or_b32_e32 v6, 0x200, v6
	v_ashrrev_i32_e32 v7, 31, v6
	v_permlane16_swap_b32_e32 v23, v25
	v_lshl_add_u64 v[6:7], v[6:7], 1, s[18:19]
	v_cvt_pk_bf16_f32 v29, v8, v9
	global_store_dwordx4 v[6:7], v[22:25], off nt
	global_store_dwordx4 v[34:35], v[26:29], off offset:1024 nt
	s_barrier
	s_cbranch_scc0 .LBB0_748

.LBB0_632:
	s_or_b64 exec, exec, s[4:5]
	s_lshl_b32 s4, s1, 10
	s_add_i32 s4, s4, 0
	v_lshlrev_b32_e32 v6, 4, v6
	s_add_i32 s4, s4, 0x25800
	v_and_b32_e32 v6, 0x3f0, v6
	v_add_u32_e32 v6, s4, v6
	s_and_b32 s68, s19, 0xffffffc0
	ds_write_b128 v6, v[2:5]
	v_mov_b32_e32 v6, v235
	s_mul_i32 s5, s1, 0x1200
	s_add_i32 s68, s68, 0
	s_waitcnt lgkmcnt(0)
	s_barrier
	s_add_i32 s5, s77, s5
	v_lshrrev_b32_e32 v7, 2, v6
	s_add_i32 s69, s68, 0x4400
	s_addk_i32 s68, 0xff00
	v_and_b32_e32 v26, 15, v6
	v_and_b32_e32 v7, 12, v7
	s_cmp_lt_i32 s1, 4
	s_cselect_b32 s68, s69, s68
	v_lshlrev_b32_e32 v30, 1, v26
	v_mul_u32_u24_e32 v32, 0x110, v7
	v_lshlrev_b32_e32 v8, 6, v26
	v_lshlrev_b32_e32 v27, 1, v7
	s_cselect_b32 s88, s35, s96
	v_lshlrev_b32_e32 v31, 2, v7
	v_add3_u32 v21, s68, v30, v32
	v_add3_u32 v28, s4, v8, v27
	v_and_b32_e32 v29, 48, v6
	v_lshlrev_b32_e32 v10, 6, v6
	v_add_u32_e32 v20, s88, v31
	ds_read_u16 v11, v21 offset:272
	ds_read_u16 v12, v21 offset:544
	ds_read_u16 v13, v21 offset:816
	ds_read_u16 v14, v21
	ds_read_b128 v[6:9], v20
	v_and_b32_e32 v15, 0x3c0, v10
	s_waitcnt lgkmcnt(4)
	v_lshlrev_b32_e32 v11, 16, v11
	v_add3_u32 v33, s76, v15, v29
	s_waitcnt lgkmcnt(1)
	v_lshlrev_b32_e32 v10, 16, v14
	s_waitcnt lgkmcnt(0)
	v_pk_mul_f32 v[6:7], v[6:7], v[10:11]
	v_lshlrev_b32_e32 v11, 16, v13
	v_lshlrev_b32_e32 v10, 16, v12
	v_pk_mul_f32 v[8:9], v[8:9], v[10:11]
	v_cvt_pk_bf16_f32 v6, v6, v7
	v_cvt_pk_bf16_f32 v7, v8, v9
	ds_write_b64 v28, v[6:7]
	s_waitcnt lgkmcnt(0)
	ds_read_b128 v[6:9], v33
	v_add3_u32 v34, s4, v15, v29
	ds_read_b128 v[10:13], v34
	s_waitcnt lgkmcnt(0)
	v_mfma_f32_16x16x32_bf16 v[6:9], v[6:9], v[10:13], 0
	v_mov_b32_e32 v15, s5
	v_mad_u32_u24 v15, v26, s6, v15
	v_add_u32_e32 v35, v15, v27
	s_nop 4
	v_cvt_pk_bf16_f32 v6, v6, v7
	v_cvt_pk_bf16_f32 v7, v8, v9
	ds_write_b64 v35, v[6:7]
	s_waitcnt lgkmcnt(0)
	v_add_u32_e32 v24, v15, v29
	ds_read_b128 v[6:9], v20 offset:64
	ds_read_u16 v15, v21 offset:4352
	ds_read_u16 v16, v21 offset:4624
	v_mul_u32_u24_e32 v14, 0x90, v26
	v_add3_u32 v36, s86, v29, v14
	ds_read_b128 v[10:13], v36 offset:2304
	ds_read_u16 v22, v21 offset:4896
	ds_read_u16 v23, v21 offset:5168
	s_waitcnt lgkmcnt(4)
	v_lshlrev_b32_e32 v18, 16, v15
	s_waitcnt lgkmcnt(3)
	v_lshlrev_b32_e32 v19, 16, v16
	ds_read_b128 v[14:17], v24
	v_pk_mul_f32 v[6:7], v[6:7], v[18:19]
	s_waitcnt lgkmcnt(1)
	v_lshlrev_b32_e32 v19, 16, v23
	v_lshlrev_b32_e32 v18, 16, v22
	v_pk_mul_f32 v[8:9], v[8:9], v[18:19]
	s_or_b32 s4, s87, 1
	s_lshl_b32 s68, s4, 5
	s_waitcnt lgkmcnt(0)
	v_mfma_f32_16x16x32_bf16 v[6:9], v[10:13], v[14:17], v[6:9]
	s_mul_i32 s5, s4, 0x900
	s_add_i32 s68, s68, 0
	s_add_i32 s5, s77, s5
	s_add_i32 s69, s68, 0x4400
	s_addk_i32 s68, 0xff00
	s_nop 2
	v_cvt_pk_bf16_f32 v6, v6, v7
	v_cvt_pk_bf16_f32 v7, v8, v9
	ds_write_b64 v28, v[6:7]
	s_waitcnt lgkmcnt(0)
	ds_read_b128 v[6:9], v33 offset:1024
	ds_read_b128 v[10:13], v34
	s_waitcnt lgkmcnt(0)
	v_mfma_f32_16x16x32_bf16 v[6:9], v[6:9], v[10:13], 0
	s_cmp_lt_i32 s4, 8
	s_cselect_b32 s68, s69, s68
	s_cselect_b32 s4, s35, s96
	s_nop 4
	v_cvt_pk_bf16_f32 v6, v6, v7
	v_cvt_pk_bf16_f32 v7, v8, v9
	ds_write_b64 v35, v[6:7] offset:32
	s_waitcnt lgkmcnt(0)
	ds_read_u16 v14, v21 offset:8704
	ds_read_u16 v15, v21 offset:8976
	ds_read_b128 v[6:9], v20 offset:128
	ds_read_b128 v[10:13], v36 offset:4608
	ds_read_u16 v22, v21 offset:9248
	ds_read_u16 v23, v21 offset:9520
	s_waitcnt lgkmcnt(4)
	v_lshlrev_b32_e32 v19, 16, v15
	v_lshlrev_b32_e32 v18, 16, v14
	ds_read_b128 v[14:17], v24
	s_waitcnt lgkmcnt(4)
	v_pk_mul_f32 v[6:7], v[6:7], v[18:19]
	s_waitcnt lgkmcnt(1)
	v_lshlrev_b32_e32 v19, 16, v23
	v_lshlrev_b32_e32 v18, 16, v22
	v_pk_mul_f32 v[8:9], v[8:9], v[18:19]
	s_lshl_b32 s0, s0, 2
	s_or_b32 s86, s0, s26
	s_waitcnt lgkmcnt(0)
	v_mfma_f32_16x16x32_bf16 v[6:9], v[10:13], v[14:17], v[6:9]
	s_ashr_i32 s87, s86, 31
	s_bfe_u32 s0, s19, 0x20006
	s_ashr_i32 s90, s19, 8
	s_lshl_b64 s[88:89], s[86:87], 14
	v_mov_b32_e32 v47, v235
	s_nop 2
	v_cvt_pk_bf16_f32 v6, v6, v7
	v_cvt_pk_bf16_f32 v7, v8, v9
	ds_write_b64 v28, v[6:7]
	s_waitcnt lgkmcnt(0)
	ds_read_b128 v[6:9], v33 offset:2048
	ds_read_b128 v[10:13], v34
	s_waitcnt lgkmcnt(0)
	v_mfma_f32_16x16x32_bf16 v[6:9], v[6:9], v[10:13], 0
	s_nop 7
	v_cvt_pk_bf16_f32 v6, v6, v7
	v_cvt_pk_bf16_f32 v7, v8, v9
	ds_write_b64 v35, v[6:7] offset:64
	s_waitcnt lgkmcnt(0)
	ds_read_u16 v10, v21 offset:13328
	ds_read_u16 v22, v21 offset:13600
	ds_read_u16 v23, v21 offset:13872
	ds_read_u16 v14, v21 offset:13056
	ds_read_b128 v[6:9], v20 offset:192
	s_waitcnt lgkmcnt(4)
	v_lshlrev_b32_e32 v15, 16, v10
	ds_read_b128 v[10:13], v36 offset:6912
	s_waitcnt lgkmcnt(3)
	v_lshlrev_b32_e32 v23, 16, v23
	s_waitcnt lgkmcnt(2)
	v_lshlrev_b32_e32 v14, 16, v14
	s_waitcnt lgkmcnt(1)
	v_pk_mul_f32 v[6:7], v[6:7], v[14:15]
	ds_read_b128 v[14:17], v24
	ds_read_b128 v[18:21], v36 offset:6976
	v_lshlrev_b32_e32 v22, 16, v22
	v_pk_mul_f32 v[8:9], v[8:9], v[22:23]
	ds_read_b128 v[22:25], v24 offset:64
	s_waitcnt lgkmcnt(2)
	v_mfma_f32_16x16x32_bf16 v[6:9], v[10:13], v[14:17], v[6:9]
	v_mov_b32_e32 v14, s5
	v_mad_u32_u24 v14, v26, s6, v14
	v_add_u32_e32 v26, v14, v27
	s_waitcnt lgkmcnt(0)
	v_mfma_f32_16x16x32_bf16 v[6:9], v[18:21], v[22:25], v[6:9]
	v_add3_u32 v20, s68, v30, v32
	v_add_u32_e32 v21, s4, v31
	v_add_u32_e32 v24, v14, v29
	s_add_u32 s68, s14, s88
	s_addc_u32 s69, s15, s89
	s_nop 2
	v_cvt_pk_bf16_f32 v6, v6, v7
	v_cvt_pk_bf16_f32 v7, v8, v9
	ds_write_b64 v28, v[6:7]
	s_waitcnt lgkmcnt(0)
	ds_read_b128 v[6:9], v33 offset:3072
	ds_read_b128 v[10:13], v34
	s_waitcnt lgkmcnt(0)
	v_mfma_f32_16x16x32_bf16 v[6:9], v[6:9], v[10:13], 0
	s_add_u32 s88, s23, s88
	s_addc_u32 s89, s21, s89
	s_add_i32 s5, 0, 0x19800
	s_nop 4
	v_cvt_pk_bf16_f32 v6, v6, v7
	v_cvt_pk_bf16_f32 v7, v8, v9
	ds_write_b64 v35, v[6:7] offset:96
	s_waitcnt lgkmcnt(0)
	ds_read_u16 v10, v20
	ds_read_u16 v11, v20 offset:272
	ds_read_b128 v[6:9], v21
	ds_read_u16 v12, v20 offset:816
	ds_read_u16 v13, v20 offset:544
	s_lshl_b32 s91, s90, 2
	s_or_b32 vcc_lo, s91, 1
	s_waitcnt lgkmcnt(4)
	v_lshlrev_b32_e32 v10, 16, v10
	s_waitcnt lgkmcnt(3)
	v_lshlrev_b32_e32 v11, 16, v11
	s_waitcnt lgkmcnt(2)
	v_pk_mul_f32 v[6:7], v[6:7], v[10:11]
	s_waitcnt lgkmcnt(1)
	v_lshlrev_b32_e32 v11, 16, v12
	s_waitcnt lgkmcnt(0)
	v_lshlrev_b32_e32 v10, 16, v13
	v_pk_mul_f32 v[8:9], v[8:9], v[10:11]
	v_cvt_pk_bf16_f32 v6, v6, v7
	v_cvt_pk_bf16_f32 v7, v8, v9
	ds_write_b64 v28, v[6:7]
	s_waitcnt lgkmcnt(0)
	ds_read_b128 v[6:9], v33
	ds_read_b128 v[10:13], v34
	s_waitcnt lgkmcnt(0)
	v_mfma_f32_16x16x32_bf16 v[6:9], v[6:9], v[10:13], 0
	s_lshl_b32 s19, s0, 2
	s_lshl_b64 s[86:87], s[86:87], 15
	s_mov_b32 s4, 1
	s_nop 4
	v_cvt_pk_bf16_f32 v6, v6, v7
	v_cvt_pk_bf16_f32 v7, v8, v9
	ds_write_b64 v26, v[6:7]
	s_waitcnt lgkmcnt(0)
	ds_read_u16 v14, v20 offset:4352
	ds_read_u16 v15, v20 offset:4624
	ds_read_b128 v[6:9], v21 offset:64
	ds_read_b128 v[10:13], v36 offset:2304
	ds_read_u16 v22, v20 offset:4896
	ds_read_u16 v23, v20 offset:5168
	s_waitcnt lgkmcnt(4)
	v_lshlrev_b32_e32 v19, 16, v15
	v_lshlrev_b32_e32 v18, 16, v14
	ds_read_b128 v[14:17], v24
	s_waitcnt lgkmcnt(4)
	v_pk_mul_f32 v[6:7], v[6:7], v[18:19]
	s_waitcnt lgkmcnt(1)
	v_lshlrev_b32_e32 v19, 16, v23
	v_lshlrev_b32_e32 v18, 16, v22
	v_pk_mul_f32 v[8:9], v[8:9], v[18:19]
	s_waitcnt lgkmcnt(0)
	s_nop 0
	v_mfma_f32_16x16x32_bf16 v[6:9], v[10:13], v[14:17], v[6:9]
	s_nop 7
	v_cvt_pk_bf16_f32 v6, v6, v7
	v_cvt_pk_bf16_f32 v7, v8, v9
	ds_write_b64 v28, v[6:7]
	s_waitcnt lgkmcnt(0)
	ds_read_b128 v[6:9], v33 offset:1024
	ds_read_b128 v[10:13], v34
	s_waitcnt lgkmcnt(0)
	v_mfma_f32_16x16x32_bf16 v[6:9], v[6:9], v[10:13], 0
	s_nop 7
	v_cvt_pk_bf16_f32 v6, v6, v7
	v_cvt_pk_bf16_f32 v7, v8, v9
	ds_write_b64 v26, v[6:7] offset:32
	s_waitcnt lgkmcnt(0)
	ds_read_u16 v14, v20 offset:8704
	ds_read_u16 v15, v20 offset:8976
	ds_read_b128 v[6:9], v21 offset:128
	ds_read_b128 v[10:13], v36 offset:4608
	ds_read_u16 v22, v20 offset:9248
	ds_read_u16 v23, v20 offset:9520
	s_waitcnt lgkmcnt(4)
	v_lshlrev_b32_e32 v19, 16, v15
	v_lshlrev_b32_e32 v18, 16, v14
	ds_read_b128 v[14:17], v24
	s_waitcnt lgkmcnt(4)
	v_pk_mul_f32 v[6:7], v[6:7], v[18:19]
	s_waitcnt lgkmcnt(1)
	v_lshlrev_b32_e32 v19, 16, v23
	v_lshlrev_b32_e32 v18, 16, v22
	v_pk_mul_f32 v[8:9], v[8:9], v[18:19]
	s_waitcnt lgkmcnt(0)
	s_nop 0
	v_mfma_f32_16x16x32_bf16 v[6:9], v[10:13], v[14:17], v[6:9]
	s_nop 7
	v_cvt_pk_bf16_f32 v6, v6, v7
	v_cvt_pk_bf16_f32 v7, v8, v9
	ds_write_b64 v28, v[6:7]
	s_waitcnt lgkmcnt(0)
	ds_read_b128 v[6:9], v33 offset:2048
	ds_read_b128 v[10:13], v34
	s_waitcnt lgkmcnt(0)
	v_mfma_f32_16x16x32_bf16 v[6:9], v[6:9], v[10:13], 0
	s_nop 7
	v_cvt_pk_bf16_f32 v6, v6, v7
	v_cvt_pk_bf16_f32 v7, v8, v9
	ds_write_b64 v26, v[6:7] offset:64
	s_waitcnt lgkmcnt(0)
	ds_read_u16 v10, v20 offset:13328
	ds_read_u16 v22, v20 offset:13600
	ds_read_u16 v23, v20 offset:13872
	ds_read_u16 v14, v20 offset:13056
	ds_read_b128 v[6:9], v21 offset:192
	s_waitcnt lgkmcnt(4)
	v_lshlrev_b32_e32 v15, 16, v10
	ds_read_b128 v[10:13], v36 offset:6912
	s_waitcnt lgkmcnt(3)
	v_lshlrev_b32_e32 v23, 16, v23
	s_waitcnt lgkmcnt(2)
	v_lshlrev_b32_e32 v14, 16, v14
	s_waitcnt lgkmcnt(1)
	v_pk_mul_f32 v[6:7], v[6:7], v[14:15]
	ds_read_b128 v[14:17], v24
	ds_read_b128 v[18:21], v36 offset:6976
	v_lshlrev_b32_e32 v22, 16, v22
	v_pk_mul_f32 v[8:9], v[8:9], v[22:23]
	ds_read_b128 v[22:25], v24 offset:64
	s_waitcnt lgkmcnt(2)
	v_mfma_f32_16x16x32_bf16 v[6:9], v[10:13], v[14:17], v[6:9]
	s_waitcnt lgkmcnt(0)
	v_mfma_f32_16x16x32_bf16 v[6:9], v[18:21], v[22:25], v[6:9]
	s_nop 7
	v_cvt_pk_bf16_f32 v6, v6, v7
	v_cvt_pk_bf16_f32 v7, v8, v9
	ds_write_b64 v28, v[6:7]
	s_waitcnt lgkmcnt(0)
	ds_read_b128 v[6:9], v33 offset:3072
	ds_read_b128 v[10:13], v34
	s_waitcnt lgkmcnt(0)
	v_mfma_f32_16x16x32_bf16 v[6:9], v[6:9], v[10:13], 0
	s_nop 7
	v_cvt_pk_bf16_f32 v6, v6, v7
	v_cvt_pk_bf16_f32 v7, v8, v9
	ds_write_b64 v26, v[6:7] offset:96
	s_waitcnt lgkmcnt(0)
	s_waitcnt lgkmcnt(0)
	s_barrier
	s_nop 0
	v_and_b32_e32 v100, 15, v47
	v_lshrrev_b32_e32 v7, 1, v47
	v_lshl_or_b32 v18, s0, 4, v100
	v_and_b32_e32 v50, 24, v7
	v_mul_u32_u24_e32 v6, 0x90, v18
	v_lshlrev_b32_e32 v10, 1, v50
	v_add3_u32 v19, s5, v6, v10
	v_readlane_b32 s5, v254, 58
	v_add_u32_e32 v46, s77, v10
	v_bfe_u32 v52, v47, 4, 2
	v_add_u32_e32 v51, s5, v10
	s_lshl_b32 s5, s90, 6
	v_or_b32_e32 v6, s5, v100
	v_mul_lo_u32 v11, v6, s6
	v_add_u32_e32 v22, v51, v11
	ds_read_b128 v[6:9], v22
	v_add_u32_e32 v26, v46, v11
	ds_read_b128 v[10:13], v19
	ds_read_b128 v[14:17], v26
	v_mul_u32_u24_e32 v27, 0x110, v18
	ds_read_b128 v[18:21], v19 offset:64
	ds_read_b128 v[22:25], v22 offset:64
	s_waitcnt lgkmcnt(3)
	v_mfma_f32_16x16x32_bf16 v[6:9], v[6:9], v[10:13], 0
	v_lshlrev_b32_e32 v126, 3, v52
	v_add3_u32 v54, 0, v27, v126
	ds_read_b128 v[26:29], v26 offset:64
	v_and_b32_e32 v30, 63, v47
	s_waitcnt lgkmcnt(1)
	v_mfma_f32_16x16x32_bf16 v[6:9], v[22:25], v[18:21], v[6:9]
	v_lshl_add_u32 v22, s90, 7, v54
	v_lshlrev_b32_e32 v101, 3, v30
	ds_read_b64 v[30:31], v22 offset:52224
	v_lshl_or_b32 v22, vcc_lo, 4, v100
	v_mfma_f32_16x16x32_bf16 v[14:17], v[14:17], v[10:13], 0
	v_mul_lo_u32 v32, v22, s6
	v_add_u32_e32 v33, v51, v32
	ds_read_b128 v[22:25], v33
	v_add_u32_e32 v42, v46, v32
	s_waitcnt lgkmcnt(2)
	v_mfma_f32_16x16x32_bf16 v[14:17], v[26:29], v[18:21], v[14:17]
	ds_read_b128 v[26:29], v42
	s_waitcnt lgkmcnt(2)
	v_lshlrev_b32_e32 v48, 16, v30
	v_and_b32_e32 v38, 0xffff0000, v30
	v_lshlrev_b32_e32 v39, 16, v31
	v_and_b32_e32 v40, 0xffff0000, v31
	ds_read_b128 v[30:33], v33 offset:64
	ds_read_b128 v[42:45], v42 offset:64
	s_waitcnt lgkmcnt(3)
	v_mfma_f32_16x16x32_bf16 v[34:37], v[22:25], v[10:13], 0
	v_lshl_add_u32 v24, vcc_lo, 5, v54
	v_sub_f32_e32 v23, v40, v9
	v_sub_f32_e32 v49, v39, v8
	v_sub_f32_e32 v7, v38, v7
	s_waitcnt lgkmcnt(2)
	v_mfma_f32_16x16x32_bf16 v[38:41], v[26:29], v[10:13], 0
	ds_read_b64 v[24:25], v24 offset:52224
	v_sub_f32_e32 v6, v48, v6
	v_cvt_pk_bf16_f32 v22, v6, v7
	s_waitcnt lgkmcnt(2)
	v_mfma_f32_16x16x32_bf16 v[6:9], v[30:33], v[18:21], v[34:37]
	v_cvt_pk_bf16_f32 v26, v14, v15
	v_cvt_pk_bf16_f32 v27, v16, v17
	s_waitcnt lgkmcnt(0)
	v_lshlrev_b32_e32 v28, 16, v24
	v_mfma_f32_16x16x32_bf16 v[14:17], v[42:45], v[18:21], v[38:41]
	v_and_b32_e32 v24, 0xffff0000, v24
	s_nop 1
	v_sub_f32_e32 v7, v24, v7
	v_sub_f32_e32 v6, v28, v6
	s_or_b32 vcc_lo, s91, 2
	v_cvt_pk_bf16_f32 v24, v6, v7
	v_lshl_or_b32 v6, vcc_lo, 4, v100
	v_lshlrev_b32_e32 v29, 16, v25
	v_and_b32_e32 v25, 0xffff0000, v25
	v_cvt_pk_bf16_f32 v28, v14, v15
	v_mul_lo_u32 v14, v6, s6
	v_sub_f32_e32 v9, v25, v9
	v_sub_f32_e32 v8, v29, v8
	v_add_u32_e32 v30, v51, v14
	v_cvt_pk_bf16_f32 v25, v8, v9
	ds_read_b128 v[6:9], v30
	ds_read_b128 v[30:33], v30 offset:64
	v_add_u32_e32 v34, v46, v14
	s_waitcnt lgkmcnt(1)
	v_mfma_f32_16x16x32_bf16 v[6:9], v[6:9], v[10:13], 0
	v_cvt_pk_bf16_f32 v29, v16, v17
	ds_read_b128 v[14:17], v34
	s_lshl_b32 s90, s90, 10
	s_lshl_b32 s0, s0, 11
	s_add_i32 s0, s0, s90
	v_or_b32_e32 v38, s0, v101
	v_ashrrev_i32_e32 v39, 31, v38
	s_waitcnt lgkmcnt(1)
	v_mfma_f32_16x16x32_bf16 v[6:9], v[30:33], v[18:21], v[6:9]
	v_lshl_add_u32 v30, vcc_lo, 5, v54
	v_cvt_pk_bf16_f32 v23, v49, v23
	v_lshl_add_u64 v[48:49], v[38:39], 1, s[88:89]
	ds_read_b64 v[38:39], v30 offset:52224
	ds_read_b128 v[34:37], v34 offset:64
	s_or_b32 s0, s91, 3
	v_lshl_or_b32 v30, s0, 4, v100
	v_mul_lo_u32 v40, v30, s6
	v_add_u32_e32 v41, v51, v40
	ds_read_b128 v[30:33], v41
	s_waitcnt lgkmcnt(3)
	v_mfma_f32_16x16x32_bf16 v[14:17], v[14:17], v[10:13], 0
	v_add_u32_e32 v127, v46, v40
	s_waitcnt lgkmcnt(2)
	v_and_b32_e32 v128, 0xffff0000, v38
	v_lshlrev_b32_e32 v129, 16, v39
	s_waitcnt lgkmcnt(1)
	v_mfma_f32_16x16x32_bf16 v[14:17], v[34:37], v[18:21], v[14:17]
	ds_read_b128 v[34:37], v127
	v_and_b32_e32 v130, 0xffff0000, v39
	v_lshlrev_b32_e32 v55, 16, v38
	ds_read_b128 v[38:41], v41 offset:64
	s_waitcnt lgkmcnt(2)
	v_mfma_f32_16x16x32_bf16 v[42:45], v[30:33], v[10:13], 0
	v_sub_f32_e32 v31, v130, v9
	v_sub_f32_e32 v32, v129, v8
	v_sub_f32_e32 v7, v128, v7
	ds_read_b128 v[128:131], v127 offset:64
	s_waitcnt lgkmcnt(2)
	v_mfma_f32_16x16x32_bf16 v[8:11], v[34:37], v[10:13], 0
	v_sub_f32_e32 v6, v55, v6
	v_cvt_pk_bf16_f32 v30, v6, v7
	v_lshl_add_u32 v6, s0, 5, v54
	ds_read_b64 v[12:13], v6 offset:52224
	s_waitcnt lgkmcnt(2)
	v_mfma_f32_16x16x32_bf16 v[36:39], v[38:41], v[18:21], v[42:45]
	v_lshl_or_b32 v127, s1, 4, v100
	v_cvt_pk_bf16_f32 v31, v32, v31
	v_and_b32_e32 v53, 16, v47
	s_waitcnt lgkmcnt(1)
	v_mfma_f32_16x16x32_bf16 v[6:9], v[128:131], v[18:21], v[8:11]
	v_mad_u32_u24 v129, v100, s6, v51
	v_cvt_pk_bf16_f32 v34, v14, v15
	v_cvt_pk_bf16_f32 v35, v16, v17
	s_waitcnt lgkmcnt(0)
	v_lshlrev_b32_e32 v10, 16, v12
	v_and_b32_e32 v11, 0xffff0000, v12
	v_lshlrev_b32_e32 v12, 16, v13
	v_and_b32_e32 v13, 0xffff0000, v13
	v_sub_f32_e32 v13, v13, v39
	v_sub_f32_e32 v12, v12, v38
	v_sub_f32_e32 v10, v10, v36
	v_cvt_pk_bf16_f32 v36, v6, v7
	v_mov_b32_e32 v6, s97
	v_cvt_pk_bf16_f32 v33, v12, v13
	ds_read_b32 v12, v6
	ds_read_b128 v[38:41], v129
	v_sub_f32_e32 v11, v11, v37
	v_cvt_pk_bf16_f32 v32, v10, v11
	v_mad_u64_u32 v[10:11], s[90:91], v127, s6, v[46:47]
	s_waitcnt lgkmcnt(1)
	v_mul_f32_e32 v11, 0x3fb8aa3b, v12
	v_exp_f32_e32 v128, v11
	v_lshrrev_b32_e32 v11, 2, v47
	v_and_or_b32 v11, v11, 3, v50
	v_lshlrev_b32_e32 v12, 3, v47
	v_mul_u32_u24_e32 v11, 0x110, v11
	v_and_b32_e32 v12, 24, v12
	v_add3_u32 v130, 0, v11, v12
	v_lshl_add_u32 v11, s1, 5, v130
	v_cvt_pk_bf16_f32 v37, v8, v9
	ds_read_b128 v[6:9], v10
	ds_read_b64_tr_b16 v[18:19], v11 offset:34816
	ds_read_b128 v[42:45], v129 offset:64
	ds_read_b64_tr_b16 v[20:21], v11 offset:35904
	ds_read_b64_tr_b16 v[14:15], v11 offset:43520
	ds_read_b64_tr_b16 v[16:17], v11 offset:44608
	ds_read_b128 v[10:13], v10 offset:64
	ds_read_b64_tr_b16 v[46:47], v130 offset:44768
	ds_read_b64_tr_b16 v[50:51], v130 offset:44800
	ds_read_b64_tr_b16 v[54:55], v130 offset:44832
	s_waitcnt lgkmcnt(6)
	v_mfma_f32_16x16x32_bf16 v[38:41], v[38:41], v[18:21], 0
	v_lshlrev_b32_e32 v156, 2, v52
	v_cmp_eq_u32_e32 vcc, 0, v53
	v_permlane16_swap_b32_e32 v22, v24
	s_waitcnt lgkmcnt(4)
	v_mfma_f32_16x16x32_bf16 v[38:41], v[42:45], v[14:17], v[38:41]
	v_add_u32_e32 v42, 12, v156
	v_cndmask_b32_e32 v42, v42, v156, vcc
	v_or_b32_e32 v43, s5, v42
	v_ashrrev_i32_e32 v44, 5, v43
	v_lshlrev_b32_e32 v42, 1, v42
	v_add_lshl_u32 v43, v44, s19, 6
	v_and_b32_e32 v45, 48, v42
	v_or3_b32 v42, v43, v45, v100
	v_lshlrev_b32_e32 v42, 3, v42
	v_ashrrev_i32_e32 v43, 31, v42
	v_permlane16_swap_b32_e32 v23, v25
	v_lshl_add_u64 v[42:43], v[42:43], 1, s[68:69]
	ds_read_b64_tr_b16 v[132:133], v130 offset:34816
	ds_read_b64_tr_b16 v[134:135], v130 offset:35904
	ds_read_b128 v[136:139], v129 offset:2304
	ds_read_b64_tr_b16 v[140:141], v130 offset:43520
	ds_read_b64_tr_b16 v[142:143], v130 offset:44608
	global_store_dwordx4 v[42:43], v[22:25], off nt
	global_store_dwordx4 v[48:49], v[26:29], off nt
	v_permlane16_swap_b32_e32 v30, v32
	v_or_b32_e32 v22, 1, v44
	v_add_lshl_u32 v22, v22, s19, 6
	v_or3_b32 v22, v22, v45, v100
	v_lshlrev_b32_e32 v22, 3, v22
	v_ashrrev_i32_e32 v23, 31, v22
	v_permlane16_swap_b32_e32 v31, v33
	v_lshl_add_u64 v[22:23], v[22:23], 1, s[68:69]
	global_store_dwordx4 v[22:23], v[30:33], off nt
	global_store_dwordx4 v[48:49], v[34:37], off offset:1024 nt
	v_or_b32_e32 v23, 1, v156
	v_cmp_eq_u32_e64 s[68:69], v156, v127
	v_or_b32_e32 v24, 2, v156
	v_or_b32_e32 v131, 17, v156
	v_cndmask_b32_e64 v22, 0, v128, s[68:69]
	v_cmp_eq_u32_e64 s[68:69], v23, v127
	s_add_u32 s88, s78, s86
	s_addc_u32 s89, s79, s87
	v_cndmask_b32_e64 v23, 0, v128, s[68:69]
	v_pk_add_f32 v[42:43], v[22:23], v[38:39] neg_lo:[0,1] neg_hi:[0,1]
	v_or_b32_e32 v22, 3, v156
	v_cmp_eq_u32_e64 s[68:69], v22, v127
	s_add_u32 s86, s3, s86
	s_addc_u32 s87, s2, s87
	v_cndmask_b32_e64 v23, 0, v128, s[68:69]
	v_cmp_eq_u32_e64 s[68:69], v24, v127
	s_lshl_b32 s5, s1, 8
	s_lshl_b32 s0, s1, 2
	v_cndmask_b32_e64 v22, 0, v128, s[68:69]
	v_pk_add_f32 v[144:145], v[22:23], v[40:41] neg_lo:[0,1] neg_hi:[0,1]
	s_waitcnt lgkmcnt(3)
	v_mfma_f32_16x16x32_bf16 v[38:41], v[132:135], v[6:9], 0
	ds_read_b64_tr_b16 v[22:23], v130 offset:34976
	ds_read_b64_tr_b16 v[26:27], v130 offset:35008
	ds_read_b64_tr_b16 v[30:31], v130 offset:35040
	ds_read_b128 v[34:37], v129 offset:16192
	ds_read_b64_tr_b16 v[24:25], v130 offset:36064
	ds_read_b64_tr_b16 v[28:29], v130 offset:36096
	ds_read_b64_tr_b16 v[32:33], v130 offset:36128
	ds_read_b64_tr_b16 v[44:45], v130 offset:43680
	ds_read_b64_tr_b16 v[48:49], v130 offset:43712
	ds_read_b64_tr_b16 v[52:53], v130 offset:43744
	ds_read_b128 v[132:135], v129 offset:2368
	s_waitcnt lgkmcnt(11)
	v_mfma_f32_16x16x32_bf16 v[38:41], v[140:143], v[10:13], v[38:41]
	v_cvt_pk_bf16_f32 v140, v42, v43
	v_or_b32_e32 v142, 16, v156
	v_cmp_eq_u32_e64 s[68:69], v131, v127
	v_cvt_pk_bf16_f32 v141, v144, v145
	v_or_b32_e32 v131, 18, v156
	s_nop 2
	v_cvt_pk_bf16_f32 v38, v38, v39
	v_cvt_pk_bf16_f32 v39, v40, v41
	v_mfma_f32_16x16x32_bf16 v[40:43], v[136:139], v[18:21], 0
	v_cndmask_b32_e64 v143, 0, v128, s[68:69]
	v_cmp_eq_u32_e64 s[68:69], v142, v127
	ds_read_b64_tr_b16 v[136:137], v130 offset:34848
	ds_read_b64_tr_b16 v[138:139], v130 offset:35936
	ds_read_b128 v[144:147], v129 offset:4608
	s_waitcnt lgkmcnt(3)
	v_mfma_f32_16x16x32_bf16 v[40:43], v[132:135], v[14:17], v[40:43]
	v_cndmask_b32_e64 v142, 0, v128, s[68:69]
	ds_read_b64_tr_b16 v[132:133], v130 offset:43552
	ds_read_b64_tr_b16 v[134:135], v130 offset:44640
	ds_read_b64_tr_b16 v[150:151], v130 offset:35968
	ds_read_b64_tr_b16 v[154:155], v130 offset:36000
	ds_read_b64_tr_b16 v[160:161], v130 offset:36032
	ds_read_b64_tr_b16 v[148:149], v130 offset:34880
	ds_read_b64_tr_b16 v[152:153], v130 offset:34912
	ds_read_b64_tr_b16 v[158:159], v130 offset:34944
	v_pk_add_f32 v[142:143], v[142:143], v[40:41] neg_lo:[0,1] neg_hi:[0,1]
	v_or_b32_e32 v40, 19, v156
	v_cmp_eq_u32_e64 s[68:69], v40, v127
	v_cvt_pk_bf16_f32 v142, v142, v143
	s_nop 1
	v_permlane16_swap_b32_e32 v140, v142
	v_cndmask_b32_e64 v41, 0, v128, s[68:69]
	v_cmp_eq_u32_e64 s[68:69], v131, v127
	v_mfma_f32_16x16x32_bf16 v[22:25], v[22:25], v[6:9], 0
	s_nop 0
	v_cndmask_b32_e64 v40, 0, v128, s[68:69]
	v_pk_add_f32 v[170:171], v[40:41], v[42:43] neg_lo:[0,1] neg_hi:[0,1]
	s_waitcnt lgkmcnt(9)
	v_mfma_f32_16x16x32_bf16 v[40:43], v[136:139], v[6:9], 0
	v_cvt_pk_bf16_f32 v143, v170, v171
	ds_read_b64_tr_b16 v[136:137], v130 offset:43584
	ds_read_b64_tr_b16 v[162:163], v130 offset:43616
	ds_read_b64_tr_b16 v[166:167], v130 offset:43648
	ds_read_b64_tr_b16 v[138:139], v130 offset:44672
	ds_read_b64_tr_b16 v[164:165], v130 offset:44704
	ds_read_b64_tr_b16 v[168:169], v130 offset:44736
	v_permlane16_swap_b32_e32 v141, v143
	s_waitcnt lgkmcnt(12)
	v_mfma_f32_16x16x32_bf16 v[40:43], v[132:135], v[10:13], v[40:43]
	ds_read_b128 v[130:133], v129 offset:4672
	v_or_b32_e32 v134, 32, v156
	v_mfma_f32_16x16x32_bf16 v[22:25], v[44:47], v[10:13], v[22:25]
	v_mfma_f32_16x16x32_bf16 v[26:29], v[26:29], v[6:9], 0
	s_nop 3
	v_cvt_pk_bf16_f32 v40, v40, v41
	v_cvt_pk_bf16_f32 v41, v42, v43
	v_add_u32_e32 v42, 24, v126
	v_cndmask_b32_e32 v42, v42, v126, vcc
	v_and_b32_e32 v126, 48, v42
	v_or3_b32 v42, v126, s5, v100
	v_lshlrev_b32_e32 v42, 3, v42
	v_ashrrev_i32_e32 v43, 31, v42
	v_lshl_add_u64 v[42:43], v[42:43], 1, s[88:89]
	global_store_dwordx4 v[42:43], v[140:143], off nt
	v_lshl_or_b32 v42, s1, 11, v101
	v_ashrrev_i32_e32 v43, 31, v42
	v_lshl_add_u64 v[42:43], v[42:43], 1, s[86:87]
	global_store_dwordx4 v[42:43], v[38:41], off nt
	ds_read_b128 v[38:41], v129 offset:6912
	v_mfma_f32_16x16x32_bf16 v[140:143], v[144:147], v[18:21], 0
	ds_read_b128 v[144:147], v129 offset:6976
	v_or_b32_e32 v42, 33, v156
	v_cmp_eq_u32_e32 vcc, v42, v127
	s_waitcnt lgkmcnt(2)
	v_mfma_f32_16x16x32_bf16 v[130:133], v[130:133], v[14:17], v[140:143]
	s_or_b32 s1, s0, 1
	v_cndmask_b32_e32 v43, 0, v128, vcc
	v_cmp_eq_u32_e32 vcc, v134, v127
	v_mfma_f32_16x16x32_bf16 v[140:143], v[148:151], v[6:9], 0
	v_or_b32_e32 v134, 34, v156
	v_cndmask_b32_e32 v42, 0, v128, vcc
	s_nop 1
	v_pk_add_f32 v[42:43], v[42:43], v[130:131] neg_lo:[0,1] neg_hi:[0,1]
	v_or_b32_e32 v130, 35, v156
	s_waitcnt lgkmcnt(1)
	v_mfma_f32_16x16x32_bf16 v[38:41], v[38:41], v[18:21], 0
	v_cmp_eq_u32_e32 vcc, v130, v127
	s_lshl_b32 s5, s1, 6
	s_nop 0
	v_cndmask_b32_e32 v131, 0, v128, vcc
	v_cmp_eq_u32_e32 vcc, v134, v127
	v_mfma_f32_16x16x32_bf16 v[134:137], v[136:139], v[10:13], v[140:143]
	s_nop 0
	v_cndmask_b32_e32 v130, 0, v128, vcc
	v_pk_add_f32 v[132:133], v[130:131], v[132:133] neg_lo:[0,1] neg_hi:[0,1]
	v_cvt_pk_bf16_f32 v130, v42, v43
	ds_read_b128 v[138:141], v129 offset:9216
	s_waitcnt lgkmcnt(1)
	v_mfma_f32_16x16x32_bf16 v[38:41], v[144:147], v[14:17], v[38:41]
	v_or_b32_e32 v42, 49, v156
	v_cvt_pk_bf16_f32 v131, v132, v133
	v_or_b32_e32 v132, 48, v156
	v_cmp_eq_u32_e32 vcc, v42, v127
	v_mfma_f32_16x16x32_bf16 v[142:145], v[152:155], v[6:9], 0
	v_cvt_pk_bf16_f32 v134, v134, v135
	v_cndmask_b32_e32 v43, 0, v128, vcc
	v_cmp_eq_u32_e32 vcc, v132, v127
	v_or_b32_e32 v132, 50, v156
	v_cvt_pk_bf16_f32 v135, v136, v137
	v_cndmask_b32_e32 v42, 0, v128, vcc
	v_pk_add_f32 v[42:43], v[42:43], v[38:39] neg_lo:[0,1] neg_hi:[0,1]
	v_or_b32_e32 v38, 51, v156
	v_cmp_eq_u32_e32 vcc, v38, v127
	v_mfma_f32_16x16x32_bf16 v[26:29], v[48:51], v[10:13], v[26:29]
	s_nop 0
	v_cndmask_b32_e32 v39, 0, v128, vcc
	v_cmp_eq_u32_e32 vcc, v132, v127
	v_cvt_pk_bf16_f32 v132, v42, v43
	s_nop 1
	v_permlane16_swap_b32_e32 v130, v132
	v_cndmask_b32_e32 v38, 0, v128, vcc
	v_pk_add_f32 v[136:137], v[38:39], v[40:41] neg_lo:[0,1] neg_hi:[0,1]
	v_mfma_f32_16x16x32_bf16 v[38:41], v[162:165], v[10:13], v[142:145]
	v_cvt_pk_bf16_f32 v133, v136, v137
	s_nop 1
	v_permlane16_swap_b32_e32 v131, v133
	v_cvt_pk_bf16_f32 v26, v26, v27
	v_cvt_pk_bf16_f32 v27, v28, v29
	s_nop 1
	v_cvt_pk_bf16_f32 v136, v38, v39
	v_or3_b32 v38, v126, s5, v100
	v_cvt_pk_bf16_f32 v137, v40, v41
	v_lshlrev_b32_e32 v42, 3, v38
	ds_read_b128 v[38:41], v129 offset:9280
	v_ashrrev_i32_e32 v43, 31, v42
	v_lshl_add_u64 v[42:43], v[42:43], 1, s[88:89]
	global_store_dwordx4 v[42:43], v[130:133], off nt
	v_lshl_or_b32 v42, s1, 9, v101
	v_ashrrev_i32_e32 v43, 31, v42
	s_waitcnt lgkmcnt(1)
	v_mfma_f32_16x16x32_bf16 v[130:133], v[138:141], v[18:21], 0
	v_lshl_add_u64 v[42:43], v[42:43], 1, s[86:87]
	global_store_dwordx4 v[42:43], v[134:137], off nt
	ds_read_b128 v[134:137], v129 offset:11520
	s_waitcnt lgkmcnt(1)
	v_mfma_f32_16x16x32_bf16 v[38:41], v[38:41], v[14:17], v[130:133]
	v_or_b32_e32 v42, 0x41, v156
	v_cmp_eq_u32_e32 vcc, v42, v127
	v_or_b32_e32 v138, 0x42, v156
	v_or_b32_e32 v130, 64, v156
	v_cndmask_b32_e32 v43, 0, v128, vcc
	v_cmp_eq_u32_e32 vcc, v130, v127
	v_mfma_f32_16x16x32_bf16 v[130:133], v[158:161], v[6:9], 0
	s_or_b32 s1, s0, 2
	v_cndmask_b32_e32 v42, 0, v128, vcc
	v_pk_add_f32 v[38:39], v[42:43], v[38:39] neg_lo:[0,1] neg_hi:[0,1]
	v_or_b32_e32 v42, 0x43, v156
	v_cmp_eq_u32_e32 vcc, v42, v127
	v_mfma_f32_16x16x32_bf16 v[130:133], v[166:169], v[10:13], v[130:133]
	v_cvt_pk_bf16_f32 v38, v38, v39
	v_cndmask_b32_e32 v43, 0, v128, vcc
	v_cmp_eq_u32_e32 vcc, v138, v127
	ds_read_b128 v[138:141], v129 offset:11584
	s_lshl_b32 s5, s1, 6
	v_cndmask_b32_e32 v42, 0, v128, vcc
	v_pk_add_f32 v[40:41], v[42:43], v[40:41] neg_lo:[0,1] neg_hi:[0,1]
	s_nop 0
	v_cvt_pk_bf16_f32 v130, v130, v131
	v_cvt_pk_bf16_f32 v39, v40, v41
	s_waitcnt lgkmcnt(1)
	v_mfma_f32_16x16x32_bf16 v[40:43], v[134:137], v[18:21], 0
	v_cvt_pk_bf16_f32 v131, v132, v133
	ds_read_b128 v[134:137], v129 offset:13824
	v_or_b32_e32 v132, 0x51, v156
	s_waitcnt lgkmcnt(1)
	v_mfma_f32_16x16x32_bf16 v[40:43], v[138:141], v[14:17], v[40:43]
	v_or_b32_e32 v138, 0x50, v156
	v_cmp_eq_u32_e32 vcc, v132, v127
	s_or_b32 s0, s0, 3
	v_mfma_f32_16x16x32_bf16 v[6:9], v[30:33], v[6:9], 0
	v_cndmask_b32_e32 v133, 0, v128, vcc
	v_cmp_eq_u32_e32 vcc, v138, v127
	v_or_b32_e32 v138, 0x52, v156
	v_mfma_f32_16x16x32_bf16 v[6:9], v[52:55], v[10:13], v[6:9]
	v_cndmask_b32_e32 v132, 0, v128, vcc
	v_pk_add_f32 v[40:41], v[132:133], v[40:41] neg_lo:[0,1] neg_hi:[0,1]
	v_or_b32_e32 v132, 0x53, v156
	v_cmp_eq_u32_e32 vcc, v132, v127
	v_cvt_pk_bf16_f32 v40, v40, v41
	s_nop 1
	v_permlane16_swap_b32_e32 v38, v40
	v_cndmask_b32_e32 v133, 0, v128, vcc
	v_cmp_eq_u32_e32 vcc, v138, v127
	v_cvt_pk_bf16_f32 v28, v6, v7
	v_cvt_pk_bf16_f32 v29, v8, v9
	v_cndmask_b32_e32 v132, 0, v128, vcc
	v_pk_add_f32 v[42:43], v[132:133], v[42:43] neg_lo:[0,1] neg_hi:[0,1]
	v_cvt_pk_bf16_f32 v132, v22, v23
	v_or3_b32 v22, v126, s5, v100
	v_cvt_pk_bf16_f32 v41, v42, v43
	v_lshlrev_b32_e32 v42, 3, v22
	v_ashrrev_i32_e32 v43, 31, v42
	v_permlane16_swap_b32_e32 v39, v41
	v_lshl_add_u64 v[42:43], v[42:43], 1, s[88:89]
	global_store_dwordx4 v[42:43], v[38:41], off nt
	v_lshl_or_b32 v42, s1, 9, v101
	v_cvt_pk_bf16_f32 v133, v24, v25
	ds_read_b128 v[22:25], v129 offset:13888
	v_ashrrev_i32_e32 v43, 31, v42
	v_lshl_add_u64 v[42:43], v[42:43], 1, s[86:87]
	global_store_dwordx4 v[42:43], v[130:133], off nt
	ds_read_b128 v[42:45], v129 offset:16128
	s_waitcnt lgkmcnt(2)
	v_mfma_f32_16x16x32_bf16 v[38:41], v[134:137], v[18:21], 0
	s_lshl_b32 s1, s0, 6
	v_or3_b32 v6, v126, s1, v100
	v_lshlrev_b32_e32 v6, 3, v6
	s_waitcnt lgkmcnt(1)
	v_mfma_f32_16x16x32_bf16 v[22:25], v[22:25], v[14:17], v[38:41]
	v_ashrrev_i32_e32 v7, 31, v6
	v_lshl_add_u64 v[6:7], v[6:7], 1, s[88:89]
	s_nop 0
	v_or_b32_e32 v38, 0x61, v156
	v_or_b32_e32 v40, 0x60, v156
	v_cmp_eq_u32_e32 vcc, v38, v127
	s_waitcnt lgkmcnt(0)
	v_mfma_f32_16x16x32_bf16 v[18:21], v[42:45], v[18:21], 0
	v_cndmask_b32_e32 v39, 0, v128, vcc
	v_cmp_eq_u32_e32 vcc, v40, v127
	v_or_b32_e32 v40, 0x62, v156
	v_mfma_f32_16x16x32_bf16 v[14:17], v[34:37], v[14:17], v[18:21]
	v_cndmask_b32_e32 v38, 0, v128, vcc
	v_pk_add_f32 v[22:23], v[38:39], v[22:23] neg_lo:[0,1] neg_hi:[0,1]
	v_or_b32_e32 v38, 0x63, v156
	v_cmp_eq_u32_e32 vcc, v38, v127
	v_or_b32_e32 v18, 0x71, v156
	v_or_b32_e32 v20, 0x70, v156
	v_cndmask_b32_e32 v39, 0, v128, vcc
	v_cmp_eq_u32_e32 vcc, v40, v127
	v_cvt_pk_bf16_f32 v22, v22, v23
	s_nop 0
	v_cndmask_b32_e32 v38, 0, v128, vcc
	v_cmp_eq_u32_e32 vcc, v18, v127
	v_pk_add_f32 v[24:25], v[38:39], v[24:25] neg_lo:[0,1] neg_hi:[0,1]
	s_nop 0
	v_cndmask_b32_e32 v19, 0, v128, vcc
	v_cmp_eq_u32_e32 vcc, v20, v127
	v_or_b32_e32 v20, 0x72, v156
	v_cvt_pk_bf16_f32 v23, v24, v25
	v_cndmask_b32_e32 v18, 0, v128, vcc
	v_pk_add_f32 v[14:15], v[18:19], v[14:15] neg_lo:[0,1] neg_hi:[0,1]
	v_or_b32_e32 v18, 0x73, v156
	v_cmp_eq_u32_e32 vcc, v18, v127
	v_cvt_pk_bf16_f32 v24, v14, v15
	s_nop 1
	v_permlane16_swap_b32_e32 v22, v24
	v_cndmask_b32_e32 v19, 0, v128, vcc
	v_cmp_eq_u32_e32 vcc, v20, v127
	s_nop 1
	v_cndmask_b32_e32 v18, 0, v128, vcc
	v_pk_add_f32 v[16:17], v[18:19], v[16:17] neg_lo:[0,1] neg_hi:[0,1]
	s_andn2_b64 vcc, exec, s[70:71]
	v_cvt_pk_bf16_f32 v25, v16, v17
	s_nop 1
	v_permlane16_swap_b32_e32 v23, v25
	global_store_dwordx4 v[6:7], v[22:25], off nt
	v_lshl_or_b32 v6, s0, 9, v101
	v_ashrrev_i32_e32 v7, 31, v6
	v_lshl_add_u64 v[6:7], v[6:7], 1, s[86:87]
	global_store_dwordx4 v[6:7], v[26:29], off nt
	s_waitcnt lgkmcnt(0)
	s_barrier
	s_mov_b64 s[86:87], 0
	s_cbranch_vccz .LBB0_630

.LBB0_754:
	s_cmp_eq_u32 s29, 2
	s_mov_b32 s2, 0x1b401000
	s_cselect_b32 s2, s2, 0x1bc01000
	s_cmp_lg_u32 s29, 1
	s_cselect_b32 s2, s2, 0x1ac01000
	s_and_b64 s[4:5], s[68:69], exec
	s_cselect_b32 s2, 0x1a401000, s2
	s_add_u32 s2, s12, s2
	s_addc_u32 s15, s13, 0
	s_lshl_b64 s[4:5], s[50:51], 1
	s_add_u32 s4, s2, s4
	s_addc_u32 s5, s15, s5
	s_lshl_b32 s2, s82, 9
	v_and_b32_e32 v86, 63, v91
	s_and_b32 s2, s2, 0x200
	v_lshl_or_b32 v88, v86, 3, s2
	v_and_b32_e32 v86, 16, v91
	v_lshl_or_b32 v87, s82, 5, v96
	v_add_u32_e32 v89, 12, v87
	v_cmp_eq_u32_e32 vcc, 0, v86
	s_movk_i32 s2, 0x70
	s_mov_b32 s42, s14
	v_cndmask_b32_e32 v86, v89, v87, vcc
	v_lshlrev_b32_e32 v86, 1, v86
	v_and_or_b32 v86, v86, s2, v90
	v_lshlrev_b32_e32 v89, 3, v86
	v_cndmask_b32_e64 v86, v88, v89, s[38:39]
	v_lshlrev_b32_e32 v190, 1, v86
	global_store_dwordx4 v190, v[70:73], s[4:5] nt
	v_lshl_add_u64 v[86:87], s[4:5], 0, v[190:191]
	s_nop 0
	v_or_b32_e32 v70, 0x400, v88
	v_or_b32_e32 v71, 0x400, v89
	v_cndmask_b32_e64 v70, v70, v71, s[38:39]
	v_lshlrev_b32_e32 v70, 1, v70
	global_store_dwordx4 v70, v[74:77], s[4:5] nt
	v_add_co_u32_e32 v70, vcc, 0x1000, v86
	s_nop 1
	v_addc_co_u32_e32 v71, vcc, 0, v87, vcc
	global_store_dwordx4 v[70:71], v[78:81], off nt
	v_or_b32_e32 v70, 0xc00, v88
	v_or_b32_e32 v71, 0xc00, v89
	v_cndmask_b32_e64 v70, v70, v71, s[38:39]
	v_lshlrev_b32_e32 v70, 1, v70
	global_store_dwordx4 v70, v[82:85], s[4:5] nt
	s_waitcnt lgkmcnt(0)
	s_barrier
	s_and_b64 vcc, exec, s[18:19]
	s_cbranch_vccnz .LBB0_896

.LBB0_759:
	s_or_b64 exec, exec, s[4:5]
	v_add_f32_e32 v78, v78, v79
	s_add_i32 s14, s42, s22
	s_cmpk_gt_i32 s14, 0x3ff
	v_pk_mul_f32 v[80:81], v[170:171], v[78:79] op_sel_hi:[1,0]
	v_pk_mul_f32 v[84:85], v[172:173], v[78:79] op_sel_hi:[1,0]
	s_cselect_b64 s[18:19], -1, 0
	s_cmpk_lt_i32 s14, 0x400
	v_cvt_pk_bf16_f32 v80, v80, v81
	v_cvt_pk_bf16_f32 v81, v84, v85
	v_pk_mul_f32 v[84:85], v[174:175], v[78:79] op_sel_hi:[1,0]
	v_pk_mul_f32 v[78:79], v[176:177], v[78:79] op_sel_hi:[1,0]
	s_cselect_b32 s15, s14, -1
	v_cvt_pk_bf16_f32 v84, v84, v85
	v_cvt_pk_bf16_f32 v85, v78, v79
	s_ashr_i32 s43, s42, 31
	v_lshrrev_b32_e32 v77, 5, v242
	v_lshrrev_b32_e32 v78, 1, v214
	s_mov_b32 s29, 0xfffffc
	s_lshl_b64 s[4:5], s[42:43], 13
	v_and_or_b32 v77, v77, s29, v78
	v_lshlrev_b32_e32 v78, 7, v214
	v_lshlrev_b32_e32 v79, 2, v212
	s_add_u32 s36, s0, s4
	v_and_b32_e32 v78, 0x80, v78
	v_lshlrev_b32_e32 v77, 8, v77
	v_and_b32_e32 v79, 60, v79
	s_addc_u32 s37, s1, s5
	v_or3_b32 v78, v77, v79, v78
	s_add_u32 s4, s3, s4
	v_ashrrev_i32_e32 v79, 31, v78
	s_addc_u32 s5, s23, s5
	v_lshlrev_b64 v[78:79], 1, v[78:79]
	v_cvt_pk_bf16_f32 v82, v122, v123
	v_cvt_pk_bf16_f32 v83, v124, v125
	v_lshl_add_u64 v[88:89], s[36:37], 0, v[78:79]
	v_lshl_add_u64 v[78:79], s[4:5], 0, v[78:79]
	v_cvt_pk_bf16_f32 v86, v118, v119
	v_cvt_pk_bf16_f32 v87, v120, v121
	global_store_dwordx2 v[88:89], v[80:81], off nt
	global_store_dwordx2 v[78:79], v[82:83], off nt
	global_store_dwordx2 v[88:89], v[84:85], off offset:128 nt
	global_store_dwordx2 v[78:79], v[86:87], off offset:128 nt
	s_waitcnt lgkmcnt(0)
	s_barrier
	s_cmp_gt_i32 s15, -1
	v_mov_b32_e32 v170, v235
	s_cselect_b64 s[36:37], -1, 0
	s_cmp_lt_i32 s15, 0
	s_cbranch_scc1 .LBB0_763
	v_mov_b32_e32 v6, v235
	s_lshl_b32 s4, s15, 3
	s_and_b32 s4, s4, 0x7fffffc0
	v_ashrrev_i32_e32 v7, 3, v6
	v_and_b32_e32 v77, 7, v6
	v_add_u32_e32 v18, s4, v7
	s_lshl_b32 s4, s15, 6
	s_and_b32 s4, s4, 0x1c0
	v_lshlrev_b32_e32 v6, 3, v77
	v_or_b32_e32 v7, s4, v6
	v_mov_b64_e32 v[8:9], s[12:13]
	v_mad_i64_i32 v[78:79], s[4:5], v18, s9, v[8:9]
	v_lshlrev_b32_e32 v190, 1, v7
	v_lshl_add_u64 v[82:83], v[78:79], 0, v[190:191]
	v_add_co_u32_e32 v8, vcc, 0xa403000, v82
	v_mov_b32_e32 v7, v191
	s_nop 0
	v_addc_co_u32_e32 v9, vcc, 0, v83, vcc
	v_lshl_add_u64 v[6:7], v[78:79], 0, v[6:7]
	v_mul_u32_u24_e32 v10, 12, v77
	v_add_co_u32_e32 v14, vcc, 0xa403000, v6
	v_lshlrev_b32_e32 v190, 1, v10
	s_nop 0
	v_addc_co_u32_e32 v15, vcc, 0, v7, vcc
	v_lshl_add_u64 v[80:81], v[78:79], 0, v[190:191]
	v_add_co_u32_e32 v10, vcc, 0xa403000, v80
	s_mov_b64 s[4:5], 0xa4034a0
	s_nop 0
	v_addc_co_u32_e32 v11, vcc, 0, v81, vcc
	global_load_dwordx4 v[6:9], v[8:9], off offset:32
	s_nop 0
	global_load_dwordx2 v[158:159], v[14:15], off offset:1056
	v_lshl_add_u64 v[16:17], v[80:81], 0, s[4:5]
	global_load_dwordx4 v[10:13], v[10:11], off offset:1184
	s_nop 0
	global_load_dwordx2 v[162:163], v[14:15], off offset:1120
	global_load_dwordx2 v[160:161], v[16:17], off offset:16
	v_mov_b32_e32 v190, v191
	v_cmp_lt_i32_e32 vcc, 0, v18
	v_mov_b32_e32 v14, v191
	v_mov_b32_e32 v15, v191
	v_mov_b32_e32 v16, v191
	v_mov_b32_e32 v17, v191
	v_mov_b64_e32 v[164:165], v[190:191]
	v_mov_b64_e32 v[166:167], v[190:191]
	v_mov_b64_e32 v[18:19], v[190:191]
	v_mov_b64_e32 v[20:21], v[190:191]
	v_mov_b64_e32 v[168:169], v[190:191]
	s_and_saveexec_b64 s[38:39], vcc
	s_cbranch_execz .LBB0_762
	v_lshlrev_b32_e32 v16, 2, v77
	v_add_co_u32_e32 v14, vcc, 0xa3ff000, v82
	v_lshlrev_b32_e32 v190, 1, v16
	s_nop 0
	v_addc_co_u32_e32 v15, vcc, 0, v83, vcc
	v_lshl_add_u64 v[16:17], v[78:79], 0, v[190:191]
	v_add_co_u32_e32 v78, vcc, 0xa3ff000, v16
	s_mov_b64 s[4:5], 0xa3ffea0
	s_nop 0
	v_addc_co_u32_e32 v79, vcc, 0, v17, vcc
	v_add_co_u32_e32 v18, vcc, 0xa3ff000, v80
	global_load_dwordx4 v[14:17], v[14:15], off offset:2592
	s_nop 0
	global_load_dwordx2 v[164:165], v[78:79], off offset:3616
	v_addc_co_u32_e32 v19, vcc, 0, v81, vcc
	v_lshl_add_u64 v[82:83], v[80:81], 0, s[4:5]
	global_load_dwordx4 v[18:21], v[18:19], off offset:3744
	s_nop 0
	global_load_dwordx2 v[166:167], v[78:79], off offset:3680
	global_load_dwordx2 v[168:169], v[82:83], off offset:16

.LBB0_898:
	s_or_b64 exec, exec, s[4:5]
	s_add_i32 s4, s40, s41
	s_ashr_i32 s89, s88, 31
	s_lshl_b64 s[62:63], s[88:89], 3
	s_ashr_i32 s5, s4, 31
	s_add_u32 s62, s62, s4
	v_cvt_pk_bf16_f32 v8, v17, v16
	v_cvt_pk_bf16_f32 v9, v7, v6
	s_addc_u32 s63, s63, s5
	s_lshl_b64 s[4:5], s[4:5], 2
	ds_write_b64 v10, v[8:9] offset:27648
	s_add_u32 s4, s21, s4
	s_waitcnt lgkmcnt(0)
	s_barrier
	s_addc_u32 s5, s23, s5
	global_load_dword v22, v191, s[4:5]
	s_lshl_b64 s[4:5], s[62:63], 13
	s_add_u32 s84, s26, s4
	s_addc_u32 s85, s29, s5
	s_and_b32 s4, s37, 0xffffff80
	s_add_i32 s5, s4, 0
	v_lshl_add_u32 v6, v105, 1, s5
	s_lshl_b32 s37, s91, 5
	s_mulk_i32 s40, 0x2400
	v_add3_u32 v20, v6, s37, v107
	v_add3_u32 v26, v106, s40, v108
	s_waitcnt lgkmcnt(1)
	ds_read_b64_tr_b16 v[10:11], v20 offset:34816
	ds_read_b64_tr_b16 v[12:13], v20 offset:36928
	ds_read_b128 v[14:17], v26
	v_add_u32_e32 v23, s5, v102
	s_lshl_b32 s5, s90, 9
	s_and_b32 s5, s5, 0x200
	v_or_b32_e32 v27, s5, v67
	s_lshl_b32 s5, s60, 5
	ds_read_b64_tr_b16 v[18:19], v20 offset:51712
	ds_read_b64_tr_b16 v[20:21], v20 offset:53824
	ds_read_b128 v[28:31], v26 offset:64
	v_add3_u32 v38, v6, s5, v107
	v_add_u32_e32 v39, v23, v109
	s_waitcnt lgkmcnt(3)
	v_mfma_f32_16x16x32_bf16 v[6:9], v[10:13], v[14:17], 0
	v_add_u32_e32 v24, s37, v39
	ds_read_b64 v[24:25], v24 offset:34816
	v_lshlrev_b32_e32 v190, 1, v27
	s_waitcnt lgkmcnt(1)
	v_mfma_f32_16x16x32_bf16 v[6:9], v[18:21], v[28:31], v[6:9]
	v_add_u32_e32 v27, v23, v110
	v_add_u32_e32 v40, s37, v27
	s_waitcnt lgkmcnt(0)
	v_lshlrev_b32_e32 v32, 16, v24
	v_and_b32_e32 v33, 0xffff0000, v24
	v_lshlrev_b32_e32 v24, 16, v25
	v_and_b32_e32 v25, 0xffff0000, v25
	v_add_u32_e32 v27, s5, v27
	s_movk_i32 s40, 0x1000
	s_lshl_b64 s[82:83], s[62:63], 14
	s_add_u32 s82, s2, s82
	s_addc_u32 s83, s3, s83
	v_add3_u32 v60, v114, s4, v107
	s_movk_i32 s4, 0x2000
	s_add_i32 s36, s36, s22
	s_waitcnt vmcnt(0)
	v_pk_fma_f32 v[8:9], v[22:23], v[24:25], v[8:9] op_sel_hi:[0,1,1]
	v_pk_fma_f32 v[6:7], v[22:23], v[32:33], v[6:7] op_sel_hi:[0,1,1]
	v_cvt_pk_bf16_f32 v32, v6, v7
	v_cvt_pk_bf16_f32 v33, v8, v9
	ds_read_b64_tr_b16 v[6:7], v38 offset:34816
	ds_read_b64_tr_b16 v[8:9], v38 offset:36928
	s_waitcnt lgkmcnt(0)
	v_mfma_f32_16x16x32_bf16 v[34:37], v[6:9], v[14:17], 0
	ds_read_b64_tr_b16 v[14:15], v38 offset:51712
	ds_read_b64_tr_b16 v[16:17], v38 offset:53824
	v_add_u32_e32 v24, s5, v39
	ds_read_b64 v[24:25], v24 offset:34816
	s_waitcnt lgkmcnt(1)
	v_mfma_f32_16x16x32_bf16 v[28:31], v[14:17], v[28:31], v[34:37]
	ds_read_b64 v[40:41], v40 offset:34816
	s_nop 1
	ds_read_b128 v[36:39], v26 offset:2368
	s_waitcnt lgkmcnt(2)
	v_lshlrev_b32_e32 v34, 16, v24
	v_and_b32_e32 v35, 0xffff0000, v24
	v_lshlrev_b32_e32 v24, 16, v25
	v_and_b32_e32 v25, 0xffff0000, v25
	v_pk_fma_f32 v[28:29], v[22:23], v[34:35], v[28:29] op_sel_hi:[0,1,1]
	v_pk_fma_f32 v[24:25], v[22:23], v[24:25], v[30:31] op_sel_hi:[0,1,1]
	v_cvt_pk_bf16_f32 v34, v28, v29
	ds_read_b128 v[28:31], v26 offset:2304
	v_cvt_pk_bf16_f32 v35, v24, v25
	global_store_dwordx4 v190, v[32:35], s[84:85] nt
	s_waitcnt lgkmcnt(2)
	v_lshlrev_b32_e32 v42, 16, v40
	v_and_b32_e32 v43, 0xffff0000, v40
	s_waitcnt lgkmcnt(0)
	v_mfma_f32_16x16x32_bf16 v[32:35], v[10:13], v[28:31], 0
	v_lshlrev_b32_e32 v40, 16, v41
	v_and_b32_e32 v41, 0xffff0000, v41
	v_lshl_add_u64 v[24:25], s[84:85], 0, v[190:191]
	v_mfma_f32_16x16x32_bf16 v[32:35], v[18:21], v[36:39], v[32:35]
	v_mfma_f32_16x16x32_bf16 v[28:31], v[6:9], v[28:31], 0
	v_mfma_f32_16x16x32_bf16 v[28:31], v[14:17], v[36:39], v[28:31]
	s_nop 5
	v_fma_f32 v34, v22, v40, v34
	v_fma_f32 v35, v22, v41, v35
	v_pk_fma_f32 v[32:33], v[22:23], v[42:43], v[32:33] op_sel_hi:[0,1,1]
	v_cvt_pk_bf16_f32 v32, v32, v33
	v_cvt_pk_bf16_f32 v33, v34, v35
	ds_read_b64 v[34:35], v27 offset:34816
	v_add_u32_e32 v27, v23, v111
	v_add_u32_e32 v40, s37, v27
	ds_read_b64 v[40:41], v40 offset:34816
	v_add_u32_e32 v27, s5, v27
	s_waitcnt lgkmcnt(1)
	v_lshlrev_b32_e32 v36, 16, v34
	v_and_b32_e32 v37, 0xffff0000, v34
	v_lshlrev_b32_e32 v34, 16, v35
	v_and_b32_e32 v35, 0xffff0000, v35
	v_pk_fma_f32 v[30:31], v[22:23], v[34:35], v[30:31] op_sel_hi:[0,1,1]
	v_pk_fma_f32 v[28:29], v[22:23], v[36:37], v[28:29] op_sel_hi:[0,1,1]
	v_cvt_pk_bf16_f32 v34, v28, v29
	v_cvt_pk_bf16_f32 v35, v30, v31
	ds_read_b128 v[28:31], v26 offset:4608
	ds_read_b128 v[36:39], v26 offset:4672
	global_store_dwordx4 v190, v[32:35], s[84:85] offset:2048 nt
	s_waitcnt lgkmcnt(2)
	v_lshlrev_b32_e32 v42, 16, v40
	v_and_b32_e32 v43, 0xffff0000, v40
	s_waitcnt lgkmcnt(1)
	v_mfma_f32_16x16x32_bf16 v[32:35], v[10:13], v[28:31], 0
	v_lshlrev_b32_e32 v40, 16, v41
	v_and_b32_e32 v41, 0xffff0000, v41
	s_waitcnt lgkmcnt(0)
	v_mfma_f32_16x16x32_bf16 v[32:35], v[18:21], v[36:39], v[32:35]
	v_mfma_f32_16x16x32_bf16 v[28:31], v[6:9], v[28:31], 0
	v_mfma_f32_16x16x32_bf16 v[28:31], v[14:17], v[36:39], v[28:31]
	s_nop 5
	v_fma_f32 v34, v22, v40, v34
	v_fma_f32 v35, v22, v41, v35
	v_pk_fma_f32 v[32:33], v[22:23], v[42:43], v[32:33] op_sel_hi:[0,1,1]
	v_cvt_pk_bf16_f32 v32, v32, v33
	v_cvt_pk_bf16_f32 v33, v34, v35
	ds_read_b64 v[34:35], v27 offset:34816
	s_waitcnt lgkmcnt(0)
	v_lshlrev_b32_e32 v36, 16, v34
	v_and_b32_e32 v37, 0xffff0000, v34
	v_lshlrev_b32_e32 v34, 16, v35
	v_and_b32_e32 v35, 0xffff0000, v35
	v_pk_fma_f32 v[30:31], v[22:23], v[34:35], v[30:31] op_sel_hi:[0,1,1]
	v_pk_fma_f32 v[28:29], v[22:23], v[36:37], v[28:29] op_sel_hi:[0,1,1]
	v_cvt_pk_bf16_f32 v34, v28, v29
	v_cvt_pk_bf16_f32 v35, v30, v31
	ds_read_b128 v[28:31], v26 offset:6912
	v_add_co_u32_e32 v36, vcc, s40, v24
	s_waitcnt lgkmcnt(0)
	v_mfma_f32_16x16x32_bf16 v[10:13], v[10:13], v[28:31], 0
	v_addc_co_u32_e32 v37, vcc, 0, v25, vcc
	ds_read_b128 v[24:27], v26 offset:6976
	v_add_u32_e32 v23, v23, v112
	s_waitcnt lgkmcnt(0)
	v_mfma_f32_16x16x32_bf16 v[10:13], v[18:21], v[24:27], v[10:13]
	v_add_u32_e32 v18, s37, v23
	ds_read_b64 v[18:19], v18 offset:34816
	global_store_dwordx4 v[36:37], v[32:35], off nt
	v_mfma_f32_16x16x32_bf16 v[6:9], v[6:9], v[28:31], 0
	s_waitcnt lgkmcnt(0)
	v_lshlrev_b32_e32 v20, 16, v18
	v_and_b32_e32 v21, 0xffff0000, v18
	v_lshlrev_b32_e32 v18, 16, v19
	v_and_b32_e32 v19, 0xffff0000, v19
	v_pk_fma_f32 v[12:13], v[22:23], v[18:19], v[12:13] op_sel_hi:[0,1,1]
	v_pk_fma_f32 v[10:11], v[22:23], v[20:21], v[10:11] op_sel_hi:[0,1,1]
	v_cvt_pk_bf16_f32 v10, v10, v11
	v_cvt_pk_bf16_f32 v11, v12, v13
	v_add_u32_e32 v12, s5, v23
	ds_read_b64 v[12:13], v12 offset:34816
	v_mfma_f32_16x16x32_bf16 v[6:9], v[14:17], v[24:27], v[6:9]
	s_lshl_b32 s5, s90, 7
	s_and_b32 s5, s5, 0x80
	v_add3_u32 v118, v113, s5, v115
	s_waitcnt lgkmcnt(0)
	v_lshlrev_b32_e32 v14, 16, v12
	v_and_b32_e32 v15, 0xffff0000, v12
	v_lshlrev_b32_e32 v12, 16, v13
	v_and_b32_e32 v13, 0xffff0000, v13
	v_pk_fma_f32 v[8:9], v[22:23], v[12:13], v[8:9] op_sel_hi:[0,1,1]
	v_pk_fma_f32 v[6:7], v[22:23], v[14:15], v[6:7] op_sel_hi:[0,1,1]
	v_cvt_pk_bf16_f32 v12, v6, v7
	v_cvt_pk_bf16_f32 v13, v8, v9
	global_store_dwordx4 v[36:37], v[10:13], off offset:2048 nt
	ds_read_b64_tr_b16 v[28:29], v118 offset:1088
	ds_read_b64_tr_b16 v[26:27], v118
	ds_read_b64_tr_b16 v[34:35], v118 offset:32
	ds_read_b64_tr_b16 v[46:47], v60
	ds_read_b64_tr_b16 v[48:49], v60 offset:2112
	ds_read_b64_tr_b16 v[38:39], v118 offset:8704
	ds_read_b64_tr_b16 v[40:41], v118 offset:9792
	ds_read_b64_tr_b16 v[6:7], v60 offset:16896
	ds_read_b64_tr_b16 v[8:9], v60 offset:19008
	ds_read_b64_tr_b16 v[36:37], v118 offset:1120
	s_waitcnt lgkmcnt(5)
	v_mfma_f32_16x16x32_bf16 v[10:13], v[26:29], v[46:49], 0
	ds_read_b64_tr_b16 v[42:43], v118 offset:8736
	ds_read_b64_tr_b16 v[44:45], v118 offset:9824
	s_cmpk_gt_i32 s36, 0xff
	s_waitcnt lgkmcnt(3)
	v_mfma_f32_16x16x32_bf16 v[10:13], v[38:41], v[6:9], v[10:13]
	s_nop 7
	v_cvt_pk_bf16_f32 v10, v10, v11
	v_cvt_pk_bf16_f32 v11, v12, v13
	s_waitcnt lgkmcnt(2)
	v_mfma_f32_16x16x32_bf16 v[12:15], v[34:37], v[46:49], 0
	s_waitcnt lgkmcnt(0)
	v_mfma_f32_16x16x32_bf16 v[12:15], v[42:45], v[6:9], v[12:15]
	s_nop 7
	v_cvt_pk_bf16_f32 v12, v12, v13
	v_cvt_pk_bf16_f32 v13, v14, v15
	v_or_b32_e32 v14, s5, v116
	v_permlane16_swap_b32_e32 v10, v12
	v_permlane16_swap_b32_e32 v11, v13
	v_lshlrev_b32_e32 v190, 4, v14
	global_store_dwordx4 v190, v[10:13], s[82:83] nt
	ds_read_b64_tr_b16 v[14:15], v60 offset:32
	ds_read_b64_tr_b16 v[16:17], v60 offset:2144
	ds_read_b64_tr_b16 v[10:11], v60 offset:16928
	ds_read_b64_tr_b16 v[12:13], v60 offset:19040
	s_waitcnt lgkmcnt(2)
	v_mfma_f32_16x16x32_bf16 v[18:21], v[26:29], v[14:17], 0
	v_lshl_add_u64 v[50:51], s[82:83], 0, v[190:191]
	v_add_co_u32_e32 v58, vcc, s40, v50
	s_waitcnt lgkmcnt(0)
	v_mfma_f32_16x16x32_bf16 v[18:21], v[38:41], v[10:13], v[18:21]
	v_addc_co_u32_e32 v59, vcc, 0, v51, vcc
	v_add_co_u32_e32 v56, vcc, s4, v50
	s_movk_i32 s4, 0x3000
	s_nop 4
	v_cvt_pk_bf16_f32 v18, v18, v19
	v_cvt_pk_bf16_f32 v19, v20, v21
	v_mfma_f32_16x16x32_bf16 v[20:23], v[34:37], v[14:17], 0
	v_addc_co_u32_e32 v57, vcc, 0, v51, vcc
	v_mfma_f32_16x16x32_bf16 v[20:23], v[42:45], v[10:13], v[20:23]
	s_nop 7
	v_cvt_pk_bf16_f32 v20, v20, v21
	v_cvt_pk_bf16_f32 v21, v22, v23
	s_nop 0
	v_permlane16_swap_b32_e32 v18, v20
	v_permlane16_swap_b32_e32 v19, v21
	global_store_dwordx4 v[56:57], v[18:21], off offset:-4096 nt
	ds_read_b64_tr_b16 v[22:23], v60 offset:64
	ds_read_b64_tr_b16 v[24:25], v60 offset:2176
	ds_read_b64_tr_b16 v[18:19], v60 offset:16960
	ds_read_b64_tr_b16 v[20:21], v60 offset:19072
	s_waitcnt lgkmcnt(2)
	v_mfma_f32_16x16x32_bf16 v[30:33], v[26:29], v[22:25], 0
	v_mfma_f32_16x16x32_bf16 v[52:55], v[34:37], v[22:25], 0
	s_waitcnt lgkmcnt(0)
	v_mfma_f32_16x16x32_bf16 v[30:33], v[38:41], v[18:21], v[30:33]
	v_mfma_f32_16x16x32_bf16 v[52:55], v[42:45], v[18:21], v[52:55]
	s_nop 6
	v_cvt_pk_bf16_f32 v30, v30, v31
	v_cvt_pk_bf16_f32 v31, v32, v33
	v_cvt_pk_bf16_f32 v32, v52, v53
	v_cvt_pk_bf16_f32 v33, v54, v55
	s_nop 0
	v_permlane16_swap_b32_e32 v30, v32
	v_permlane16_swap_b32_e32 v31, v33
	global_store_dwordx4 v[56:57], v[30:33], off nt
	ds_read_b64_tr_b16 v[30:31], v60 offset:96
	ds_read_b64_tr_b16 v[32:33], v60 offset:2208
	s_waitcnt lgkmcnt(0)
	v_mfma_f32_16x16x32_bf16 v[52:55], v[26:29], v[30:33], 0
	ds_read_b64_tr_b16 v[26:27], v60 offset:16992
	ds_read_b64_tr_b16 v[28:29], v60 offset:19104
	v_add_co_u32_e32 v60, vcc, s4, v50
	v_mfma_f32_16x16x32_bf16 v[34:37], v[34:37], v[30:33], 0
	s_nop 0
	v_addc_co_u32_e32 v61, vcc, 0, v51, vcc
	s_waitcnt lgkmcnt(0)
	v_mfma_f32_16x16x32_bf16 v[38:41], v[38:41], v[26:29], v[52:55]
	v_mfma_f32_16x16x32_bf16 v[34:37], v[42:45], v[26:29], v[34:37]
	s_nop 6
	v_cvt_pk_bf16_f32 v38, v38, v39
	v_cvt_pk_bf16_f32 v39, v40, v41
	v_cvt_pk_bf16_f32 v40, v34, v35
	v_cvt_pk_bf16_f32 v41, v36, v37
	s_nop 0
	v_permlane16_swap_b32_e32 v38, v40
	v_permlane16_swap_b32_e32 v39, v41
	global_store_dwordx4 v[60:61], v[38:41], off nt
	ds_read_b64_tr_b16 v[36:37], v118 offset:1152
	ds_read_b64_tr_b16 v[34:35], v118 offset:64
	ds_read_b64_tr_b16 v[38:39], v118 offset:96
	ds_read_b64_tr_b16 v[42:43], v118 offset:8768
	ds_read_b64_tr_b16 v[44:45], v118 offset:9856
	ds_read_b64_tr_b16 v[40:41], v118 offset:1184
	s_waitcnt lgkmcnt(4)
	v_mfma_f32_16x16x32_bf16 v[50:53], v[34:37], v[46:49], 0
	s_waitcnt lgkmcnt(1)
	v_mfma_f32_16x16x32_bf16 v[50:53], v[42:45], v[6:9], v[50:53]
	s_nop 7
	v_cvt_pk_bf16_f32 v50, v50, v51
	v_cvt_pk_bf16_f32 v51, v52, v53
	s_waitcnt lgkmcnt(0)
	v_mfma_f32_16x16x32_bf16 v[52:55], v[38:41], v[46:49], 0
	ds_read_b64_tr_b16 v[46:47], v118 offset:8800
	ds_read_b64_tr_b16 v[48:49], v118 offset:9888
	s_waitcnt lgkmcnt(0)
	v_mfma_f32_16x16x32_bf16 v[6:9], v[46:49], v[6:9], v[52:55]
	s_nop 7
	v_cvt_pk_bf16_f32 v52, v6, v7
	v_cvt_pk_bf16_f32 v53, v8, v9
	v_or_b32_e32 v6, s5, v117
	v_permlane16_swap_b32_e32 v50, v52
	v_permlane16_swap_b32_e32 v51, v53
	v_lshlrev_b32_e32 v6, 4, v6
	global_store_dwordx4 v6, v[50:53], s[82:83] nt
	v_mfma_f32_16x16x32_bf16 v[6:9], v[34:37], v[14:17], 0
	v_mfma_f32_16x16x32_bf16 v[6:9], v[42:45], v[10:13], v[6:9]
	v_mfma_f32_16x16x32_bf16 v[14:17], v[38:41], v[14:17], 0
	s_nop 6
	v_cvt_pk_bf16_f32 v6, v6, v7
	v_cvt_pk_bf16_f32 v7, v8, v9
	v_mfma_f32_16x16x32_bf16 v[8:11], v[46:49], v[10:13], v[14:17]
	s_nop 7
	v_cvt_pk_bf16_f32 v8, v8, v9
	v_cvt_pk_bf16_f32 v9, v10, v11
	s_nop 0
	v_permlane16_swap_b32_e32 v6, v8
	v_permlane16_swap_b32_e32 v7, v9
	global_store_dwordx4 v[58:59], v[6:9], off offset:1024 nt
	s_nop 1
	v_mfma_f32_16x16x32_bf16 v[6:9], v[34:37], v[22:25], 0
	v_mfma_f32_16x16x32_bf16 v[6:9], v[42:45], v[18:21], v[6:9]
	s_nop 7
	v_cvt_pk_bf16_f32 v6, v6, v7
	v_cvt_pk_bf16_f32 v7, v8, v9
	v_mfma_f32_16x16x32_bf16 v[8:11], v[38:41], v[22:25], 0
	v_mfma_f32_16x16x32_bf16 v[8:11], v[46:49], v[18:21], v[8:11]
	s_nop 7
	v_cvt_pk_bf16_f32 v8, v8, v9
	v_cvt_pk_bf16_f32 v9, v10, v11
	s_nop 0
	v_permlane16_swap_b32_e32 v6, v8
	v_permlane16_swap_b32_e32 v7, v9
	global_store_dwordx4 v[56:57], v[6:9], off offset:1024 nt
	s_nop 1
	v_mfma_f32_16x16x32_bf16 v[6:9], v[34:37], v[30:33], 0
	v_mfma_f32_16x16x32_bf16 v[6:9], v[42:45], v[26:29], v[6:9]
	s_nop 7
	v_cvt_pk_bf16_f32 v6, v6, v7
	v_cvt_pk_bf16_f32 v7, v8, v9
	v_mfma_f32_16x16x32_bf16 v[8:11], v[38:41], v[30:33], 0
	v_mfma_f32_16x16x32_bf16 v[8:11], v[46:49], v[26:29], v[8:11]
	s_nop 7
	v_cvt_pk_bf16_f32 v8, v8, v9
	v_cvt_pk_bf16_f32 v9, v10, v11
	s_nop 0
	v_permlane16_swap_b32_e32 v6, v8
	v_permlane16_swap_b32_e32 v7, v9
	global_store_dwordx4 v[60:61], v[6:9], off offset:1024 nt
	s_waitcnt lgkmcnt(0)
	s_barrier
	s_cbranch_scc1 .LBB0_1020

.LBB0_949:
	s_or_b64 exec, exec, s[82:83]
	s_waitcnt lgkmcnt(0)
	s_barrier
	s_and_saveexec_b64 s[82:83], s[66:67]
	s_cbranch_execz .LBB0_952
	v_add_u32_e32 v6, 0, v78
	v_add_u32_e32 v10, 0x22400, v6
	ds_read_b128 v[6:9], v10
	v_and_b32_e32 v11, 64, v221
	v_add_u32_e32 v12, -1, v221
	v_cmp_lt_i32_e32 vcc, v12, v11
	v_readlane_b32 s4, v255, 28
	v_readlane_b32 s5, v255, 29
	v_cndmask_b32_e32 v12, v12, v221, vcc
	v_lshlrev_b32_e32 v12, 2, v12
	s_waitcnt lgkmcnt(0)
	ds_bpermute_b32 v13, v12, v6
	ds_bpermute_b32 v14, v12, v7
	ds_bpermute_b32 v15, v12, v8
	ds_bpermute_b32 v12, v12, v9
	s_waitcnt lgkmcnt(3)
	v_add_f32_e32 v13, v6, v13
	s_waitcnt lgkmcnt(2)
	v_add_f32_e32 v14, v7, v14
	s_waitcnt lgkmcnt(1)
	v_add_f32_e32 v15, v8, v15
	s_waitcnt lgkmcnt(0)
	v_add_f32_e32 v12, v9, v12
	v_cndmask_b32_e64 v9, v12, v9, s[68:69]
	v_add_u32_e32 v12, -2, v221
	v_cmp_lt_i32_e32 vcc, v12, v11
	v_cndmask_b32_e64 v8, v15, v8, s[68:69]
	v_cndmask_b32_e64 v7, v14, v7, s[68:69]
	v_cndmask_b32_e32 v12, v12, v221, vcc
	v_cndmask_b32_e64 v6, v13, v6, s[68:69]
	v_lshlrev_b32_e32 v12, 2, v12
	ds_bpermute_b32 v13, v12, v6
	ds_bpermute_b32 v14, v12, v7
	ds_bpermute_b32 v15, v12, v8
	ds_bpermute_b32 v12, v12, v9
	s_waitcnt lgkmcnt(3)
	v_add_f32_e32 v13, v6, v13
	s_waitcnt lgkmcnt(2)
	v_add_f32_e32 v14, v7, v14
	s_waitcnt lgkmcnt(1)
	v_add_f32_e32 v15, v8, v15
	s_waitcnt lgkmcnt(0)
	v_add_f32_e32 v12, v9, v12
	v_cndmask_b32_e64 v9, v12, v9, s[70:71]
	v_add_u32_e32 v12, -4, v221
	v_cmp_lt_i32_e32 vcc, v12, v11
	v_cndmask_b32_e64 v8, v15, v8, s[70:71]
	v_cndmask_b32_e64 v7, v14, v7, s[70:71]
	v_cndmask_b32_e32 v12, v12, v221, vcc
	v_cndmask_b32_e64 v6, v13, v6, s[70:71]
	v_lshlrev_b32_e32 v12, 2, v12
	ds_bpermute_b32 v13, v12, v6
	ds_bpermute_b32 v14, v12, v7
	ds_bpermute_b32 v15, v12, v8
	ds_bpermute_b32 v12, v12, v9
	s_waitcnt lgkmcnt(3)
	v_add_f32_e32 v13, v6, v13
	s_waitcnt lgkmcnt(2)
	v_add_f32_e32 v14, v7, v14
	s_waitcnt lgkmcnt(1)
	v_add_f32_e32 v15, v8, v15
	s_waitcnt lgkmcnt(0)
	v_add_f32_e32 v12, v9, v12
	v_cndmask_b32_e64 v9, v12, v9, s[64:65]
	v_add_u32_e32 v12, -8, v221
	v_cmp_lt_i32_e32 vcc, v12, v11
	v_cndmask_b32_e64 v8, v15, v8, s[64:65]
	v_cndmask_b32_e64 v7, v14, v7, s[64:65]
	v_cndmask_b32_e32 v12, v12, v221, vcc
	v_cndmask_b32_e64 v6, v13, v6, s[64:65]
	v_lshlrev_b32_e32 v12, 2, v12
	ds_bpermute_b32 v13, v12, v6
	ds_bpermute_b32 v14, v12, v7
	ds_bpermute_b32 v15, v12, v8
	ds_bpermute_b32 v12, v12, v9
	s_waitcnt lgkmcnt(3)
	v_add_f32_e32 v13, v6, v13
	s_waitcnt lgkmcnt(2)
	v_add_f32_e32 v14, v7, v14
	s_waitcnt lgkmcnt(1)
	v_add_f32_e32 v15, v8, v15
	s_waitcnt lgkmcnt(0)
	v_add_f32_e32 v12, v9, v12
	v_cndmask_b32_e64 v9, v12, v9, s[74:75]
	v_add_u32_e32 v12, -16, v221
	v_cmp_lt_i32_e32 vcc, v12, v11
	v_cndmask_b32_e64 v8, v15, v8, s[74:75]
	v_cndmask_b32_e64 v7, v14, v7, s[74:75]
	v_cndmask_b32_e32 v12, v12, v221, vcc
	v_cndmask_b32_e64 v6, v13, v6, s[74:75]
	v_lshlrev_b32_e32 v12, 2, v12
	ds_bpermute_b32 v13, v12, v6
	ds_bpermute_b32 v14, v12, v7
	ds_bpermute_b32 v15, v12, v8
	ds_bpermute_b32 v12, v12, v9
	s_waitcnt lgkmcnt(3)
	v_add_f32_e32 v13, v6, v13
	s_waitcnt lgkmcnt(2)
	v_add_f32_e32 v14, v7, v14
	s_waitcnt lgkmcnt(1)
	v_add_f32_e32 v15, v8, v15
	s_waitcnt lgkmcnt(0)
	v_add_f32_e32 v12, v9, v12
	v_cndmask_b32_e64 v9, v12, v9, s[80:81]
	v_subrev_u32_e32 v12, 32, v221
	v_cmp_lt_i32_e32 vcc, v12, v11
	v_cndmask_b32_e64 v8, v15, v8, s[80:81]
	v_cndmask_b32_e64 v7, v14, v7, s[80:81]
	v_cndmask_b32_e32 v11, v12, v221, vcc
	v_cndmask_b32_e64 v6, v13, v6, s[80:81]
	v_lshlrev_b32_e32 v11, 2, v11
	ds_bpermute_b32 v12, v11, v6
	ds_bpermute_b32 v13, v11, v7
	ds_bpermute_b32 v14, v11, v8
	ds_bpermute_b32 v11, v11, v9
	s_waitcnt lgkmcnt(3)
	v_add_f32_e32 v12, v6, v12
	s_waitcnt lgkmcnt(2)
	v_add_f32_e32 v13, v7, v13
	s_waitcnt lgkmcnt(1)
	v_add_f32_e32 v14, v8, v14
	s_waitcnt lgkmcnt(0)
	v_add_f32_e32 v11, v9, v11
	v_cndmask_b32_e64 v9, v11, v9, s[78:79]
	v_cndmask_b32_e64 v8, v14, v8, s[78:79]
	v_cndmask_b32_e64 v7, v13, v7, s[78:79]
	v_cndmask_b32_e64 v6, v12, v6, s[78:79]
	ds_write_b128 v10, v[6:9]
	s_and_b64 exec, exec, s[4:5]
	s_cbranch_execz .LBB0_952
	s_lshl_b32 s4, s88, 3
	s_lshl_b32 s5, s86, 2
	s_or_b32 s4, s5, s4
	s_ashr_i32 s5, s4, 31
	s_lshl_b64 s[4:5], s[4:5], 2
	v_readlane_b32 s40, v255, 40
	s_add_u32 s4, s40, s4
	v_readlane_b32 s40, v255, 41
	s_addc_u32 s5, s40, s5
	v_readlane_b32 s40, v255, 8
	v_mul_f32_e32 v10, 0x3fb8aa3b, v6
	v_mul_f32_e32 v11, 0x3fb8aa3b, v7
	v_mov_b32_e32 v13, s40
	v_mul_f32_e32 v12, 0x3fb8aa3b, v8
	ds_write_b128 v13, v[6:9]
	v_mul_f32_e32 v6, 0x3fb8aa3b, v9
	v_exp_f32_e32 v10, v10
	v_exp_f32_e32 v11, v11
	v_exp_f32_e32 v12, v12
	v_exp_f32_e32 v13, v6
	global_store_dwordx4 v191, v[10:13], s[4:5] nt
.LBB0_952:
	s_or_b64 exec, exec, s[82:83]
	s_waitcnt lgkmcnt(0)
	s_barrier
	ds_read_b32 v10, v98
	ds_read_b32 v11, v99
	ds_read_b128 v[6:9], v100 offset:34816
	ds_read_b32 v12, v97
	s_lshl_b32 s4, s88, 3
	s_lshl_b32 s41, s86, 2
	s_waitcnt lgkmcnt(2)
	v_sub_f32_e32 v10, v10, v11
	v_mul_f32_e32 v10, 0x3fb8aa3b, v10
	v_exp_f32_e32 v10, v10
	s_waitcnt lgkmcnt(1)
	v_lshlrev_b32_e32 v24, 16, v6
	v_and_b32_e32 v25, 0xffff0000, v6
	s_ashr_i32 s40, s37, 7
	s_waitcnt lgkmcnt(0)
	v_mul_f32_e32 v22, v12, v10
	v_pk_mul_f32 v[24:25], v[22:23], v[24:25] op_sel_hi:[0,1]
	v_cvt_pk_bf16_f32 v6, v24, v25
	v_lshlrev_b32_e32 v24, 16, v7
	v_and_b32_e32 v25, 0xffff0000, v7
	v_pk_mul_f32 v[24:25], v[22:23], v[24:25] op_sel_hi:[0,1]
	v_cvt_pk_bf16_f32 v7, v24, v25
	v_lshlrev_b32_e32 v24, 16, v8
	v_and_b32_e32 v25, 0xffff0000, v8
	v_pk_mul_f32 v[24:25], v[22:23], v[24:25] op_sel_hi:[0,1]
	ds_read_b128 v[10:13], v100 offset:34832
	ds_read_b128 v[14:17], v100 offset:34848
	ds_read_b128 v[18:21], v100 offset:34864
	v_cvt_pk_bf16_f32 v8, v24, v25
	v_lshlrev_b32_e32 v24, 16, v9
	v_and_b32_e32 v25, 0xffff0000, v9
	v_pk_mul_f32 v[24:25], v[22:23], v[24:25] op_sel_hi:[0,1]
	v_cvt_pk_bf16_f32 v9, v24, v25
	ds_write_b128 v101, v[6:9]
	s_waitcnt lgkmcnt(3)
	v_lshlrev_b32_e32 v6, 16, v10
	v_and_b32_e32 v7, 0xffff0000, v10
	v_lshlrev_b32_e32 v8, 16, v11
	v_and_b32_e32 v9, 0xffff0000, v11
	v_pk_mul_f32 v[6:7], v[22:23], v[6:7] op_sel_hi:[0,1]
	v_pk_mul_f32 v[8:9], v[22:23], v[8:9] op_sel_hi:[0,1]
	v_cvt_pk_bf16_f32 v6, v6, v7
	v_cvt_pk_bf16_f32 v7, v8, v9
	v_lshlrev_b32_e32 v8, 16, v12
	v_and_b32_e32 v9, 0xffff0000, v12
	v_lshlrev_b32_e32 v10, 16, v13
	v_and_b32_e32 v11, 0xffff0000, v13
	v_pk_mul_f32 v[8:9], v[22:23], v[8:9] op_sel_hi:[0,1]
	v_pk_mul_f32 v[10:11], v[22:23], v[10:11] op_sel_hi:[0,1]
	v_cvt_pk_bf16_f32 v8, v8, v9
	v_cvt_pk_bf16_f32 v9, v10, v11
	ds_write_b128 v101, v[6:9] offset:16
	s_waitcnt lgkmcnt(3)
	v_lshlrev_b32_e32 v6, 16, v14
	v_and_b32_e32 v7, 0xffff0000, v14
	v_lshlrev_b32_e32 v8, 16, v15
	v_and_b32_e32 v9, 0xffff0000, v15
	v_pk_mul_f32 v[6:7], v[22:23], v[6:7] op_sel_hi:[0,1]
	v_pk_mul_f32 v[8:9], v[22:23], v[8:9] op_sel_hi:[0,1]
	s_or_b32 s4, s41, s4
	v_cvt_pk_bf16_f32 v6, v6, v7
	v_cvt_pk_bf16_f32 v7, v8, v9
	v_lshlrev_b32_e32 v8, 16, v16
	v_and_b32_e32 v9, 0xffff0000, v16
	v_lshlrev_b32_e32 v10, 16, v17
	v_and_b32_e32 v11, 0xffff0000, v17
	s_add_i32 s4, s4, s40
	v_pk_mul_f32 v[8:9], v[22:23], v[8:9] op_sel_hi:[0,1]
	v_pk_mul_f32 v[10:11], v[22:23], v[10:11] op_sel_hi:[0,1]
	s_ashr_i32 s5, s4, 31
	s_ashr_i32 s90, s37, 6
	v_cvt_pk_bf16_f32 v8, v8, v9
	v_cvt_pk_bf16_f32 v9, v10, v11
	s_lshl_b64 s[4:5], s[4:5], 14
	ds_write_b128 v101, v[6:9] offset:32
	s_waitcnt lgkmcnt(3)
	v_lshlrev_b32_e32 v6, 16, v18
	v_and_b32_e32 v7, 0xffff0000, v18
	v_lshlrev_b32_e32 v8, 16, v19
	v_and_b32_e32 v9, 0xffff0000, v19
	s_add_u32 s82, s14, s4
	v_pk_mul_f32 v[6:7], v[22:23], v[6:7] op_sel_hi:[0,1]
	v_pk_mul_f32 v[8:9], v[22:23], v[8:9] op_sel_hi:[0,1]
	s_addc_u32 s83, s15, s5
	s_lshl_b32 s4, s90, 1
	v_cvt_pk_bf16_f32 v6, v6, v7
	v_cvt_pk_bf16_f32 v7, v8, v9
	v_lshlrev_b32_e32 v8, 16, v20
	v_and_b32_e32 v9, 0xffff0000, v20
	v_lshlrev_b32_e32 v10, 16, v21
	v_and_b32_e32 v11, 0xffff0000, v21
	s_and_b32 s91, s4, 2
	s_lshl_b32 s4, s40, 2
	v_pk_mul_f32 v[8:9], v[22:23], v[8:9] op_sel_hi:[0,1]
	v_pk_mul_f32 v[10:11], v[22:23], v[10:11] op_sel_hi:[0,1]
	s_add_i32 s4, s4, 0
	v_lshl_or_b32 v21, s91, 4, v66
	v_cvt_pk_bf16_f32 v8, v8, v9
	v_cvt_pk_bf16_f32 v9, v10, v11
	s_add_i32 s4, s4, 0x22400
	v_lshlrev_b32_e32 v22, 4, v21
	ds_write_b128 v101, v[6:9] offset:48
	v_add_u32_e32 v6, s4, v22
	ds_read_b32 v10, v6
	v_mad_u32_u24 v15, v21, s7, v236
	ds_read_b128 v[6:9], v15 offset:17408
	v_lshlrev_b32_e32 v20, 1, v67
	v_lshl_or_b32 v18, s91, 12, v20
	s_waitcnt lgkmcnt(1)
	v_mul_f32_e32 v10, 0x3fb8aa3b, v10
	v_exp_f32_e32 v14, v10
	s_waitcnt lgkmcnt(0)
	v_lshlrev_b32_e32 v10, 16, v6
	v_and_b32_e32 v11, 0xffff0000, v6
	s_or_b32 s60, s91, 1
	v_pk_mul_f32 v[10:11], v[14:15], v[10:11] op_sel_hi:[0,1]
	v_cvt_pk_bf16_f32 v6, v10, v11
	v_lshlrev_b32_e32 v10, 16, v7
	v_and_b32_e32 v11, 0xffff0000, v7
	v_pk_mul_f32 v[10:11], v[14:15], v[10:11] op_sel_hi:[0,1]
	v_cvt_pk_bf16_f32 v7, v10, v11
	v_lshlrev_b32_e32 v10, 16, v8
	v_and_b32_e32 v11, 0xffff0000, v8
	v_pk_mul_f32 v[10:11], v[14:15], v[10:11] op_sel_hi:[0,1]
	v_cvt_pk_bf16_f32 v8, v10, v11
	v_lshlrev_b32_e32 v10, 16, v9
	v_and_b32_e32 v11, 0xffff0000, v9
	v_pk_mul_f32 v[10:11], v[14:15], v[10:11] op_sel_hi:[0,1]
	v_cvt_pk_bf16_f32 v9, v10, v11
	ds_read_b128 v[10:13], v15 offset:17472
	global_store_dwordx4 v18, v[6:9], s[82:83] nt
	ds_read_b128 v[6:9], v15 offset:17536
	v_lshl_or_b32 v20, s60, 12, v20
	v_mov_b32_e32 v23, 0
	s_waitcnt lgkmcnt(1)
	v_lshlrev_b32_e32 v16, 16, v10
	v_and_b32_e32 v17, 0xffff0000, v10
	v_pk_mul_f32 v[16:17], v[14:15], v[16:17] op_sel_hi:[0,1]
	v_cvt_pk_bf16_f32 v10, v16, v17
	v_lshlrev_b32_e32 v16, 16, v11
	v_and_b32_e32 v17, 0xffff0000, v11
	v_pk_mul_f32 v[16:17], v[14:15], v[16:17] op_sel_hi:[0,1]
	v_cvt_pk_bf16_f32 v11, v16, v17
	v_lshlrev_b32_e32 v16, 16, v12
	v_and_b32_e32 v17, 0xffff0000, v12
	v_pk_mul_f32 v[16:17], v[14:15], v[16:17] op_sel_hi:[0,1]
	v_cvt_pk_bf16_f32 v12, v16, v17
	v_lshlrev_b32_e32 v16, 16, v13
	v_and_b32_e32 v17, 0xffff0000, v13
	v_pk_mul_f32 v[16:17], v[14:15], v[16:17] op_sel_hi:[0,1]
	v_cvt_pk_bf16_f32 v13, v16, v17
	global_store_dwordx4 v18, v[10:13], s[82:83] offset:1024 nt
	s_waitcnt lgkmcnt(0)
	s_nop 0
	v_lshlrev_b32_e32 v10, 16, v6
	v_and_b32_e32 v11, 0xffff0000, v6
	v_pk_mul_f32 v[10:11], v[14:15], v[10:11] op_sel_hi:[0,1]
	v_cvt_pk_bf16_f32 v6, v10, v11
	v_lshlrev_b32_e32 v10, 16, v7
	v_and_b32_e32 v11, 0xffff0000, v7
	v_pk_mul_f32 v[10:11], v[14:15], v[10:11] op_sel_hi:[0,1]
	v_cvt_pk_bf16_f32 v7, v10, v11
	v_lshlrev_b32_e32 v10, 16, v8
	v_and_b32_e32 v11, 0xffff0000, v8
	v_pk_mul_f32 v[10:11], v[14:15], v[10:11] op_sel_hi:[0,1]
	v_cvt_pk_bf16_f32 v8, v10, v11
	v_lshlrev_b32_e32 v10, 16, v9
	v_and_b32_e32 v11, 0xffff0000, v9
	v_pk_mul_f32 v[10:11], v[14:15], v[10:11] op_sel_hi:[0,1]
	v_cvt_pk_bf16_f32 v9, v10, v11
	global_store_dwordx4 v18, v[6:9], s[82:83] offset:2048 nt
	ds_read_b128 v[6:9], v15 offset:17600
	v_lshl_or_b32 v10, s60, 4, v66
	v_lshlrev_b32_e32 v11, 4, v10
	v_add_u32_e32 v12, s4, v11
	ds_read_b32 v16, v12
	s_waitcnt lgkmcnt(1)
	v_lshlrev_b32_e32 v12, 16, v6
	v_and_b32_e32 v13, 0xffff0000, v6
	v_pk_mul_f32 v[12:13], v[14:15], v[12:13] op_sel_hi:[0,1]
	v_cvt_pk_bf16_f32 v6, v12, v13
	v_lshlrev_b32_e32 v12, 16, v7
	v_and_b32_e32 v13, 0xffff0000, v7
	v_pk_mul_f32 v[12:13], v[14:15], v[12:13] op_sel_hi:[0,1]
	v_cvt_pk_bf16_f32 v7, v12, v13
	v_lshlrev_b32_e32 v12, 16, v8
	v_and_b32_e32 v13, 0xffff0000, v8
	v_pk_mul_f32 v[12:13], v[14:15], v[12:13] op_sel_hi:[0,1]
	v_cvt_pk_bf16_f32 v8, v12, v13
	v_lshlrev_b32_e32 v12, 16, v9
	v_and_b32_e32 v13, 0xffff0000, v9
	v_pk_mul_f32 v[12:13], v[14:15], v[12:13] op_sel_hi:[0,1]
	v_mad_u32_u24 v17, v10, s7, v236
	v_cvt_pk_bf16_f32 v9, v12, v13
	ds_read_b128 v[12:15], v17 offset:17408
	global_store_dwordx4 v18, v[6:9], s[82:83] offset:3072 nt
	s_lshl_b32 s4, s40, 4
	s_cmp_lt_i32 s91, s40
	s_waitcnt lgkmcnt(1)
	v_mul_f32_e32 v6, 0x3fb8aa3b, v16
	v_exp_f32_e32 v16, v6
	ds_read_b128 v[6:9], v17 offset:17472
	s_waitcnt lgkmcnt(1)
	v_lshlrev_b32_e32 v18, 16, v12
	v_and_b32_e32 v19, 0xffff0000, v12
	v_pk_mul_f32 v[18:19], v[16:17], v[18:19] op_sel_hi:[0,1]
	v_cvt_pk_bf16_f32 v12, v18, v19
	v_lshlrev_b32_e32 v18, 16, v13
	v_and_b32_e32 v19, 0xffff0000, v13
	v_pk_mul_f32 v[18:19], v[16:17], v[18:19] op_sel_hi:[0,1]
	v_cvt_pk_bf16_f32 v13, v18, v19
	v_lshlrev_b32_e32 v18, 16, v14
	v_and_b32_e32 v19, 0xffff0000, v14
	v_pk_mul_f32 v[18:19], v[16:17], v[18:19] op_sel_hi:[0,1]
	v_cvt_pk_bf16_f32 v14, v18, v19
	v_lshlrev_b32_e32 v18, 16, v15
	v_and_b32_e32 v19, 0xffff0000, v15
	v_pk_mul_f32 v[18:19], v[16:17], v[18:19] op_sel_hi:[0,1]
	v_cvt_pk_bf16_f32 v15, v18, v19
	global_store_dwordx4 v20, v[12:15], s[82:83] nt
	s_waitcnt lgkmcnt(0)
	v_lshlrev_b32_e32 v18, 16, v9
	v_and_b32_e32 v19, 0xffff0000, v9
	v_lshlrev_b32_e32 v12, 16, v6
	v_and_b32_e32 v13, 0xffff0000, v6
	v_pk_mul_f32 v[12:13], v[16:17], v[12:13] op_sel_hi:[0,1]
	v_cvt_pk_bf16_f32 v6, v12, v13
	v_lshlrev_b32_e32 v12, 16, v7
	v_and_b32_e32 v13, 0xffff0000, v7
	v_pk_mul_f32 v[12:13], v[16:17], v[12:13] op_sel_hi:[0,1]
	v_cvt_pk_bf16_f32 v7, v12, v13
	v_lshlrev_b32_e32 v12, 16, v8
	v_and_b32_e32 v13, 0xffff0000, v8
	v_pk_mul_f32 v[12:13], v[16:17], v[12:13] op_sel_hi:[0,1]
	v_cvt_pk_bf16_f32 v8, v12, v13
	ds_read_b128 v[12:15], v17 offset:17536
	v_pk_mul_f32 v[18:19], v[16:17], v[18:19] op_sel_hi:[0,1]
	v_cvt_pk_bf16_f32 v9, v18, v19
	global_store_dwordx4 v20, v[6:9], s[82:83] offset:1024 nt
	ds_read_b128 v[6:9], v17 offset:17600
	s_waitcnt lgkmcnt(1)
	v_lshlrev_b32_e32 v18, 16, v12
	v_and_b32_e32 v19, 0xffff0000, v12
	v_pk_mul_f32 v[18:19], v[16:17], v[18:19] op_sel_hi:[0,1]
	v_cvt_pk_bf16_f32 v12, v18, v19
	v_lshlrev_b32_e32 v18, 16, v13
	v_and_b32_e32 v19, 0xffff0000, v13
	v_pk_mul_f32 v[18:19], v[16:17], v[18:19] op_sel_hi:[0,1]
	v_cvt_pk_bf16_f32 v13, v18, v19
	v_lshlrev_b32_e32 v18, 16, v14
	v_and_b32_e32 v19, 0xffff0000, v14
	v_pk_mul_f32 v[18:19], v[16:17], v[18:19] op_sel_hi:[0,1]
	v_cvt_pk_bf16_f32 v14, v18, v19
	v_lshlrev_b32_e32 v18, 16, v15
	v_and_b32_e32 v19, 0xffff0000, v15
	v_pk_mul_f32 v[18:19], v[16:17], v[18:19] op_sel_hi:[0,1]
	v_cvt_pk_bf16_f32 v15, v18, v19
	global_store_dwordx4 v20, v[12:15], s[82:83] offset:2048 nt
	s_waitcnt lgkmcnt(0)
	s_nop 0
	v_lshlrev_b32_e32 v12, 16, v6
	v_and_b32_e32 v13, 0xffff0000, v6
	v_pk_mul_f32 v[12:13], v[16:17], v[12:13] op_sel_hi:[0,1]
	v_cvt_pk_bf16_f32 v6, v12, v13
	v_lshlrev_b32_e32 v12, 16, v7
	v_and_b32_e32 v13, 0xffff0000, v7
	v_pk_mul_f32 v[12:13], v[16:17], v[12:13] op_sel_hi:[0,1]
	v_cvt_pk_bf16_f32 v7, v12, v13
	v_lshlrev_b32_e32 v12, 16, v8
	v_and_b32_e32 v13, 0xffff0000, v8
	v_pk_mul_f32 v[12:13], v[16:17], v[12:13] op_sel_hi:[0,1]
	v_cvt_pk_bf16_f32 v8, v12, v13
	v_lshlrev_b32_e32 v12, 16, v9
	v_and_b32_e32 v13, 0xffff0000, v9
	v_pk_mul_f32 v[12:13], v[16:17], v[12:13] op_sel_hi:[0,1]
	v_cvt_pk_bf16_f32 v9, v12, v13
	global_store_dwordx4 v20, v[6:9], s[82:83] offset:3072 nt
	s_nop 1
	v_or_b32_e32 v6, s4, v66
	v_mul_lo_u32 v6, v6, s7
	v_add_u32_e32 v17, v104, v6
	v_mov_b32_e32 v6, 0
	v_mov_b32_e32 v7, 0
	v_mov_b32_e32 v8, 0
	v_mov_b32_e32 v9, 0
	s_cbranch_scc1 .LBB0_954
	v_mul_u32_u24_e32 v6, 0x110, v21
	v_add_u32_e32 v16, v104, v6
	ds_read_b128 v[6:9], v17
	ds_read_b128 v[12:15], v16 offset:17408
	s_waitcnt lgkmcnt(0)
	v_mfma_f32_16x16x32_bf16 v[6:9], v[6:9], v[12:15], 0
	ds_read_b128 v[12:15], v17 offset:64
	ds_read_b128 v[24:27], v16 offset:17472
	s_waitcnt lgkmcnt(0)
	v_mfma_f32_16x16x32_bf16 v[6:9], v[12:15], v[24:27], v[6:9]
	ds_read_b128 v[12:15], v17 offset:128
	ds_read_b128 v[24:27], v16 offset:17536
	s_waitcnt lgkmcnt(0)
	v_mfma_f32_16x16x32_bf16 v[6:9], v[12:15], v[24:27], v[6:9]
	ds_read_b128 v[12:15], v17 offset:192
	ds_read_b128 v[24:27], v16 offset:17600
	s_waitcnt lgkmcnt(0)
	v_mfma_f32_16x16x32_bf16 v[6:9], v[12:15], v[24:27], v[6:9]

.LBB0_1022:
	v_add_u32_e32 v6, v12, v6
	s_bfe_u32 s14, s3, 0x20006
	s_lshl_b32 s15, s4, 5
	ds_write_b64 v6, v[32:33] offset:45056
	v_lshl_or_b32 v10, s14, 4, v34
	s_and_b32 s21, s15, 0xffffff80
	s_waitcnt lgkmcnt(0)
	s_barrier
	v_add_u32_e32 v31, s21, v53
	v_mad_u32_u24 v32, v10, s6, v47
	ds_read_b64_tr_b16 v[8:9], v31 offset:28736
	ds_read_b64_tr_b16 v[6:7], v31 offset:27648
	ds_read_b128 v[10:13], v32 offset:45056
	ds_read_b128 v[56:59], v32 offset:45120
	ds_read_b64_tr_b16 v[66:67], v31 offset:28768
	ds_read_b64_tr_b16 v[70:71], v31 offset:28800
	ds_read_b64_tr_b16 v[68:69], v31 offset:27712
	ds_read_b64_tr_b16 v[64:65], v31 offset:27680
	ds_read_b64_tr_b16 v[74:75], v31 offset:37504
	ds_read_b64_tr_b16 v[76:77], v31 offset:36352
	ds_read_b64_tr_b16 v[78:79], v31 offset:37440
	ds_read_b64_tr_b16 v[80:81], v31 offset:36384
	ds_read_b64_tr_b16 v[72:73], v31 offset:36416
	ds_read_b64_tr_b16 v[82:83], v31 offset:37472
	s_waitcnt lgkmcnt(11)
	v_mfma_f32_16x16x32_bf16 v[6:9], v[6:9], v[10:13], 0
	s_lshl_b32 s3, s3, 2
	s_and_b32 s3, s3, 0xfffffc00
	v_lshl_or_b32 v31, s14, 11, v48
	s_waitcnt lgkmcnt(6)
	v_mfma_f32_16x16x32_bf16 v[64:67], v[64:67], v[10:13], 0
	s_add_u32 s38, s12, s36
	v_add_u32_e32 v32, s3, v31
	s_addc_u32 s39, s13, s37
	s_waitcnt lgkmcnt(3)
	v_mfma_f32_16x16x32_bf16 v[6:9], v[76:79], v[56:59], v[6:9]
	s_or_b32 s3, s15, 0x60
	v_add_u32_e32 v31, s3, v53
	v_ashrrev_i32_e32 v33, 31, v32
	s_waitcnt lgkmcnt(0)
	v_mfma_f32_16x16x32_bf16 v[64:67], v[80:83], v[56:59], v[64:67]
	v_lshl_add_u64 v[60:61], v[32:33], 1, s[38:39]
	s_nop 1
	v_cvt_pk_bf16_f32 v6, v6, v7
	v_cvt_pk_bf16_f32 v7, v8, v9
	s_mov_b32 s14, 0x15800000
	v_add_co_u32_e32 v60, vcc, s14, v60
	s_nop 0
	v_cvt_pk_bf16_f32 v8, v64, v65
	v_cvt_pk_bf16_f32 v9, v66, v67
	v_mfma_f32_16x16x32_bf16 v[64:67], v[68:71], v[10:13], 0
	ds_read_b64_tr_b16 v[68:69], v31 offset:27648
	ds_read_b64_tr_b16 v[70:71], v31 offset:28736
	v_addc_co_u32_e32 v61, vcc, 0, v61, vcc
	v_mfma_f32_16x16x32_bf16 v[64:67], v[72:75], v[56:59], v[64:67]
	ds_read_b64_tr_b16 v[72:73], v31 offset:36352
	ds_read_b64_tr_b16 v[74:75], v31 offset:37440
	global_store_dwordx4 v[60:61], v[6:9], off nt
	s_and_b32 s3, s4, -2
	s_waitcnt lgkmcnt(2)
	v_mfma_f32_16x16x32_bf16 v[10:13], v[68:71], v[10:13], 0
	s_lshl_b32 s5, s5, 5
	v_or_b32_e32 v32, 0x200, v32
	v_add3_u32 v31, v49, s5, v51
	s_waitcnt lgkmcnt(0)
	v_mfma_f32_16x16x32_bf16 v[8:11], v[72:75], v[56:59], v[10:13]
	s_lshl_b32 s5, s3, 5
	v_ashrrev_i32_e32 v33, 31, v32
	v_add3_u32 v60, v49, s5, v50
	v_cvt_pk_bf16_f32 v6, v64, v65
	v_cvt_pk_bf16_f32 v7, v66, v67
	s_nop 2
	v_cvt_pk_bf16_f32 v8, v8, v9
	v_cvt_pk_bf16_f32 v9, v10, v11
	ds_read_b64_tr_b16 v[12:13], v31 offset:19008
	ds_read_b64_tr_b16 v[10:11], v31 offset:18432
	ds_read_b64_tr_b16 v[56:57], v60 offset:27648
	ds_read_b64_tr_b16 v[58:59], v60 offset:28736
	ds_read_b64_tr_b16 v[64:65], v31 offset:23040
	ds_read_b64_tr_b16 v[66:67], v31 offset:23616
	ds_read_b64_tr_b16 v[70:71], v31 offset:19040
	ds_read_b64_tr_b16 v[68:69], v31 offset:18464
	ds_read_b64_tr_b16 v[72:73], v60 offset:36352
	ds_read_b64_tr_b16 v[74:75], v60 offset:37440
	v_lshl_add_u64 v[32:33], v[32:33], 1, s[38:39]
	v_add_co_u32_e32 v32, vcc, s14, v32
	ds_read_b64_tr_b16 v[82:83], v31 offset:23648
	ds_read_b64_tr_b16 v[80:81], v31 offset:23072
	v_addc_co_u32_e32 v33, vcc, 0, v33, vcc
	global_store_dwordx4 v[32:33], v[6:9], off nt
	s_lshl_b32 s5, s4, 6
	s_or_b32 s4, s4, 1
	s_waitcnt lgkmcnt(4)
	v_mfma_f32_16x16x32_bf16 v[6:9], v[68:71], v[56:59], 0
	s_lshl_b32 s14, s4, 5
	v_add3_u32 v31, v49, s14, v50
	s_and_b32 s5, s5, 64
	s_waitcnt lgkmcnt(0)
	v_mfma_f32_16x16x32_bf16 v[6:9], v[80:83], v[72:75], v[6:9]
	v_lshl_or_b32 v32, s3, 7, v52
	v_or_b32_e32 v32, s5, v32
	v_lshlrev_b32_e32 v32, 3, v32
	v_mfma_f32_16x16x32_bf16 v[76:79], v[10:13], v[56:59], 0
	v_ashrrev_i32_e32 v33, 31, v32
	s_nop 2
	v_cvt_pk_bf16_f32 v58, v6, v7
	v_cvt_pk_bf16_f32 v59, v8, v9
	ds_read_b64_tr_b16 v[6:7], v31 offset:27648
	ds_read_b64_tr_b16 v[8:9], v31 offset:28736
	v_mfma_f32_16x16x32_bf16 v[76:79], v[64:67], v[72:75], v[76:79]
	ds_read_b64_tr_b16 v[72:73], v31 offset:36352
	ds_read_b64_tr_b16 v[74:75], v31 offset:37440
	v_lshl_add_u64 v[32:33], v[32:33], 1, s[38:39]
	s_mov_b32 s3, 0x15000000
	s_waitcnt lgkmcnt(2)
	v_mfma_f32_16x16x32_bf16 v[10:13], v[10:13], v[6:9], 0
	v_add_co_u32_e32 v32, vcc, s3, v32
	s_nop 0
	v_cvt_pk_bf16_f32 v56, v76, v77
	v_mfma_f32_16x16x32_bf16 v[6:9], v[68:71], v[6:9], 0
	v_addc_co_u32_e32 v33, vcc, 0, v33, vcc
	v_cvt_pk_bf16_f32 v57, v78, v79
	s_waitcnt lgkmcnt(0)
	v_mfma_f32_16x16x32_bf16 v[10:13], v[64:67], v[72:75], v[10:13]
	v_permlane16_swap_b32_e32 v56, v58
	v_permlane16_swap_b32_e32 v57, v59
	v_mfma_f32_16x16x32_bf16 v[6:9], v[80:83], v[72:75], v[6:9]
	s_nop 4
	v_cvt_pk_bf16_f32 v10, v10, v11
	v_cvt_pk_bf16_f32 v11, v12, v13
	global_store_dwordx4 v[32:33], v[56:59], off nt
	s_add_i32 s2, s2, s22
	s_add_i32 s0, s0, s1
	v_cvt_pk_bf16_f32 v12, v6, v7
	v_lshl_or_b32 v6, s4, 7, v52
	v_or_b32_e32 v6, s5, v6
	v_lshlrev_b32_e32 v6, 3, v6
	v_ashrrev_i32_e32 v7, 31, v6
	v_lshl_add_u64 v[6:7], v[6:7], 1, s[38:39]
	v_cvt_pk_bf16_f32 v13, v8, v9
	v_add_co_u32_e32 v6, vcc, s3, v6
	v_permlane16_swap_b32_e32 v10, v12
	v_permlane16_swap_b32_e32 v11, v13
	v_addc_co_u32_e32 v7, vcc, 0, v7, vcc
	global_store_dwordx4 v[6:7], v[10:13], off nt
	s_waitcnt lgkmcnt(0)
	s_barrier
	s_add_u32 s36, s36, s44
	s_addc_u32 s37, s37, s45
	v_lshl_add_u64 v[22:23], v[22:23], 0, s[46:47]
	v_lshl_add_u64 v[24:25], v[24:25], 0, s[46:47]
	v_lshl_add_u64 v[26:27], v[26:27], 0, s[46:47]
	s_cmpk_gt_i32 s2, 0x1ff
	v_lshl_add_u64 v[28:29], v[28:29], 0, s[46:47]
	s_cbranch_scc1 .LBB0_1043

.LBB0_1027:
	s_or_b64 exec, exec, s[4:5]
	v_cvt_f32_ubyte0_e32 v31, s14
	v_sub_f32_e32 v31, 0xc0a00000, v31
	s_mov_b32 s14, 0xc2fc0000
	v_cmp_gt_f32_e32 vcc, s14, v31
	s_and_b64 s[4:5], vcc, exec
	s_cselect_b32 s4, 0xffffffc0, 0
	v_cndmask_b32_e32 v70, 0, v227, vcc
	v_add_f32_e32 v31, v31, v70
	v_exp_f32_e32 v31, v31
	v_mul_f32_e32 v71, v68, v68
	v_fmamk_f32 v72, v71, 0xb94c1982, v224
	v_xor_b32_e32 v67, v67, v66
	v_ldexp_f32 v31, v31, s4
	v_sub_f32_e32 v31, 1.0, v31
	s_mov_b32 s4, 0x800000
	v_cmp_gt_f32_e32 vcc, s4, v31
	s_and_b64 s[4:5], vcc, exec
	s_cselect_b32 s4, 32, 0
	v_ldexp_f32 v31, v31, s4
	v_log_f32_e32 v31, v31
	v_cndmask_b32_e32 v70, 0, v228, vcc
	s_brev_b32 s4, 1
	s_waitcnt vmcnt(8)
	v_and_b32_e32 v73, 0xffff0000, v64
	v_sub_f32_e32 v31, v31, v70
	v_fmaak_f32 v70, v71, v72, 0xbe2aaa9d
	v_mul_f32_e32 v70, v71, v70
	v_fmac_f32_e32 v68, v68, v70
	v_fmamk_f32 v70, v71, 0x37d75334, v225
	v_fmaak_f32 v70, v71, v70, 0x3d2aabf7
	v_fmaak_f32 v70, v71, v70, 0xbf000004
	v_fma_f32 v70, v71, v70, 1.0
	v_lshlrev_b32_e32 v71, 30, v69
	v_and_b32_e32 v69, 1, v69
	v_cmp_eq_u32_e32 vcc, 0, v69
	v_and_b32_e32 v72, 0x80000000, v71
	v_cvt_f32_i32_e32 v63, v63
	v_cndmask_b32_e32 v69, v70, v68, vcc
	v_xor_b32_e32 v68, 0x80000000, v68
	v_cndmask_b32_e32 v68, v68, v70, vcc
	v_xor_b32_e32 v67, v67, v69
	v_bitop3_b32 v68, v68, v71, s4 bitop3:0x78
	s_movk_i32 s4, 0x1f8
	v_xor_b32_e32 v67, v67, v72
	v_cmp_class_f32_e64 vcc, v66, s4
	v_lshlrev_b32_e32 v70, 16, v65
	v_and_b32_e32 v71, 0xffff0000, v65
	v_cndmask_b32_e32 v66, v232, v68, vcc
	v_cndmask_b32_e32 v68, v232, v67, vcc
	v_lshlrev_b32_e32 v72, 16, v64
	v_pk_mul_f32 v[64:65], v[68:69], v[70:71] op_sel_hi:[0,1]
	v_pk_fma_f32 v[74:75], v[66:67], v[70:71], v[64:65] op_sel:[0,0,1] op_sel_hi:[1,1,0] neg_lo:[0,0,1] neg_hi:[0,0,1]
	v_pk_fma_f32 v[64:65], v[66:67], v[70:71], v[64:65] op_sel:[0,0,1] op_sel_hi:[0,1,0]
	v_pk_mul_f32 v[68:69], v[68:69], v[72:73] op_sel_hi:[0,1]
	v_mul_f32_e32 v64, v31, v42
	v_pk_fma_f32 v[70:71], v[66:67], v[72:73], v[68:69] op_sel:[0,0,1] op_sel_hi:[1,1,0] neg_lo:[0,0,1] neg_hi:[0,0,1]
	v_pk_fma_f32 v[66:67], v[66:67], v[72:73], v[68:69] op_sel:[0,0,1] op_sel_hi:[0,1,0]
	v_cmp_gt_f32_e32 vcc, s14, v64
	v_mul_f32_e32 v68, v31, v43
	v_cmp_gt_f32_e64 s[38:39], s14, v68
	v_cndmask_b32_e32 v64, 0, v227, vcc
	v_fmac_f32_e32 v64, v31, v42
	v_cndmask_b32_e64 v68, 0, v227, s[38:39]
	v_exp_f32_e32 v64, v64
	v_fmac_f32_e32 v68, v31, v43
	v_exp_f32_e32 v68, v68
	v_mov_b32_e32 v71, v67
	s_mov_b32 s4, 0x3e000000
	v_cndmask_b32_e32 v69, 0, v230, vcc
	v_pk_mul_f32 v[66:67], v[70:71], s[4:5] op_sel_hi:[1,0]
	v_ldexp_f32 v64, v64, v69
	v_cndmask_b32_e64 v69, 0, v230, s[38:39]
	v_mov_b32_e32 v75, v65
	v_ldexp_f32 v68, v68, v69
	v_cvt_pk_bf16_f32 v65, v74, v65
	v_cvt_pk_bf16_f32 v69, v66, v67
	ds_write2st64_b32 v14, v65, v69 offset1:36
	v_pk_mul_f32 v[64:65], v[64:65], v[66:67] op_sel_hi:[0,1]
	v_cvt_pk_bf16_f32 v64, v64, v65
	ds_write_b32 v14, v64 offset:18432
	v_pk_mul_f32 v[64:65], v[68:69], v[74:75] op_sel_hi:[0,1]
	v_cvt_pk_bf16_f32 v66, v64, v65
	v_lshl_add_u64 v[64:65], s[12:13], 0, v[28:29]
	v_mul_f32_e32 v63, v41, v63
	s_brev_b32 s4, 18
	global_store_dword v[64:65], v66, off nt
	v_and_b32_e32 v64, 0x7fffffff, v63
	v_cmp_nlt_f32_e64 s[4:5], |v63|, s4
	s_and_saveexec_b64 s[14:15], s[4:5]
	s_xor_b64 s[48:49], exec, s[14:15]
	s_cbranch_execz .LBB0_1029
	v_lshrrev_b32_e32 v65, 23, v64
	v_add_u32_e32 v65, 0xffffff88, v65
	v_cmp_lt_u32_e32 vcc, 63, v65
	s_mov_b32 s4, 0xfe5163ab
	v_mov_b32_e32 v69, v191
	v_cndmask_b32_e32 v66, 0, v230, vcc
	v_add_u32_e32 v65, v66, v65
	v_cmp_lt_u32_e64 s[38:39], 31, v65
	v_mov_b32_e32 v71, v191
	v_mov_b32_e32 v73, v191
	v_cndmask_b32_e64 v66, 0, v231, s[38:39]
	v_add_u32_e32 v65, v66, v65
	v_cmp_lt_u32_e64 s[40:41], 31, v65
	v_mov_b32_e32 v75, v191
	v_mov_b32_e32 v77, v191
	v_cndmask_b32_e64 v66, 0, v231, s[40:41]
	v_add_u32_e32 v65, v66, v65
	v_and_b32_e32 v66, 0x7fffff, v64
	v_or_b32_e32 v80, 0x800000, v66
	v_mad_u64_u32 v[66:67], s[4:5], v80, s4, 0
	v_mov_b32_e32 v68, v67
	s_mov_b32 s4, 0x3c439041
	v_mad_u64_u32 v[68:69], s[4:5], v80, s4, v[68:69]
	v_mov_b32_e32 v70, v69
	s_mov_b32 s4, 0xdb629599
	v_mad_u64_u32 v[70:71], s[4:5], v80, s4, v[70:71]
	v_mov_b32_e32 v72, v71
	s_mov_b32 s4, 0xf534ddc0
	v_mad_u64_u32 v[72:73], s[4:5], v80, s4, v[72:73]
	v_mov_b32_e32 v74, v73
	s_mov_b32 s4, 0xfc2757d1
	v_mad_u64_u32 v[74:75], s[4:5], v80, s4, v[74:75]
	v_mov_b32_e32 v76, v75
	s_mov_b32 s4, 0x4e441529
	v_mad_u64_u32 v[76:77], s[4:5], v80, s4, v[76:77]
	v_mov_b32_e32 v78, v77
	v_mov_b32_e32 v79, v191
	s_mov_b32 s4, 0xa2f9836e
	v_mad_u64_u32 v[78:79], s[4:5], v80, s4, v[78:79]
	v_cndmask_b32_e32 v67, v76, v72, vcc
	v_cndmask_b32_e32 v69, v78, v74, vcc
	v_cndmask_b32_e32 v73, v79, v76, vcc
	v_cndmask_b32_e64 v71, v69, v67, s[38:39]
	v_cndmask_b32_e64 v69, v73, v69, s[38:39]
	v_cndmask_b32_e32 v73, v74, v70, vcc
	v_cndmask_b32_e64 v67, v67, v73, s[38:39]
	v_sub_u32_e32 v74, 32, v65
	v_cmp_eq_u32_e64 s[42:43], 0, v65
	v_cndmask_b32_e32 v65, v72, v68, vcc
	v_cndmask_b32_e64 v69, v69, v71, s[40:41]
	v_cndmask_b32_e64 v71, v71, v67, s[40:41]
	v_cndmask_b32_e64 v68, v73, v65, s[38:39]
	v_alignbit_b32 v75, v69, v71, v74
	v_cndmask_b32_e64 v67, v67, v68, s[40:41]
	v_cndmask_b32_e64 v69, v75, v69, s[42:43]
	v_alignbit_b32 v72, v71, v67, v74
	v_cndmask_b32_e32 v66, v70, v66, vcc
	v_cndmask_b32_e64 v71, v72, v71, s[42:43]
	v_bfe_u32 v75, v69, 29, 1
	v_cndmask_b32_e64 v65, v65, v66, s[38:39]
	v_alignbit_b32 v72, v69, v71, 30
	v_sub_u32_e32 v76, 0, v75
	v_cndmask_b32_e64 v65, v68, v65, s[40:41]
	v_xor_b32_e32 v72, v72, v76
	v_alignbit_b32 v66, v67, v65, v74
	v_cndmask_b32_e64 v66, v66, v67, s[42:43]
	v_ffbh_u32_e32 v68, v72
	v_alignbit_b32 v67, v71, v66, 30
	v_min_u32_e32 v68, 32, v68
	v_alignbit_b32 v65, v66, v65, 30
	v_xor_b32_e32 v67, v67, v76
	v_sub_u32_e32 v70, 31, v68
	v_xor_b32_e32 v65, v65, v76
	v_alignbit_b32 v71, v72, v67, v70
	v_alignbit_b32 v65, v67, v65, v70
	v_alignbit_b32 v66, v71, v65, 9
	v_ffbh_u32_e32 v67, v66
	v_min_u32_e32 v67, 32, v67
	v_lshrrev_b32_e32 v73, 29, v69
	v_not_b32_e32 v70, v67
	v_alignbit_b32 v65, v66, v65, v70
	v_lshlrev_b32_e32 v66, 31, v73
	v_or_b32_e32 v70, 0x33000000, v66
	v_add_lshl_u32 v67, v67, v68, 23
	v_lshrrev_b32_e32 v65, 9, v65
	v_sub_u32_e32 v67, v70, v67
	v_or_b32_e32 v66, 0.5, v66
	v_lshlrev_b32_e32 v68, 23, v68
	v_or_b32_e32 v65, v67, v65
	v_lshrrev_b32_e32 v67, 9, v71
	v_sub_u32_e32 v66, v66, v68
	v_or_b32_e32 v66, v67, v66
	v_mul_f32_e32 v67, 0x3fc90fda, v66
	s_mov_b32 s4, 0x3fc90fda
	v_fma_f32 v68, v66, s4, -v67
	v_fmac_f32_e32 v68, 0x33a22168, v66
	v_fmac_f32_e32 v68, 0x3fc90fda, v65
	v_lshrrev_b32_e32 v66, 30, v69
	v_add_f32_e32 v65, v67, v68
	v_add_u32_e32 v66, v75, v66

.LBB0_1031:
	s_or_b64 exec, exec, s[4:5]
	v_mul_f32_e32 v67, v65, v65
	v_fmamk_f32 v68, v67, 0xb94c1982, v224
	v_fmaak_f32 v68, v67, v68, 0xbe2aaa9d
	v_mul_f32_e32 v68, v67, v68
	v_fmac_f32_e32 v65, v65, v68
	v_fmamk_f32 v68, v67, 0x37d75334, v225
	v_fmaak_f32 v68, v67, v68, 0x3d2aabf7
	v_fmaak_f32 v68, v67, v68, 0xbf000004
	v_fma_f32 v67, v67, v68, 1.0
	v_lshlrev_b32_e32 v68, 30, v66
	v_and_b32_e32 v66, 1, v66
	v_cmp_eq_u32_e32 vcc, 0, v66
	v_xor_b32_e32 v64, v64, v63
	v_and_b32_e32 v69, 0x80000000, v68
	v_cndmask_b32_e32 v66, v67, v65, vcc
	v_xor_b32_e32 v64, v64, v66
	v_xor_b32_e32 v66, v64, v69
	v_xor_b32_e32 v64, 0x80000000, v65
	v_cndmask_b32_e32 v64, v64, v67, vcc
	s_brev_b32 s4, 1
	v_bitop3_b32 v64, v64, v68, s4 bitop3:0x78
	s_movk_i32 s4, 0x1f8
	v_cmp_class_f32_e64 vcc, v63, s4
	s_waitcnt vmcnt(8)
	v_lshlrev_b32_e32 v68, 16, v61
	v_and_b32_e32 v69, 0xffff0000, v61
	v_cndmask_b32_e32 v66, v232, v66, vcc
	v_cndmask_b32_e32 v64, v232, v64, vcc
	s_waitcnt vmcnt(7)
	v_lshlrev_b32_e32 v70, 16, v60
	v_and_b32_e32 v71, 0xffff0000, v60
	v_pk_mul_f32 v[60:61], v[66:67], v[68:69] op_sel_hi:[0,1]
	v_pk_fma_f32 v[72:73], v[64:65], v[68:69], v[60:61] op_sel:[0,0,1] op_sel_hi:[1,1,0] neg_lo:[0,0,1] neg_hi:[0,0,1]
	v_pk_fma_f32 v[60:61], v[64:65], v[68:69], v[60:61] op_sel:[0,0,1] op_sel_hi:[0,1,0]
	v_pk_mul_f32 v[66:67], v[66:67], v[70:71] op_sel_hi:[0,1]
	v_mul_f32_e32 v60, v31, v15
	s_mov_b32 s4, 0xc2fc0000
	v_pk_fma_f32 v[68:69], v[64:65], v[70:71], v[66:67] op_sel:[0,0,1] op_sel_hi:[1,1,0] neg_lo:[0,0,1] neg_hi:[0,0,1]
	v_pk_fma_f32 v[64:65], v[64:65], v[70:71], v[66:67] op_sel:[0,0,1] op_sel_hi:[0,1,0]
	v_cmp_gt_f32_e32 vcc, s4, v60
	v_mul_f32_e32 v64, v31, v44
	v_mov_b32_e32 v69, v65
	v_cndmask_b32_e32 v63, 0, v227, vcc
	v_cndmask_b32_e32 v60, 0, v230, vcc
	v_fmac_f32_e32 v63, v31, v15
	v_cmp_gt_f32_e32 vcc, s4, v64
	v_exp_f32_e32 v63, v63
	s_mov_b32 s4, 0x3e000000
	v_cndmask_b32_e32 v64, 0, v227, vcc
	v_fmac_f32_e32 v64, v31, v44
	v_exp_f32_e32 v67, v64
	v_pk_mul_f32 v[64:65], v[68:69], s[4:5] op_sel_hi:[1,0]
	v_mov_b32_e32 v73, v61
	v_ldexp_f32 v60, v63, v60
	v_cvt_pk_bf16_f32 v61, v72, v61
	v_cvt_pk_bf16_f32 v63, v64, v65
	v_cvt_f32_i32_e32 v59, v59
	v_cndmask_b32_e32 v66, 0, v230, vcc
	ds_write2st64_b32 v16, v61, v63 offset1:36
	v_pk_mul_f32 v[60:61], v[60:61], v[64:65] op_sel_hi:[0,1]
	v_ldexp_f32 v66, v67, v66
	v_cvt_pk_bf16_f32 v60, v60, v61
	ds_write_b32 v16, v60 offset:18432
	v_pk_mul_f32 v[60:61], v[66:67], v[72:73] op_sel_hi:[0,1]
	v_cvt_pk_bf16_f32 v63, v60, v61
	v_lshl_add_u64 v[60:61], s[12:13], 0, v[26:27]
	v_mul_f32_e32 v59, v41, v59
	s_brev_b32 s4, 18
	global_store_dword v[60:61], v63, off nt
	v_and_b32_e32 v60, 0x7fffffff, v59
	v_cmp_nlt_f32_e64 s[4:5], |v59|, s4
	s_and_saveexec_b64 s[14:15], s[4:5]
	s_xor_b64 s[48:49], exec, s[14:15]
	s_cbranch_execz .LBB0_1033
	v_lshrrev_b32_e32 v61, 23, v60
	v_add_u32_e32 v61, 0xffffff88, v61
	v_cmp_lt_u32_e32 vcc, 63, v61
	s_mov_b32 s4, 0xfe5163ab
	v_mov_b32_e32 v67, v191
	v_cndmask_b32_e32 v63, 0, v230, vcc
	v_add_u32_e32 v61, v63, v61
	v_cmp_lt_u32_e64 s[38:39], 31, v61
	v_mov_b32_e32 v69, v191
	v_mov_b32_e32 v71, v191
	v_cndmask_b32_e64 v63, 0, v231, s[38:39]
	v_add_u32_e32 v61, v63, v61
	v_cmp_lt_u32_e64 s[40:41], 31, v61
	v_mov_b32_e32 v73, v191
	v_mov_b32_e32 v75, v191
	v_cndmask_b32_e64 v63, 0, v231, s[40:41]
	v_add_u32_e32 v61, v63, v61
	v_and_b32_e32 v63, 0x7fffff, v60
	v_or_b32_e32 v63, 0x800000, v63
	v_mad_u64_u32 v[64:65], s[4:5], v63, s4, 0
	v_mov_b32_e32 v66, v65
	s_mov_b32 s4, 0x3c439041
	v_mad_u64_u32 v[66:67], s[4:5], v63, s4, v[66:67]
	v_mov_b32_e32 v68, v67
	s_mov_b32 s4, 0xdb629599
	v_mad_u64_u32 v[68:69], s[4:5], v63, s4, v[68:69]
	v_mov_b32_e32 v70, v69
	s_mov_b32 s4, 0xf534ddc0
	v_mad_u64_u32 v[70:71], s[4:5], v63, s4, v[70:71]
	v_mov_b32_e32 v72, v71
	s_mov_b32 s4, 0xfc2757d1
	v_mad_u64_u32 v[72:73], s[4:5], v63, s4, v[72:73]
	v_mov_b32_e32 v74, v73
	s_mov_b32 s4, 0x4e441529
	v_mad_u64_u32 v[74:75], s[4:5], v63, s4, v[74:75]
	v_mov_b32_e32 v76, v75
	v_mov_b32_e32 v77, v191
	s_mov_b32 s4, 0xa2f9836e
	v_mad_u64_u32 v[76:77], s[4:5], v63, s4, v[76:77]
	v_cndmask_b32_e32 v65, v74, v70, vcc
	v_cndmask_b32_e32 v63, v76, v72, vcc
	v_cndmask_b32_e32 v69, v77, v74, vcc
	v_cndmask_b32_e64 v67, v63, v65, s[38:39]
	v_cndmask_b32_e64 v63, v69, v63, s[38:39]
	v_cndmask_b32_e32 v69, v72, v68, vcc
	v_cndmask_b32_e64 v65, v65, v69, s[38:39]
	v_sub_u32_e32 v71, 32, v61
	v_cmp_eq_u32_e64 s[42:43], 0, v61
	v_cndmask_b32_e32 v61, v70, v66, vcc
	v_cndmask_b32_e64 v63, v63, v67, s[40:41]
	v_cndmask_b32_e64 v67, v67, v65, s[40:41]
	v_cndmask_b32_e64 v66, v69, v61, s[38:39]
	v_alignbit_b32 v72, v63, v67, v71
	v_cndmask_b32_e64 v65, v65, v66, s[40:41]
	v_cndmask_b32_e64 v63, v72, v63, s[42:43]
	v_alignbit_b32 v69, v67, v65, v71
	v_cndmask_b32_e32 v64, v68, v64, vcc
	v_cndmask_b32_e64 v67, v69, v67, s[42:43]
	v_bfe_u32 v72, v63, 29, 1
	v_cndmask_b32_e64 v61, v61, v64, s[38:39]
	v_alignbit_b32 v69, v63, v67, 30
	v_sub_u32_e32 v73, 0, v72
	v_cndmask_b32_e64 v61, v66, v61, s[40:41]
	v_xor_b32_e32 v69, v69, v73
	v_alignbit_b32 v64, v65, v61, v71
	v_cndmask_b32_e64 v64, v64, v65, s[42:43]
	v_ffbh_u32_e32 v66, v69
	v_alignbit_b32 v65, v67, v64, 30
	v_min_u32_e32 v66, 32, v66
	v_alignbit_b32 v61, v64, v61, 30
	v_xor_b32_e32 v65, v65, v73
	v_sub_u32_e32 v67, 31, v66
	v_xor_b32_e32 v61, v61, v73
	v_alignbit_b32 v68, v69, v65, v67
	v_alignbit_b32 v61, v65, v61, v67
	v_alignbit_b32 v64, v68, v61, 9
	v_ffbh_u32_e32 v65, v64
	v_min_u32_e32 v65, 32, v65
	v_lshrrev_b32_e32 v70, 29, v63
	v_not_b32_e32 v67, v65
	v_alignbit_b32 v61, v64, v61, v67
	v_lshlrev_b32_e32 v64, 31, v70
	v_or_b32_e32 v67, 0x33000000, v64
	v_add_lshl_u32 v65, v65, v66, 23
	v_lshrrev_b32_e32 v61, 9, v61
	v_sub_u32_e32 v65, v67, v65
	v_or_b32_e32 v64, 0.5, v64
	v_lshlrev_b32_e32 v66, 23, v66
	v_or_b32_e32 v61, v65, v61
	v_lshrrev_b32_e32 v65, 9, v68
	v_sub_u32_e32 v64, v64, v66
	v_or_b32_e32 v64, v65, v64
	v_mul_f32_e32 v65, 0x3fc90fda, v64
	s_mov_b32 s4, 0x3fc90fda
	v_fma_f32 v66, v64, s4, -v65
	v_fmac_f32_e32 v66, 0x33a22168, v64
	v_fmac_f32_e32 v66, 0x3fc90fda, v61
	v_lshrrev_b32_e32 v63, 30, v63
	v_add_f32_e32 v61, v65, v66
	v_add_u32_e32 v63, v72, v63

.LBB0_1035:
	s_or_b64 exec, exec, s[4:5]
	v_mul_f32_e32 v64, v61, v61
	v_fmamk_f32 v65, v64, 0xb94c1982, v224
	v_fmaak_f32 v65, v64, v65, 0xbe2aaa9d
	v_mul_f32_e32 v65, v64, v65
	v_fmac_f32_e32 v61, v61, v65
	v_fmamk_f32 v65, v64, 0x37d75334, v225
	v_fmaak_f32 v65, v64, v65, 0x3d2aabf7
	v_fmaak_f32 v65, v64, v65, 0xbf000004
	v_fma_f32 v64, v64, v65, 1.0
	v_lshlrev_b32_e32 v65, 30, v63
	v_and_b32_e32 v63, 1, v63
	v_cmp_eq_u32_e32 vcc, 0, v63
	v_xor_b32_e32 v60, v60, v59
	v_and_b32_e32 v66, 0x80000000, v65
	v_cndmask_b32_e32 v63, v64, v61, vcc
	v_xor_b32_e32 v60, v60, v63
	v_xor_b32_e32 v63, v60, v66
	v_xor_b32_e32 v60, 0x80000000, v61
	v_cndmask_b32_e32 v60, v60, v64, vcc
	s_brev_b32 s4, 1
	v_bitop3_b32 v60, v60, v65, s4 bitop3:0x78
	s_movk_i32 s4, 0x1f8
	v_cmp_class_f32_e64 vcc, v59, s4
	s_waitcnt vmcnt(7)
	v_lshlrev_b32_e32 v66, 16, v58
	v_and_b32_e32 v67, 0xffff0000, v58
	v_cndmask_b32_e32 v64, v232, v63, vcc
	s_waitcnt vmcnt(6)
	v_lshlrev_b32_e32 v58, 16, v57
	v_and_b32_e32 v59, 0xffff0000, v57
	v_cndmask_b32_e32 v60, v232, v60, vcc
	v_pk_mul_f32 v[68:69], v[64:65], v[66:67] op_sel_hi:[0,1]
	v_pk_mul_f32 v[64:65], v[64:65], v[58:59] op_sel_hi:[0,1]
	v_mul_f32_e32 v57, v31, v17
	s_mov_b32 s4, 0xc2fc0000
	v_pk_fma_f32 v[70:71], v[60:61], v[66:67], v[68:69] op_sel:[0,0,1] op_sel_hi:[1,1,0] neg_lo:[0,0,1] neg_hi:[0,0,1]
	v_pk_fma_f32 v[66:67], v[60:61], v[66:67], v[68:69] op_sel:[0,0,1] op_sel_hi:[0,1,0]
	v_pk_fma_f32 v[68:69], v[60:61], v[58:59], v[64:65] op_sel:[0,0,1] op_sel_hi:[1,1,0] neg_lo:[0,0,1] neg_hi:[0,0,1]
	v_pk_fma_f32 v[58:59], v[60:61], v[58:59], v[64:65] op_sel:[0,0,1] op_sel_hi:[0,1,0]
	v_cmp_gt_f32_e32 vcc, s4, v57
	v_mov_b32_e32 v69, v59
	v_cvt_f32_i32_e32 v33, v33
	v_cndmask_b32_e32 v58, 0, v227, vcc
	v_fmac_f32_e32 v58, v31, v17
	v_exp_f32_e32 v60, v58
	v_mul_f32_e32 v58, v31, v45
	v_cndmask_b32_e32 v57, 0, v230, vcc
	v_cmp_gt_f32_e32 vcc, s4, v58
	s_mov_b32 s4, 0x3e000000
	v_ldexp_f32 v60, v60, v57
	v_cndmask_b32_e32 v58, 0, v227, vcc
	v_fmac_f32_e32 v58, v31, v45
	v_exp_f32_e32 v63, v58
	v_cndmask_b32_e32 v61, 0, v230, vcc
	v_pk_mul_f32 v[58:59], v[68:69], s[4:5] op_sel_hi:[1,0]
	v_mov_b32_e32 v71, v67
	v_ldexp_f32 v64, v63, v61
	v_cvt_pk_bf16_f32 v61, v58, v59
	v_cvt_pk_bf16_f32 v57, v70, v67
	v_pk_mul_f32 v[58:59], v[60:61], v[58:59] op_sel_hi:[0,1]
	ds_write2st64_b32 v18, v57, v61 offset1:36
	v_cvt_pk_bf16_f32 v57, v58, v59
	v_pk_mul_f32 v[58:59], v[64:65], v[70:71] op_sel_hi:[0,1]
	ds_write_b32 v18, v57 offset:18432
	v_cvt_pk_bf16_f32 v57, v58, v59
	v_lshl_add_u64 v[58:59], s[12:13], 0, v[24:25]
	global_store_dword v[58:59], v57, off nt
	v_mul_f32_e32 v57, v41, v33
	s_brev_b32 s4, 18
	v_and_b32_e32 v58, 0x7fffffff, v57
	v_cmp_nlt_f32_e64 s[4:5], |v57|, s4
	s_and_saveexec_b64 s[14:15], s[4:5]
	s_xor_b64 s[48:49], exec, s[14:15]
	s_cbranch_execz .LBB0_1037
	v_lshrrev_b32_e32 v33, 23, v58
	v_add_u32_e32 v33, 0xffffff88, v33
	v_cmp_lt_u32_e32 vcc, 63, v33
	s_mov_b32 s4, 0xfe5163ab
	v_mov_b32_e32 v65, v191
	v_cndmask_b32_e32 v59, 0, v230, vcc
	v_add_u32_e32 v33, v59, v33
	v_cmp_lt_u32_e64 s[38:39], 31, v33
	v_mov_b32_e32 v67, v191
	v_mov_b32_e32 v69, v191
	v_cndmask_b32_e64 v59, 0, v231, s[38:39]
	v_add_u32_e32 v33, v59, v33
	v_cmp_lt_u32_e64 s[40:41], 31, v33
	v_mov_b32_e32 v71, v191
	v_mov_b32_e32 v73, v191
	v_cndmask_b32_e64 v59, 0, v231, s[40:41]
	v_add_u32_e32 v33, v59, v33
	v_and_b32_e32 v59, 0x7fffff, v58
	v_or_b32_e32 v59, 0x800000, v59
	v_mad_u64_u32 v[60:61], s[4:5], v59, s4, 0
	v_mov_b32_e32 v64, v61
	s_mov_b32 s4, 0x3c439041
	v_mad_u64_u32 v[64:65], s[4:5], v59, s4, v[64:65]
	v_mov_b32_e32 v66, v65
	s_mov_b32 s4, 0xdb629599
	v_mad_u64_u32 v[66:67], s[4:5], v59, s4, v[66:67]
	v_mov_b32_e32 v68, v67
	s_mov_b32 s4, 0xf534ddc0
	v_mad_u64_u32 v[68:69], s[4:5], v59, s4, v[68:69]
	v_mov_b32_e32 v70, v69
	s_mov_b32 s4, 0xfc2757d1
	v_mad_u64_u32 v[70:71], s[4:5], v59, s4, v[70:71]
	v_mov_b32_e32 v72, v71
	s_mov_b32 s4, 0x4e441529
	v_mad_u64_u32 v[72:73], s[4:5], v59, s4, v[72:73]
	v_mov_b32_e32 v74, v73
	v_mov_b32_e32 v75, v191
	s_mov_b32 s4, 0xa2f9836e
	v_mad_u64_u32 v[74:75], s[4:5], v59, s4, v[74:75]
	v_cndmask_b32_e32 v61, v72, v68, vcc
	v_cndmask_b32_e32 v59, v74, v70, vcc
	v_cndmask_b32_e32 v65, v75, v72, vcc
	v_cndmask_b32_e64 v63, v59, v61, s[38:39]
	v_cndmask_b32_e64 v59, v65, v59, s[38:39]
	v_cndmask_b32_e32 v65, v70, v66, vcc
	v_cndmask_b32_e64 v61, v61, v65, s[38:39]
	v_cndmask_b32_e64 v59, v59, v63, s[40:41]
	v_cndmask_b32_e64 v63, v63, v61, s[40:41]
	v_sub_u32_e32 v67, 32, v33
	v_alignbit_b32 v69, v59, v63, v67
	v_cmp_eq_u32_e64 s[42:43], 0, v33
	v_cndmask_b32_e32 v60, v66, v60, vcc
	s_mov_b32 s4, 0x3fc90fda
	v_cndmask_b32_e64 v33, v69, v59, s[42:43]
	v_cndmask_b32_e32 v59, v68, v64, vcc
	v_cndmask_b32_e64 v64, v65, v59, s[38:39]
	v_cndmask_b32_e64 v61, v61, v64, s[40:41]
	v_alignbit_b32 v65, v63, v61, v67
	v_cndmask_b32_e64 v59, v59, v60, s[38:39]
	v_cndmask_b32_e64 v63, v65, v63, s[42:43]
	v_bfe_u32 v69, v33, 29, 1
	v_cndmask_b32_e64 v59, v64, v59, s[40:41]
	v_alignbit_b32 v65, v33, v63, 30
	v_sub_u32_e32 v70, 0, v69
	v_alignbit_b32 v60, v61, v59, v67
	v_xor_b32_e32 v65, v65, v70
	v_cndmask_b32_e64 v60, v60, v61, s[42:43]
	v_alignbit_b32 v61, v63, v60, 30
	v_ffbh_u32_e32 v63, v65
	v_min_u32_e32 v63, 32, v63
	v_alignbit_b32 v59, v60, v59, 30
	v_xor_b32_e32 v61, v61, v70
	v_sub_u32_e32 v64, 31, v63
	v_xor_b32_e32 v59, v59, v70
	v_alignbit_b32 v65, v65, v61, v64
	v_alignbit_b32 v59, v61, v59, v64
	v_alignbit_b32 v60, v65, v59, 9
	v_ffbh_u32_e32 v61, v60
	v_min_u32_e32 v61, 32, v61
	v_lshrrev_b32_e32 v68, 29, v33
	v_not_b32_e32 v64, v61
	v_alignbit_b32 v59, v60, v59, v64
	v_lshlrev_b32_e32 v60, 31, v68
	v_or_b32_e32 v64, 0x33000000, v60
	v_add_lshl_u32 v61, v61, v63, 23
	v_lshrrev_b32_e32 v59, 9, v59
	v_sub_u32_e32 v61, v64, v61
	v_or_b32_e32 v60, 0.5, v60
	v_lshlrev_b32_e32 v63, 23, v63
	v_or_b32_e32 v59, v61, v59
	v_lshrrev_b32_e32 v61, 9, v65
	v_sub_u32_e32 v60, v60, v63
	v_or_b32_e32 v60, v61, v60
	v_mul_f32_e32 v61, 0x3fc90fda, v60
	v_fma_f32 v63, v60, s4, -v61
	v_fmac_f32_e32 v63, 0x33a22168, v60
	v_fmac_f32_e32 v63, 0x3fc90fda, v59
	v_lshrrev_b32_e32 v33, 30, v33
	v_add_f32_e32 v59, v61, v63
	v_add_u32_e32 v33, v69, v33

.LBB0_1039:
	s_or_b64 exec, exec, s[4:5]
	v_mul_f32_e32 v60, v59, v59
	v_fmamk_f32 v61, v60, 0xb94c1982, v224
	v_fmaak_f32 v61, v60, v61, 0xbe2aaa9d
	v_mul_f32_e32 v61, v60, v61
	v_fmac_f32_e32 v59, v59, v61
	v_fmamk_f32 v61, v60, 0x37d75334, v225
	v_fmaak_f32 v61, v60, v61, 0x3d2aabf7
	v_fmaak_f32 v61, v60, v61, 0xbf000004
	v_and_b32_e32 v64, 1, v33
	v_fma_f32 v60, v60, v61, 1.0
	v_cmp_eq_u32_e32 vcc, 0, v64
	v_lshlrev_b32_e32 v61, 30, v33
	v_xor_b32_e32 v58, v58, v57
	v_cndmask_b32_e32 v64, v60, v59, vcc
	v_and_b32_e32 v63, 0x80000000, v61
	v_xor_b32_e32 v58, v58, v64
	v_xor_b32_e32 v63, v58, v63
	v_xor_b32_e32 v58, 0x80000000, v59
	v_cndmask_b32_e32 v58, v58, v60, vcc
	s_brev_b32 s5, 1
	v_bitop3_b32 v58, v58, v61, s5 bitop3:0x78
	s_movk_i32 s5, 0x1f8
	v_cmp_class_f32_e64 vcc, v57, s5
	s_waitcnt vmcnt(6)
	v_lshlrev_b32_e32 v64, 16, v56
	v_and_b32_e32 v65, 0xffff0000, v56
	v_cndmask_b32_e32 v60, v232, v63, vcc
	s_waitcnt vmcnt(5)
	v_lshlrev_b32_e32 v56, 16, v32
	v_and_b32_e32 v57, 0xffff0000, v32
	v_cndmask_b32_e32 v58, v232, v58, vcc
	v_pk_mul_f32 v[66:67], v[60:61], v[64:65] op_sel_hi:[0,1]
	v_pk_mul_f32 v[60:61], v[60:61], v[56:57] op_sel_hi:[0,1]
	v_mul_f32_e32 v32, v31, v19
	s_mov_b32 s5, 0xc2fc0000
	v_pk_fma_f32 v[68:69], v[58:59], v[64:65], v[66:67] op_sel:[0,0,1] op_sel_hi:[1,1,0] neg_lo:[0,0,1] neg_hi:[0,0,1]
	v_pk_fma_f32 v[64:65], v[58:59], v[64:65], v[66:67] op_sel:[0,0,1] op_sel_hi:[0,1,0]
	v_pk_fma_f32 v[66:67], v[58:59], v[56:57], v[60:61] op_sel:[0,0,1] op_sel_hi:[1,1,0] neg_lo:[0,0,1] neg_hi:[0,0,1]
	v_pk_fma_f32 v[56:57], v[58:59], v[56:57], v[60:61] op_sel:[0,0,1] op_sel_hi:[0,1,0]
	v_cmp_gt_f32_e32 vcc, s5, v32
	v_mov_b32_e32 v67, v57
	s_mov_b32 s14, 0x3e000000
	v_cndmask_b32_e32 v56, 0, v227, vcc
	v_fmac_f32_e32 v56, v31, v19
	v_exp_f32_e32 v58, v56
	v_mul_f32_e32 v56, v31, v46
	v_cndmask_b32_e32 v32, 0, v230, vcc
	v_cmp_gt_f32_e32 vcc, s5, v56
	v_mov_b32_e32 v33, 0
	v_ldexp_f32 v32, v58, v32
	v_cndmask_b32_e32 v56, 0, v227, vcc
	v_fmac_f32_e32 v56, v31, v46
	v_exp_f32_e32 v60, v56
	v_cndmask_b32_e32 v59, 0, v230, vcc
	v_pk_mul_f32 v[56:57], v[66:67], s[14:15] op_sel_hi:[1,0]
	v_mov_b32_e32 v69, v65
	v_ldexp_f32 v58, v60, v59
	v_cvt_pk_bf16_f32 v59, v68, v65
	v_cvt_pk_bf16_f32 v60, v56, v57
	v_pk_mul_f32 v[56:57], v[32:33], v[56:57] op_sel_hi:[0,1]
	v_cvt_pk_bf16_f32 v32, v56, v57
	v_pk_mul_f32 v[56:57], v[58:59], v[68:69] op_sel_hi:[0,1]
	s_ashr_i32 s4, s3, 6
	ds_write_b32 v20, v32 offset:18432
	v_cvt_pk_bf16_f32 v32, v56, v57
	v_lshl_add_u64 v[56:57], s[12:13], 0, v[22:23]
	s_ashr_i32 s14, s3, 7
	ds_write2st64_b32 v20, v59, v60 offset1:36
	global_store_dword v[56:57], v32, off nt
	s_waitcnt vmcnt(5)
	ds_write_b128 v54, v[6:9] offset:27648
	s_waitcnt vmcnt(4)
	ds_write_b128 v55, v[10:13] offset:27648
	s_lshl_b32 s5, s4, 1
	s_lshl_b32 s15, s14, 4
	s_waitcnt lgkmcnt(0)
	s_barrier
	s_and_b32 s5, s5, 2
	v_or_b32_e32 v6, s15, v34
	v_mul_lo_u32 v6, v6, s6
	v_or_b32_e32 v10, s15, v62
	v_lshl_or_b32 v12, s5, 4, v34
	s_cmp_lt_i32 s5, s14
	v_mul_u32_u24_e32 v13, 0x90, v12
	v_add_u32_e32 v11, v47, v6
	v_or_b32_e32 v8, 3, v10
	v_or_b32_e32 v9, 2, v10
	v_mov_b32_e32 v7, 0
	v_mov_b32_e32 v6, 0
	s_cbranch_scc1 .LBB0_1041
	v_add_u32_e32 v6, v47, v13
	ds_read_b128 v[56:59], v11 offset:9216
	ds_read_b128 v[64:67], v6
	s_mov_b32 s15, 0xc2fc0000
	s_waitcnt lgkmcnt(0)
	v_mfma_f32_16x16x32_bf16 v[56:59], v[56:59], v[64:67], 0
	ds_read_b128 v[64:67], v11 offset:9280
	ds_read_b128 v[68:71], v6 offset:64
	v_sub_u32_e32 v6, v12, v10
	v_cvt_f32_i32_e32 v6, v6
	s_waitcnt lgkmcnt(0)
	v_mfma_f32_16x16x32_bf16 v[56:59], v[64:67], v[68:71], v[56:59]
	v_mul_f32_e32 v7, v31, v6
	v_cmp_gt_f32_e32 vcc, s15, v7
	s_nop 1
	v_cndmask_b32_e32 v7, 0, v227, vcc
	v_fmac_f32_e32 v7, v31, v6
	v_exp_f32_e32 v6, v7
	v_cndmask_b32_e32 v7, 0, v230, vcc
	v_cmp_ge_i32_e32 vcc, v12, v10
	v_ldexp_f32 v6, v6, v7
	v_mul_f32_e32 v6, v6, v56
	v_cndmask_b32_e32 v32, 0, v6, vcc
	v_xad_u32 v6, v10, -1, v12
	v_cvt_f32_i32_e32 v6, v6
	v_cmp_gt_i32_e32 vcc, v12, v10
	v_mul_f32_e32 v7, v31, v6
	v_cmp_gt_f32_e64 s[38:39], s15, v7
	s_nop 1
	v_cndmask_b32_e64 v7, 0, v227, s[38:39]
	v_fmac_f32_e32 v7, v31, v6
	v_exp_f32_e32 v6, v7
	v_cndmask_b32_e64 v7, 0, v230, s[38:39]
	v_ldexp_f32 v6, v6, v7
	v_mul_f32_e32 v6, v6, v57
	v_cndmask_b32_e32 v60, 0, v6, vcc
	v_sub_u32_e32 v6, v12, v9
	v_cvt_f32_i32_e32 v6, v6
	v_mul_f32_e32 v7, v31, v6
	v_cmp_gt_f32_e32 vcc, s15, v7
	s_nop 1
	v_cndmask_b32_e32 v7, 0, v227, vcc
	v_fmac_f32_e32 v7, v31, v6
	v_exp_f32_e32 v6, v7
	v_cndmask_b32_e32 v7, 0, v230, vcc
	v_ldexp_f32 v6, v6, v7
	v_sub_u32_e32 v7, v12, v8
	v_cvt_f32_i32_e32 v7, v7
	v_mul_f32_e32 v56, v31, v7
	v_cmp_gt_f32_e32 vcc, s15, v56
	s_mov_b32 s15, 0x5040100
	s_nop 0
	v_cndmask_b32_e32 v56, 0, v227, vcc
	v_fmac_f32_e32 v56, v31, v7
	v_exp_f32_e32 v7, v56
	v_cndmask_b32_e32 v56, 0, v230, vcc
	v_cmp_ge_i32_e32 vcc, v12, v9
	v_ldexp_f32 v7, v7, v56
	v_pk_mul_f32 v[56:57], v[6:7], v[58:59]
	v_cvt_pk_bf16_f32 v6, v32, v60
	v_cvt_pk_bf16_f32 v7, v56, v57
	v_cndmask_b32_e32 v32, 0, v7, vcc
	v_cmp_ge_i32_e32 vcc, v12, v8
	s_nop 1
	v_cndmask_b32_sdwa v7, v191, v7, vcc dst_sel:DWORD dst_unused:UNUSED_PAD src0_sel:DWORD src1_sel:WORD_1
	v_perm_b32 v7, v7, v32, s15
